# k9 with static priority: one s_setprio 1 for waves 4-7 at each GEMM phase start, all per-segment setprio flips in the GEMM loops deleted
# baseline (speedup 1.0000x reference)
; #define PG8_BAR __builtin_amdgcn_s_barrier()
; template <class Epi, class Sched, bool ALIGN_EPI = false, bool SP2 = false>
; __device__ __forceinline__ void gemm_phase(PG8_LAS unsigned char* lds, const Gemm g, const Sched& S, const Epi& E, const int wv0) {
;     const int tid = opaque(TID()), wid = __builtin_amdgcn_readfirstlane(tid >> 6), lane = tid & 63, wr = wid >> 2, wc = wid & 3, fr = lane & 15, fq = lane >> 4;
;     const int K = g.K, nt = K / BK;
;     unsigned voffA[2], voffB[2];
; #pragma unroll
;     for (int i = 0; i < 2; ++i) { int R, C; stage_rc(tid * 16 + i * 8192, R, C); const int Rb = Epi::PERM ? ((R & ~31) + perm32(R & 31)) : R;
;         voffA[i] = (unsigned)(R * g.lda + C) * 2u; voffB[i] = (unsigned)(Rb * g.ldb + C) * 2u; }
;     const size_t kstep = (size_t)(BK * 2);
;     const size_t hstepA = (size_t)HALF * g.lda * 2, hstepB = (size_t)HALF * g.ldb * 2;
;     const unsigned ldsw = (unsigned)wid * 1024u;
;     const int aoff = lds_byte(wr * 64 + fr, fq * 8), boff = lds_byte(wc * 32 + fr, fq * 8);
;     ...
;     Unit cur, nxt; int ui = 0;
;     if (!S.next(0, cur)) return;
;     f32x4 acc[2][2][4][2];
; #pragma unroll
;     for (int a = 0; a < 2; ++a)
; #pragma unroll
;         for (int b = 0; b < 2; ++b)
; #pragma unroll
;             for (int m = 0; m < 4; ++m)
; #pragma unroll
;                 for (int n = 0; n < 2; ++n) acc[a][b][m][n] = (f32x4){0.f, 0.f, 0.f, 0.f};
;     bf16x8 At[4][2], B0[2][2], B1[2][2];
;     const char* cA = cur.a; const char* cB = cur.b;
;     if constexpr (SP2) {
;         PG8_STAGE(PG8_SB(0, 0), cB, voffB); PG8_STAGE(PG8_SB(0, 1), cB + hstepB, voffB); PG8_STAGE(PG8_SA(0, 0), cA, voffA); PG8_STAGE(PG8_SA(0, 1), cA + hstepA, voffA);
;         if (wr == 1) PG8_BAR;
;         PG8_WAIT_V(2); PG8_BAR;
;         PG8_STAGE(PG8_SB(1, 0), cB + kstep, voffB); PG8_STAGE(PG8_SA(1, 0), cA + kstep, voffA); PG8_STAGE(PG8_SB(1, 1), cB + hstepB + kstep, voffB);
;         PG8_WAIT_V(6); PG8_BAR;
;     } else {
;         PG8_STAGE(PG8_SB(0, 0), cB, voffB); PG8_STAGE(PG8_SA(0, 0), cA, voffA); PG8_STAGE(PG8_SB(0, 1), cB + hstepB, voffB); PG8_STAGE(PG8_SA(0, 1), cA + hstepA, voffA);
;         if (wr == 1) PG8_BAR;
;         PG8_WAIT_V(4); PG8_BAR;
;         PG8_STAGE(PG8_SB(1, 0), cB + kstep, voffB); PG8_STAGE(PG8_SA(1, 0), cA + kstep, voffA); PG8_STAGE(PG8_SB(1, 1), cB + hstepB + kstep, voffB);
;         PG8_WAIT_V(6); PG8_BAR;
;     }
.LBB0_73:
	s_or_b64 exec, exec, s[0:1]
	s_barrier
	v_readfirstlane_b32 s79, v204
	s_lshr_b32 s79, s79, 6
	s_cmp_ge_u32 s79, 4
	s_cbranch_scc0 .Lprio_skip_9
	s_setprio 1
.Lprio_skip_9:
	v_mov_b32 v0, s77
	ds_read_b64 v[0:1], v0 offset:168
	v_mov_b32_e32 v2, v204
	s_mov_b32 s40, s76
	s_mov_b32 s41, s33
	v_mov_b32_e32 v9, v204
	s_waitcnt lgkmcnt(0)
	v_readfirstlane_b32 s3, v1
	v_readfirstlane_b32 s2, v0
	s_cmpk_lt_i32 s41, 0xd00
	s_nop 0
	v_readfirstlane_b32 s1, v9
	s_cbranch_scc0 .LBB0_109
	v_lshlrev_b32_e32 v0, 4, v9
	v_add_u32_e32 v1, 0x2000, v0
	v_ashrrev_i32_e32 v2, 31, v1
	v_lshrrev_b32_e32 v2, 22, v2
	v_add_u32_e32 v2, v1, v2
	v_ashrrev_i32_e32 v8, 10, v2
	v_mul_i32_i24_e32 v2, 0x400, v8
	v_sub_u32_e32 v1, v1, v2
	v_lshrrev_b32_e32 v2, 4, v1
	v_bitop3_b32 v1, v2, v1, 32 bitop3:0x6c
	v_ashrrev_i32_e32 v2, 31, v1
	v_lshrrev_b32_e32 v2, 26, v2
	v_add_u32_e32 v2, v1, v2
	v_lshlrev_b32_e32 v3, 3, v8
	v_ashrrev_i32_e32 v10, 6, v2
	v_and_b32_e32 v3, -16, v3
	v_add_u32_e32 v3, v10, v3
	v_and_b32_e32 v4, 3, v10
	s_mov_b32 s0, 0xfffe0
	v_lshrrev_b32_e32 v5, 2, v3
	v_lshlrev_b32_e32 v6, 1, v3
	v_and_b32_e32 v2, 0xc0, v2
	v_and_or_b32 v4, v3, s0, v4
	v_and_b32_e32 v5, 4, v5
	v_and_b32_e32 v6, 24, v6
	v_sub_u32_e32 v1, v1, v2
	v_mov_b32_e32 v148, 1
	v_or3_b32 v4, v4, v5, v6
	v_lshlrev_b32_e32 v5, 5, v8
	v_ashrrev_i16_sdwa v1, v148, sext(v1) dst_sel:DWORD dst_unused:UNUSED_PAD src0_sel:DWORD src1_sel:BYTE_0
	v_and_b32_e32 v5, 32, v5
	v_bfe_i32 v11, v1, 0, 16
	v_add_lshl_u32 v1, v5, v11, 1
	v_lshl_add_u32 v128, v4, 12, v1
	v_lshl_add_u32 v130, v3, 12, v1
	v_bfe_i32 v1, v9, 27, 1
	v_lshrrev_b32_e32 v1, 22, v1
	v_add_u32_e32 v1, v0, v1
	v_and_b32_e32 v1, 0xfffffc00, v1
	v_sub_u32_e32 v0, v0, v1
	v_lshrrev_b32_e32 v1, 4, v0
	v_bitop3_b32 v1, v1, v0, 32 bitop3:0x6c
	v_ashrrev_i32_e32 v0, 31, v0
	v_lshrrev_b32_e32 v0, 26, v0
	v_add_u32_e32 v0, v1, v0
	v_ashrrev_i32_e32 v12, 6, v0
	v_ashrrev_i32_e32 v0, 31, v9
	v_lshrrev_b32_e32 v0, 26, v0
	v_add_u32_e32 v0, v9, v0
	v_ashrrev_i32_e32 v13, 6, v0
	v_lshlrev_b32_e32 v0, 3, v13
	s_add_u32 s44, s2, 0x9a00000
	v_and_b32_e32 v0, -16, v0
	s_addc_u32 s45, s3, 0
	s_ashr_i32 s46, s41, 31
	v_add_u32_e32 v0, v12, v0
	v_and_b32_e32 v2, 3, v12
	v_and_or_b32 v2, v0, s0, v2
	s_lshr_b32 s0, s46, 29
	s_add_i32 s0, s41, s0
	s_ashr_i32 s14, s1, 6
	s_ashr_i32 s4, s0, 3
	s_and_b32 s0, s0, -8
	s_ashr_i32 s17, s1, 8
	s_lshl_b32 s47, s14, 10
	s_sub_i32 s0, s41, s0
	s_cmp_lt_i32 s0, 0
	s_movk_i32 s48, 0x1a1
	s_cselect_b32 s5, s48, 0x1a0
	s_mul_i32 s0, s5, s0
	s_add_i32 s0, s0, s4
	s_mul_hi_i32 s4, s0, 0x4ec4ec4f
	s_lshr_b32 s5, s4, 31
	s_ashr_i32 s4, s4, 6
	s_add_i32 s4, s4, s5
	s_mul_i32 s5, s4, 0xd0
	s_sub_i32 s5, s0, s5
	s_bfe_u32 s0, s5, 0x2001d
	s_add_i32 s6, s5, s0
	s_sext_i32_i16 s0, s6
	s_and_b32 s6, s6, 0xfffc
	s_sub_i32 s5, s5, s6
	s_lshl_b32 s4, s4, 2
	s_sext_i32_i16 s5, s5
	s_add_i32 s28, s4, s5
	v_lshrrev_b32_e32 v3, 2, v0
	v_lshlrev_b32_e32 v4, 1, v0
	s_ashr_i32 s29, s28, 31
	v_and_b32_e32 v3, 4, v3
	v_and_b32_e32 v4, 24, v4
	s_lshr_b32 s0, s0, 2
	s_lshl_b64 s[4:5], s[28:29], 20
	v_or3_b32 v2, v2, v3, v4
	v_mul_i32_i24_e32 v4, 64, v12
	s_add_u32 s30, s44, s4
	v_sub_u32_e32 v1, v1, v4
	s_addc_u32 s31, s45, s5
	s_bfe_i64 s[4:5], s[0:1], 0x100000
	v_lshlrev_b32_e32 v3, 5, v13
	v_ashrrev_i16_sdwa v1, v148, sext(v1) dst_sel:DWORD dst_unused:UNUSED_PAD src0_sel:DWORD src1_sel:BYTE_0
	s_lshl_b64 s[4:5], s[4:5], 20
	v_and_b32_e32 v3, 32, v3
	v_bfe_i32 v14, v1, 0, 16
	s_add_u32 s34, s2, s4
	v_add_lshl_u32 v1, v3, v14, 1
	s_addc_u32 s35, s3, s5
	s_add_i32 s29, s47, 0
	v_lshl_add_u32 v132, v2, 12, v1
	s_add_i32 m0, s29, 0x10000
	v_lshl_add_u32 v134, v0, 12, v1
	global_load_lds_dwordx4 v132, s[34:35]
	s_add_i32 m0, s29, 0x12000
	s_add_u32 s4, s34, 0x80000
	global_load_lds_dwordx4 v128, s[34:35]
	s_addc_u32 s5, s35, 0
	s_add_i32 m0, s29, 0x14000
	s_add_i32 s49, s29, 0x2000
	global_load_lds_dwordx4 v132, s[4:5]
	s_add_i32 m0, s29, 0x16000
	v_mov_b32_e32 v133, 0
	global_load_lds_dwordx4 v128, s[4:5]
	s_mov_b32 m0, s29
	s_add_u32 s4, s30, 0x80000
	global_load_lds_dwordx4 v134, s[30:31]
	s_mov_b32 m0, s49
	s_addc_u32 s5, s31, 0
	s_add_i32 s50, s29, 0x4000
	global_load_lds_dwordx4 v130, s[30:31]
	s_mov_b32 m0, s50
	s_add_i32 s51, s29, 0x6000
	global_load_lds_dwordx4 v134, s[4:5]
	s_mov_b32 m0, s51
	v_mov_b32_e32 v129, v133
	global_load_lds_dwordx4 v130, s[4:5]
	v_mov_b32_e32 v135, v133
	v_mov_b32_e32 v131, v133
	s_cmp_eq_u32 s17, 1
	s_movk_i32 s52, 0x2000
	v_lshl_add_u64 v[6:7], s[34:35], 0, v[132:133]
	v_lshl_add_u64 v[4:5], s[34:35], 0, v[128:129]
	v_lshl_add_u64 v[2:3], s[30:31], 0, v[134:135]
	v_lshl_add_u64 v[0:1], s[30:31], 0, v[130:131]
	s_movk_i32 s53, 0x4000
	s_cselect_b64 s[4:5], -1, 0
	s_cmp_lg_u32 s17, 1
	s_movk_i32 s54, 0x6000
	s_cbranch_scc1 .LBB0_76
	s_barrier

; #define PG8_STAGE(bufoff, gbase, voff) do { _Pragma("unroll") for (int _i = 0; _i < 2; ++_i) \
;         __builtin_amdgcn_global_load_lds((const unsigned*)((const char*)(gbase) + (voff)[_i]), (PG8_LAS unsigned*)(lds + (bufoff) + ldsw + _i * 8192), 16, 0, 0); } while (0)
; #define PG8_LDA(dst, b, h) do { _Pragma("unroll") for (int m = 0; m < 4; ++m) _Pragma("unroll") for (int k = 0; k < 2; ++k) dst[m][k] = *(const PG8_LAS bf16x8*)(lds + PG8_SA(b, h) + aoff + m * 2048 + k * 1024); } while (0)
; #define PG8_LDB(dst, b, h) do { _Pragma("unroll") for (int n = 0; n < 2; ++n) _Pragma("unroll") for (int k = 0; k < 2; ++k) dst[n][k] = *(const PG8_LAS bf16x8*)(lds + PG8_SB(b, h) + boff + n * 2048 + k * 1024); } while (0)
; #define PG8_MMA(ai, bj, At, Bt) do { __builtin_amdgcn_s_setprio(1); _Pragma("unroll") for (int m = 0; m < 4; ++m) _Pragma("unroll") for (int n = 0; n < 2; ++n) _Pragma("unroll") for (int k = 0; k < 2; ++k) \
;         acc[ai][bj][m][n] = __builtin_amdgcn_mfma_f32_16x16x32_bf16(Bt[n][k], At[m][k], acc[ai][bj][m][n], 0, 0, 0); __builtin_amdgcn_s_setprio(0); } while (0)
; #define PG8_WAIT_V(n) asm volatile("s_waitcnt vmcnt(" #n ")" ::: "memory")
; #define PG8_WAIT_L(n) asm volatile("s_waitcnt lgkmcnt(" #n ")" ::: "memory")
; #define PG8_BAR __builtin_amdgcn_s_barrier()
; #define PG8_SCHED __builtin_amdgcn_sched_barrier(0)
; template <class Epi, class Sched, bool ALIGN_EPI = false, bool SP2 = false>
; __device__ __forceinline__ void gemm_phase(PG8_LAS unsigned char* lds, const Gemm g, const Sched& S, const Epi& E, const int wv0) {
;     ...
;             PG8_LDB(B0, 0, 0); PG8_LDB(B1, 0, 1); PG8_SCHED; PG8_LDA(At, 0, 0); PG8_STAGE(PG8_SA(1, 1), a1 + hstepA, voffA);
;             PG8_WAIT_V(8); PG8_WAIT_L(0); PG8_BAR; PG8_MMA(0, 0, At, B0); PG8_MMA(0, 1, At, B1); PG8_BAR; PG8_SCHED;
.LBB0_82:
	ds_read_b128 v[156:159], v152
	ds_read_b128 v[160:163], v152 offset:1024
	ds_read_b128 v[164:167], v152 offset:2048
	ds_read_b128 v[168:171], v152 offset:3072
	ds_read_b128 v[172:175], v153
	ds_read_b128 v[176:179], v153 offset:1024
	ds_read_b128 v[180:183], v153 offset:2048
	ds_read_b128 v[184:187], v153 offset:3072
	s_add_u32 s34, s30, 0xfff80080
	s_addc_u32 s35, s31, -1
	s_cmp_eq_u32 s38, 28
	s_cselect_b32 s37, s25, s35
	s_cselect_b32 s36, s24, s34
	s_cselect_b32 s35, s27, s23
	s_cselect_b32 s34, s26, s21
	v_lshl_add_u64 v[146:147], s[30:31], 0, v[140:141]
	s_add_i32 m0, s29, 0xc000
	ds_read_b128 v[188:191], v154
	ds_read_b128 v[192:195], v154 offset:1024
	ds_read_b128 v[196:199], v154 offset:2048
	ds_read_b128 v[200:203], v154 offset:3072
	ds_read_b128 v[206:209], v154 offset:4096
	ds_read_b128 v[210:213], v154 offset:5120
	ds_read_b128 v[214:217], v154 offset:6144
	ds_read_b128 v[218:221], v154 offset:7168
	global_load_lds_dwordx4 v[146:147], off
	v_lshl_add_u64 v[146:147], s[30:31], 0, v[138:139]
	s_add_i32 m0, s29, 0xe000
	s_nop 0
	global_load_lds_dwordx4 v[146:147], off
	s_waitcnt vmcnt(8)
	s_waitcnt lgkmcnt(0)
	s_barrier
	v_mfma_f32_16x16x32_bf16 v[124:127], v[156:159], v[188:191], v[124:127]
	v_mfma_f32_16x16x32_bf16 v[120:123], v[164:167], v[188:191], v[120:123]
	v_mfma_f32_16x16x32_bf16 v[116:119], v[156:159], v[196:199], v[116:119]
	v_mfma_f32_16x16x32_bf16 v[108:111], v[164:167], v[196:199], v[108:111]
	v_mfma_f32_16x16x32_bf16 v[100:103], v[156:159], v[206:209], v[100:103]
	v_mfma_f32_16x16x32_bf16 v[92:95], v[164:167], v[206:209], v[92:95]
	v_mfma_f32_16x16x32_bf16 v[84:87], v[156:159], v[214:217], v[84:87]
	v_mfma_f32_16x16x32_bf16 v[76:79], v[164:167], v[214:217], v[76:79]
	v_mfma_f32_16x16x32_bf16 v[124:127], v[160:163], v[192:195], v[124:127]
	v_mfma_f32_16x16x32_bf16 v[120:123], v[168:171], v[192:195], v[120:123]
	v_mfma_f32_16x16x32_bf16 v[116:119], v[160:163], v[200:203], v[116:119]
	v_mfma_f32_16x16x32_bf16 v[108:111], v[168:171], v[200:203], v[108:111]
	v_mfma_f32_16x16x32_bf16 v[100:103], v[160:163], v[210:213], v[100:103]
	v_mfma_f32_16x16x32_bf16 v[92:95], v[168:171], v[210:213], v[92:95]
	v_mfma_f32_16x16x32_bf16 v[84:87], v[160:163], v[218:221], v[84:87]
	v_mfma_f32_16x16x32_bf16 v[76:79], v[168:171], v[218:221], v[76:79]
	v_mfma_f32_16x16x32_bf16 v[112:115], v[172:175], v[188:191], v[112:115]
	v_mfma_f32_16x16x32_bf16 v[104:107], v[180:183], v[188:191], v[104:107]
	v_mfma_f32_16x16x32_bf16 v[96:99], v[172:175], v[196:199], v[96:99]
	v_mfma_f32_16x16x32_bf16 v[88:91], v[180:183], v[196:199], v[88:91]
	v_mfma_f32_16x16x32_bf16 v[80:83], v[172:175], v[206:209], v[80:83]
	v_mfma_f32_16x16x32_bf16 v[72:75], v[180:183], v[206:209], v[72:75]
	v_mfma_f32_16x16x32_bf16 v[68:71], v[172:175], v[214:217], v[68:71]
	v_mfma_f32_16x16x32_bf16 v[64:67], v[180:183], v[214:217], v[64:67]
	v_mfma_f32_16x16x32_bf16 v[112:115], v[176:179], v[192:195], v[112:115]
	v_mfma_f32_16x16x32_bf16 v[104:107], v[184:187], v[192:195], v[104:107]
	v_mfma_f32_16x16x32_bf16 v[96:99], v[176:179], v[200:203], v[96:99]
	v_mfma_f32_16x16x32_bf16 v[88:91], v[184:187], v[200:203], v[88:91]
	v_mfma_f32_16x16x32_bf16 v[80:83], v[176:179], v[210:213], v[80:83]
	v_mfma_f32_16x16x32_bf16 v[72:75], v[184:187], v[210:213], v[72:75]
	v_mfma_f32_16x16x32_bf16 v[68:71], v[176:179], v[218:221], v[68:71]
	v_mfma_f32_16x16x32_bf16 v[64:67], v[184:187], v[218:221], v[64:67]
	s_barrier
	s_add_i32 s39, s62, s47
	v_lshl_add_u64 v[146:147], s[34:35], 0, v[132:133]
	s_mov_b32 m0, s39
	ds_read_b128 v[188:191], v154 offset:16384
	ds_read_b128 v[192:195], v154 offset:17408
	ds_read_b128 v[196:199], v154 offset:18432
	ds_read_b128 v[200:203], v154 offset:19456
	ds_read_b128 v[206:209], v154 offset:20480
	ds_read_b128 v[210:213], v154 offset:21504
	ds_read_b128 v[214:217], v154 offset:22528
	ds_read_b128 v[218:221], v154 offset:23552
	global_load_lds_dwordx4 v[146:147], off
	s_add_i32 m0, s39, 0x2000
	s_add_u32 s68, s34, 0x80000
	v_lshl_add_u64 v[222:223], s[34:35], 0, v[128:129]
	s_addc_u32 s69, s35, 0
	s_add_i32 s39, s63, s47
	global_load_lds_dwordx4 v[222:223], off
	v_lshl_add_u64 v[224:225], s[68:69], 0, v[132:133]
	s_mov_b32 m0, s39
	v_lshl_add_u64 v[226:227], s[36:37], 0, v[130:131]
	global_load_lds_dwordx4 v[224:225], off
	v_lshl_add_u64 v[224:225], s[68:69], 0, v[128:129]
	s_add_i32 m0, s39, 0x2000
	s_nop 0
	global_load_lds_dwordx4 v[224:225], off
	v_lshl_add_u64 v[224:225], s[36:37], 0, v[134:135]
	s_mov_b32 m0, s29
	s_nop 0
	global_load_lds_dwordx4 v[224:225], off
	s_mov_b32 m0, s49
	s_nop 0
	global_load_lds_dwordx4 v[226:227], off
	s_waitcnt vmcnt(8)
	s_waitcnt lgkmcnt(0)
	s_barrier
; #define PG8_STAGE(bufoff, gbase, voff) do { _Pragma("unroll") for (int _i = 0; _i < 2; ++_i) \
;         __builtin_amdgcn_global_load_lds((const unsigned*)((const char*)(gbase) + (voff)[_i]), (PG8_LAS unsigned*)(lds + (bufoff) + ldsw + _i * 8192), 16, 0, 0); } while (0)
; #define PG8_LDA(dst, b, h) do { _Pragma("unroll") for (int m = 0; m < 4; ++m) _Pragma("unroll") for (int k = 0; k < 2; ++k) dst[m][k] = *(const PG8_LAS bf16x8*)(lds + PG8_SA(b, h) + aoff + m * 2048 + k * 1024); } while (0)
; #define PG8_LDB(dst, b, h) do { _Pragma("unroll") for (int n = 0; n < 2; ++n) _Pragma("unroll") for (int k = 0; k < 2; ++k) dst[n][k] = *(const PG8_LAS bf16x8*)(lds + PG8_SB(b, h) + boff + n * 2048 + k * 1024); } while (0)
; #define PG8_MMA(ai, bj, At, Bt) do { __builtin_amdgcn_s_setprio(1); _Pragma("unroll") for (int m = 0; m < 4; ++m) _Pragma("unroll") for (int n = 0; n < 2; ++n) _Pragma("unroll") for (int k = 0; k < 2; ++k) \
;         acc[ai][bj][m][n] = __builtin_amdgcn_mfma_f32_16x16x32_bf16(Bt[n][k], At[m][k], acc[ai][bj][m][n], 0, 0, 0); __builtin_amdgcn_s_setprio(0); } while (0)
; #define PG8_WAIT_V(n) asm volatile("s_waitcnt vmcnt(" #n ")" ::: "memory")
; #define PG8_WAIT_L(n) asm volatile("s_waitcnt lgkmcnt(" #n ")" ::: "memory")
; #define PG8_BAR __builtin_amdgcn_s_barrier()
; #define PG8_SCHED __builtin_amdgcn_sched_barrier(0)
; template <class Epi, class Sched, bool ALIGN_EPI = false, bool SP2 = false>
; __device__ __forceinline__ void gemm_phase(PG8_LAS unsigned char* lds, const Gemm g, const Sched& S, const Epi& E, const int wv0) {
;     ...
;             PG8_WAIT_V(8); PG8_WAIT_L(0); PG8_BAR; PG8_MMA(1, 0, At, B0); PG8_MMA(1, 1, At, B1); PG8_BAR; PG8_SCHED;
;             PG8_LDB(B0, 1, 0); PG8_LDB(B1, 1, 1); PG8_SCHED; PG8_LDA(At, 1, 0); PG8_STAGE(PG8_SA(0, 1), a2 + hstepA, voffA);
;             PG8_WAIT_V(8); PG8_WAIT_L(0); PG8_BAR; PG8_MMA(0, 0, At, B0); PG8_MMA(0, 1, At, B1); PG8_BAR; PG8_SCHED;
	v_mfma_f32_16x16x32_bf16 v[60:63], v[156:159], v[188:191], v[60:63]
	v_mfma_f32_16x16x32_bf16 v[56:59], v[164:167], v[188:191], v[56:59]
	v_mfma_f32_16x16x32_bf16 v[52:55], v[156:159], v[196:199], v[52:55]
	v_mfma_f32_16x16x32_bf16 v[44:47], v[164:167], v[196:199], v[44:47]
	v_mfma_f32_16x16x32_bf16 v[36:39], v[156:159], v[206:209], v[36:39]
	v_mfma_f32_16x16x32_bf16 v[28:31], v[164:167], v[206:209], v[28:31]
	v_mfma_f32_16x16x32_bf16 v[20:23], v[156:159], v[214:217], v[20:23]
	v_mfma_f32_16x16x32_bf16 v[12:15], v[164:167], v[214:217], v[12:15]
	v_mfma_f32_16x16x32_bf16 v[60:63], v[160:163], v[192:195], v[60:63]
	v_mfma_f32_16x16x32_bf16 v[56:59], v[168:171], v[192:195], v[56:59]
	v_mfma_f32_16x16x32_bf16 v[52:55], v[160:163], v[200:203], v[52:55]
	v_mfma_f32_16x16x32_bf16 v[44:47], v[168:171], v[200:203], v[44:47]
	v_mfma_f32_16x16x32_bf16 v[36:39], v[160:163], v[210:213], v[36:39]
	v_mfma_f32_16x16x32_bf16 v[28:31], v[168:171], v[210:213], v[28:31]
	v_mfma_f32_16x16x32_bf16 v[20:23], v[160:163], v[218:221], v[20:23]
	v_mfma_f32_16x16x32_bf16 v[12:15], v[168:171], v[218:221], v[12:15]
	v_mfma_f32_16x16x32_bf16 v[48:51], v[172:175], v[188:191], v[48:51]
	v_mfma_f32_16x16x32_bf16 v[40:43], v[180:183], v[188:191], v[40:43]
	v_mfma_f32_16x16x32_bf16 v[32:35], v[172:175], v[196:199], v[32:35]
	v_mfma_f32_16x16x32_bf16 v[24:27], v[180:183], v[196:199], v[24:27]
	v_mfma_f32_16x16x32_bf16 v[16:19], v[172:175], v[206:209], v[16:19]
	v_mfma_f32_16x16x32_bf16 v[8:11], v[180:183], v[206:209], v[8:11]
	v_mfma_f32_16x16x32_bf16 v[4:7], v[172:175], v[214:217], v[4:7]
	v_mfma_f32_16x16x32_bf16 v[0:3], v[180:183], v[214:217], v[0:3]
	v_mfma_f32_16x16x32_bf16 v[48:51], v[176:179], v[192:195], v[48:51]
	v_mfma_f32_16x16x32_bf16 v[40:43], v[184:187], v[192:195], v[40:43]
	v_mfma_f32_16x16x32_bf16 v[32:35], v[176:179], v[200:203], v[32:35]
	v_mfma_f32_16x16x32_bf16 v[24:27], v[184:187], v[200:203], v[24:27]
	v_mfma_f32_16x16x32_bf16 v[16:19], v[176:179], v[210:213], v[16:19]
	v_mfma_f32_16x16x32_bf16 v[8:11], v[184:187], v[210:213], v[8:11]
	v_mfma_f32_16x16x32_bf16 v[4:7], v[176:179], v[218:221], v[4:7]
	v_mfma_f32_16x16x32_bf16 v[0:3], v[184:187], v[218:221], v[0:3]
	s_barrier
	s_add_i32 s39, 0, 0x18000
	v_add_u32_e32 v155, s39, v150
	s_add_i32 s68, 0, 0x1c000
	ds_read_b128 v[156:159], v155
	ds_read_b128 v[160:163], v155 offset:1024
	ds_read_b128 v[164:167], v155 offset:2048
	ds_read_b128 v[168:171], v155 offset:3072
	v_add_u32_e32 v155, s68, v150
	ds_read_b128 v[172:175], v155
	ds_read_b128 v[176:179], v155 offset:1024
	ds_read_b128 v[180:183], v155 offset:2048
	ds_read_b128 v[184:187], v155 offset:3072
	s_add_u32 s36, s36, 0x80000
	s_addc_u32 s37, s37, 0
	s_mov_b32 m0, s50
	v_lshl_add_u64 v[228:229], s[36:37], 0, v[134:135]
	ds_read_b128 v[188:191], v154 offset:32768
	ds_read_b128 v[192:195], v154 offset:33792
	ds_read_b128 v[196:199], v154 offset:34816
	ds_read_b128 v[200:203], v154 offset:35840
	ds_read_b128 v[206:209], v154 offset:36864
	ds_read_b128 v[210:213], v154 offset:37888
	ds_read_b128 v[214:217], v154 offset:38912
	ds_read_b128 v[218:221], v154 offset:39936
	global_load_lds_dwordx4 v[228:229], off
	v_lshl_add_u64 v[228:229], s[36:37], 0, v[130:131]
	s_mov_b32 m0, s51
	s_nop 0
	global_load_lds_dwordx4 v[228:229], off
	s_waitcnt vmcnt(8)
	s_waitcnt lgkmcnt(0)
	s_barrier
	v_mfma_f32_16x16x32_bf16 v[124:127], v[156:159], v[188:191], v[124:127]
	v_mfma_f32_16x16x32_bf16 v[120:123], v[164:167], v[188:191], v[120:123]
	v_mfma_f32_16x16x32_bf16 v[116:119], v[156:159], v[196:199], v[116:119]
	v_mfma_f32_16x16x32_bf16 v[108:111], v[164:167], v[196:199], v[108:111]
	v_mfma_f32_16x16x32_bf16 v[100:103], v[156:159], v[206:209], v[100:103]
	v_mfma_f32_16x16x32_bf16 v[92:95], v[164:167], v[206:209], v[92:95]
	v_mfma_f32_16x16x32_bf16 v[84:87], v[156:159], v[214:217], v[84:87]
	v_mfma_f32_16x16x32_bf16 v[76:79], v[164:167], v[214:217], v[76:79]
	v_mfma_f32_16x16x32_bf16 v[124:127], v[160:163], v[192:195], v[124:127]
	v_mfma_f32_16x16x32_bf16 v[120:123], v[168:171], v[192:195], v[120:123]
	v_mfma_f32_16x16x32_bf16 v[116:119], v[160:163], v[200:203], v[116:119]
	v_mfma_f32_16x16x32_bf16 v[108:111], v[168:171], v[200:203], v[108:111]
	v_mfma_f32_16x16x32_bf16 v[100:103], v[160:163], v[210:213], v[100:103]
	v_mfma_f32_16x16x32_bf16 v[92:95], v[168:171], v[210:213], v[92:95]
	v_mfma_f32_16x16x32_bf16 v[84:87], v[160:163], v[218:221], v[84:87]
	v_mfma_f32_16x16x32_bf16 v[76:79], v[168:171], v[218:221], v[76:79]
	v_mfma_f32_16x16x32_bf16 v[112:115], v[172:175], v[188:191], v[112:115]
	v_mfma_f32_16x16x32_bf16 v[104:107], v[180:183], v[188:191], v[104:107]
	v_mfma_f32_16x16x32_bf16 v[96:99], v[172:175], v[196:199], v[96:99]
	v_mfma_f32_16x16x32_bf16 v[88:91], v[180:183], v[196:199], v[88:91]
	v_mfma_f32_16x16x32_bf16 v[80:83], v[172:175], v[206:209], v[80:83]
	v_mfma_f32_16x16x32_bf16 v[72:75], v[180:183], v[206:209], v[72:75]
	v_mfma_f32_16x16x32_bf16 v[68:71], v[172:175], v[214:217], v[68:71]
	v_mfma_f32_16x16x32_bf16 v[64:67], v[180:183], v[214:217], v[64:67]
	v_mfma_f32_16x16x32_bf16 v[112:115], v[176:179], v[192:195], v[112:115]
	v_mfma_f32_16x16x32_bf16 v[104:107], v[184:187], v[192:195], v[104:107]
	v_mfma_f32_16x16x32_bf16 v[96:99], v[176:179], v[200:203], v[96:99]
	v_mfma_f32_16x16x32_bf16 v[88:91], v[184:187], v[200:203], v[88:91]
	v_mfma_f32_16x16x32_bf16 v[80:83], v[176:179], v[210:213], v[80:83]
	v_mfma_f32_16x16x32_bf16 v[72:75], v[184:187], v[210:213], v[72:75]
	v_mfma_f32_16x16x32_bf16 v[68:71], v[176:179], v[218:221], v[68:71]
	v_mfma_f32_16x16x32_bf16 v[64:67], v[184:187], v[218:221], v[64:67]
	s_barrier
; #define PG8_STAGE(bufoff, gbase, voff) do { _Pragma("unroll") for (int _i = 0; _i < 2; ++_i) \
;         __builtin_amdgcn_global_load_lds((const unsigned*)((const char*)(gbase) + (voff)[_i]), (PG8_LAS unsigned*)(lds + (bufoff) + ldsw + _i * 8192), 16, 0, 0); } while (0)
; #define PG8_LDA(dst, b, h) do { _Pragma("unroll") for (int m = 0; m < 4; ++m) _Pragma("unroll") for (int k = 0; k < 2; ++k) dst[m][k] = *(const PG8_LAS bf16x8*)(lds + PG8_SA(b, h) + aoff + m * 2048 + k * 1024); } while (0)
; #define PG8_MMA(ai, bj, At, Bt) do { __builtin_amdgcn_s_setprio(1); _Pragma("unroll") for (int m = 0; m < 4; ++m) _Pragma("unroll") for (int n = 0; n < 2; ++n) _Pragma("unroll") for (int k = 0; k < 2; ++k) \
;         acc[ai][bj][m][n] = __builtin_amdgcn_mfma_f32_16x16x32_bf16(Bt[n][k], At[m][k], acc[ai][bj][m][n], 0, 0, 0); __builtin_amdgcn_s_setprio(0); } while (0)
; #define PG8_WAIT_V(n) asm volatile("s_waitcnt vmcnt(" #n ")" ::: "memory")
; #define PG8_WAIT_L(n) asm volatile("s_waitcnt lgkmcnt(" #n ")" ::: "memory")
; #define PG8_BAR __builtin_amdgcn_s_barrier()
; #define PG8_SCHED __builtin_amdgcn_sched_barrier(0)
; template <class Epi, class Sched, bool ALIGN_EPI = false, bool SP2 = false>
; __device__ __forceinline__ void gemm_phase(PG8_LAS unsigned char* lds, const Gemm g, const Sched& S, const Epi& E, const int wv0) {
;     ...
;         for (int t = 0; t < nt; t += 2) {
;             const bool last = (t == nt - 2);
;             const char* a1 = cA + (size_t)(t + 1) * kstep;
;             const char* a2 = last ? nA : cA + (size_t)(t + 2) * kstep; const char* b2 = last ? nB : cB + (size_t)(t + 2) * kstep;
;     ...
;             PG8_LDA(At, 1, 1); PG8_STAGE(PG8_SB(1, 0), b3, voffB); PG8_STAGE(PG8_SB(1, 1), b3 + hstepB, voffB); PG8_STAGE(PG8_SA(1, 0), a3, voffA);
;             PG8_WAIT_V(8); PG8_WAIT_L(0); PG8_BAR; PG8_MMA(1, 0, At, B0); PG8_MMA(1, 1, At, B1); PG8_BAR; PG8_SCHED;
	s_add_i32 s36, s39, s47
	v_lshl_add_u64 v[146:147], v[146:147], 0, s[14:15]
	s_mov_b32 m0, s36
	ds_read_b128 v[188:191], v154 offset:49152
	ds_read_b128 v[192:195], v154 offset:50176
	ds_read_b128 v[196:199], v154 offset:51200
	ds_read_b128 v[200:203], v154 offset:52224
	ds_read_b128 v[206:209], v154 offset:53248
	ds_read_b128 v[210:213], v154 offset:54272
	ds_read_b128 v[214:217], v154 offset:55296
	ds_read_b128 v[218:221], v154 offset:56320
	global_load_lds_dwordx4 v[146:147], off
	s_add_i32 m0, s36, 0x2000
	s_add_u32 s34, s34, 0x80080
	v_lshl_add_u64 v[146:147], v[222:223], 0, s[14:15]
	s_addc_u32 s35, s35, 0
	s_add_i32 s36, s68, s47
	global_load_lds_dwordx4 v[146:147], off
	v_lshl_add_u64 v[146:147], s[34:35], 0, v[132:133]
	s_mov_b32 m0, s36
	s_nop 0
	global_load_lds_dwordx4 v[146:147], off
	v_lshl_add_u64 v[146:147], s[34:35], 0, v[128:129]
	s_add_i32 m0, s36, 0x2000
	s_nop 0
	global_load_lds_dwordx4 v[146:147], off
	v_lshl_add_u64 v[146:147], v[224:225], 0, s[14:15]
	s_mov_b32 m0, s58
	s_nop 0
	global_load_lds_dwordx4 v[146:147], off
	v_lshl_add_u64 v[146:147], v[226:227], 0, s[14:15]
	s_mov_b32 m0, s59
	s_nop 0
	global_load_lds_dwordx4 v[146:147], off
	s_waitcnt vmcnt(8)
	s_waitcnt lgkmcnt(0)
	s_barrier
	v_mfma_f32_16x16x32_bf16 v[60:63], v[156:159], v[188:191], v[60:63]
	v_mfma_f32_16x16x32_bf16 v[56:59], v[164:167], v[188:191], v[56:59]
	v_mfma_f32_16x16x32_bf16 v[52:55], v[156:159], v[196:199], v[52:55]
	v_mfma_f32_16x16x32_bf16 v[44:47], v[164:167], v[196:199], v[44:47]
	v_mfma_f32_16x16x32_bf16 v[36:39], v[156:159], v[206:209], v[36:39]
	v_mfma_f32_16x16x32_bf16 v[28:31], v[164:167], v[206:209], v[28:31]
	v_mfma_f32_16x16x32_bf16 v[20:23], v[156:159], v[214:217], v[20:23]
	v_mfma_f32_16x16x32_bf16 v[12:15], v[164:167], v[214:217], v[12:15]
	v_mfma_f32_16x16x32_bf16 v[60:63], v[160:163], v[192:195], v[60:63]
	v_mfma_f32_16x16x32_bf16 v[56:59], v[168:171], v[192:195], v[56:59]
	v_mfma_f32_16x16x32_bf16 v[52:55], v[160:163], v[200:203], v[52:55]
	v_mfma_f32_16x16x32_bf16 v[44:47], v[168:171], v[200:203], v[44:47]
	v_mfma_f32_16x16x32_bf16 v[36:39], v[160:163], v[210:213], v[36:39]
	v_mfma_f32_16x16x32_bf16 v[28:31], v[168:171], v[210:213], v[28:31]
	v_mfma_f32_16x16x32_bf16 v[20:23], v[160:163], v[218:221], v[20:23]
	v_mfma_f32_16x16x32_bf16 v[12:15], v[168:171], v[218:221], v[12:15]
	v_mfma_f32_16x16x32_bf16 v[48:51], v[172:175], v[188:191], v[48:51]
	v_mfma_f32_16x16x32_bf16 v[40:43], v[180:183], v[188:191], v[40:43]
	v_mfma_f32_16x16x32_bf16 v[32:35], v[172:175], v[196:199], v[32:35]
	v_mfma_f32_16x16x32_bf16 v[24:27], v[180:183], v[196:199], v[24:27]
	v_mfma_f32_16x16x32_bf16 v[16:19], v[172:175], v[206:209], v[16:19]
	v_mfma_f32_16x16x32_bf16 v[8:11], v[180:183], v[206:209], v[8:11]
	v_mfma_f32_16x16x32_bf16 v[4:7], v[172:175], v[214:217], v[4:7]
	v_mfma_f32_16x16x32_bf16 v[0:3], v[180:183], v[214:217], v[0:3]
	v_mfma_f32_16x16x32_bf16 v[48:51], v[176:179], v[192:195], v[48:51]
	v_mfma_f32_16x16x32_bf16 v[40:43], v[184:187], v[192:195], v[40:43]
	v_mfma_f32_16x16x32_bf16 v[32:35], v[176:179], v[200:203], v[32:35]
	v_mfma_f32_16x16x32_bf16 v[24:27], v[184:187], v[200:203], v[24:27]
	v_mfma_f32_16x16x32_bf16 v[16:19], v[176:179], v[210:213], v[16:19]
	v_mfma_f32_16x16x32_bf16 v[8:11], v[184:187], v[210:213], v[8:11]
	v_mfma_f32_16x16x32_bf16 v[4:7], v[176:179], v[218:221], v[4:7]
	v_mfma_f32_16x16x32_bf16 v[0:3], v[184:187], v[218:221], v[0:3]
	s_barrier
	s_add_i32 s38, s38, 2
	s_add_u32 s21, s21, 0x100
	s_addc_u32 s23, s23, 0
	s_add_u32 s30, s30, 0x100
	s_addc_u32 s31, s31, 0
	s_cmp_gt_u32 s38, 29
	s_cbranch_scc0 .LBB0_82
	s_and_b64 vcc, exec, s[18:19]
	s_cbranch_vccz .LBB0_85
	s_barrier

; #define TID() (wv0 * 64 + (int)__builtin_amdgcn_mbcnt_hi(~0u, __builtin_amdgcn_mbcnt_lo(~0u, 0u)))
; __device__ __forceinline__ int opaque(int x) { asm volatile("" : "+v"(x)); return x; }
; #define PG8_WAIT_V(n) asm volatile("s_waitcnt vmcnt(" #n ")" ::: "memory")
; #define PG8_BAR __builtin_amdgcn_s_barrier()
; template <class Epi, class Sched, bool ALIGN_EPI = false, bool SP2 = false>
; __device__ __forceinline__ void gemm_phase(PG8_LAS unsigned char* lds, const Gemm g, const Sched& S, const Epi& E, const int wv0) {
;     ...
;     PG8_WAIT_V(0);
;     if constexpr (!ALIGN_EPI) { if (wr == 0) PG8_BAR; }
;     PG8_BAR;
; __device__ __forceinline__ void xcd_barrier(const XcdBarrier& b, const int wv0) {
;     const bool TID0 = (opaque(TID()) == 0);
;     asm volatile("s_waitcnt vmcnt(0)" ::: "memory");
;     __syncthreads();
;     if (TID0) {
;         unsigned* bar = b.bar;
;         __builtin_amdgcn_s_waitcnt(0);
;         unsigned nloc = b.st[0], nx = b.st[1];
;         if (nloc == 0u) { xcd_barrier_complete(bar, b.x, nloc, nx); b.st[0] = nloc; b.st[1] = nx; }
.LBB0_109:
	s_waitcnt vmcnt(0)
	s_barrier
	s_setprio 0
	v_mov_b32 v0, s77
	ds_read_b64 v[0:1], v0 offset:168
	s_getreg_b32 s4, hwreg(HW_REG_XCC_ID, 0, 4)
	s_add_i32 s78, 0, 0x23fc0
	s_waitcnt lgkmcnt(0)
	v_readfirstlane_b32 s2, v0
	v_mov_b32_e32 v0, v204
	v_readfirstlane_b32 s3, v1
	v_mov_b32 v1, s78
	s_waitcnt vmcnt(0)
	s_nop 0
	v_cmp_eq_u32_e32 vcc, 0, v0
	s_barrier
	s_and_saveexec_b64 s[0:1], vcc
	s_xor_b64 s[0:1], exec, s[0:1]
	s_cbranch_execz .LBB0_162
	s_waitcnt vmcnt(0) expcnt(0) lgkmcnt(0)
	ds_read_b32 v2, v1
	ds_read_b32 v0, v1 offset:4
	s_and_b32 s40, s4, 15
	s_waitcnt lgkmcnt(1)
	v_cmp_eq_u32_e32 vcc, 0, v2
	s_and_saveexec_b64 s[4:5], vcc
	s_cbranch_execz .LBB0_125
	s_add_u32 s6, s2, 0x2e400200
	s_addc_u32 s7, s3, 0
	s_add_u32 s8, s2, 0x2e400400
	s_addc_u32 s9, s3, 0
	s_add_u32 s10, s2, 0x2e400500
	s_addc_u32 s11, s3, 0
	s_add_u32 s12, s2, 0x2e400600
	s_addc_u32 s13, s3, 0
	s_add_u32 s14, s2, 0x2e400700
	s_addc_u32 s15, s3, 0
	s_add_u32 s16, s2, 0x2e400800
	s_addc_u32 s17, s3, 0
	s_add_u32 s18, s2, 0x2e400900
	s_addc_u32 s19, s3, 0
	s_add_u32 s20, s2, 0x2e400a00
	s_addc_u32 s21, s3, 0
	s_add_u32 s22, s2, 0x2e400b00
	s_addc_u32 s23, s3, 0
	s_add_u32 s24, s2, 0x2e400c00
	s_addc_u32 s25, s3, 0
	s_add_u32 s26, s2, 0x2e400d00
	s_addc_u32 s27, s3, 0
	s_add_u32 s28, s2, 0x2e400e00
	s_addc_u32 s29, s3, 0
	s_add_u32 s30, s2, 0x2e400f00
	s_addc_u32 s31, s3, 0
	s_add_u32 s34, s2, 0x2e401000
	s_addc_u32 s35, s3, 0
	s_add_u32 s36, s2, 0x2e401100
	s_addc_u32 s37, s3, 0
	s_add_u32 s38, s2, 0x2e401200
	s_addc_u32 s39, s3, 0
	s_mul_i32 s41, s43, s76
	s_add_u32 s44, s2, 0x2e401300
	s_mul_i32 s41, s41, s42
	s_addc_u32 s45, s3, 0
	s_mov_b32 s52, 1
	v_mov_b32_e32 v17, 0
	s_branch .LBB0_113

;     __device__ __forceinline__ bool next(int i, Unit& u) const { int pm, pn; if (!to.get((long)i * G + c, pm, pn)) return false; u.pm = pm; u.pn = pn; u.aux = 0; u.a = A + (size_t)pm * ta; u.b = B + (size_t)pn * tb; return true; }
;     __device__ __forceinline__ bool next(int i, Unit& u) const { if (i != 0) return false; u = one; return true; }
;     __device__ __forceinline__ unsigned char* ws() const { return (unsigned char*)(__attribute__((address_space(1))) unsigned char*)get(21); }
;     __device__ __forceinline__ bool get(long L, int& pm, int& pn) const {
;         if (L >= nwg) return false;
;         int wgid = (int)L; { const int q = nwg / NXCD, r = nwg % NXCD, xcd = wgid % NXCD, off = wgid / NXCD; wgid = (xcd < r ? xcd * (q + 1) : r * (q + 1) + (xcd - r) * q) + off; }
;         const int nig = WGM * nN, gid = wgid / nig, fm = gid * WGM, gsz = (nM - fm) < WGM ? (nM - fm) : WGM;
;         pm = fm + ((wgid % nig) % gsz); pn = (wgid % nig) / gsz; return true;
;     }
;     __device__ __forceinline__ bool next(int i, Unit& u) const { int pm, pn; const int tl = i / 3, br = i - tl * 3; if (!to.get((long)tl * G + c, pm, pn)) return false; u.pm = pm; u.pn = pn; u.aux = br;
;         u.a = A + ((size_t)br * T + (size_t)pm * 256) * 1024 * 2; u.b = B + ((size_t)br * 2048 + (size_t)pn * 256) * 1024 * 2; return true; }
; template <int l>
; __device__ __forceinline__ void layer_body(const Ptrs& A, LAS unsigned char* lds, unsigned char* lds_raw, const int wv0) {
;     ...
;             pg8::Gemm g{1024, 1024, 1024}; pg8::SchedBranch S; S.to.init(T / 256, DM / 256); S.G = G; S.c = c; S.A = (const char*)(ws + WS_ABR); S.B = (const char*)(ws + WS_WBR);
;             pg8::EpiMerge E{(const unsigned char*)(ws + WS_GATES), (bf16*)(ws + WS_GV)};
; #pragma unroll 1
;             for (int rep = 0; rep < 1 + DUP_GEMM; ++rep) { pg8::gemm_phase<pg8::EpiMerge, pg8::SchedBranch, true, true>(lds, g, S, E, wv0); __syncthreads(); }
.LBB0_479:
	s_or_b64 exec, exec, s[0:1]
	s_waitcnt lgkmcnt(0)
	s_barrier
	v_readfirstlane_b32 s79, v204
	s_lshr_b32 s79, s79, 6
	s_cmp_ge_u32 s79, 4
	s_cbranch_scc0 .Lprio_skip_8
	s_setprio 1
.Lprio_skip_8:
	v_mov_b32 v0, s77
	ds_read_b64 v[0:1], v0 offset:168
	s_mov_b32 s15, s76
	s_mov_b32 s48, s33
	v_mov_b32_e32 v8, v204
	s_waitcnt lgkmcnt(0)
	v_readfirstlane_b32 s1, v1
	v_readfirstlane_b32 s0, v0
	s_add_u32 s49, s0, 0x27a00000
	s_addc_u32 s50, s1, 0
	s_add_u32 s51, s0, 0x3400000
	v_mov_b32_e32 v0, v204
	s_addc_u32 s52, s1, 0
	s_cmpk_lt_i32 s48, 0x200
	s_cselect_b64 s[4:5], -1, 0
	s_ashr_i32 s53, s48, 31
	s_and_b64 vcc, exec, s[4:5]
	v_readfirstlane_b32 s14, v8
	s_cbranch_vccz .LBB0_481
	s_lshr_b32 s2, s53, 29
	s_add_i32 s2, s48, s2
	s_ashr_i32 s3, s2, 3
	s_and_b32 s2, s2, -8
	s_sub_i32 s2, s48, s2
	s_lshl_b32 s7, s2, 6
	s_mul_i32 s6, s2, 0x41
	s_cmp_lt_i32 s2, 0
	s_cselect_b32 s2, s6, s7
	s_add_i32 s2, s2, s3
	s_ashr_i32 s3, s2, 31
	s_lshr_b32 s3, s3, 27
	s_add_i32 s3, s2, s3
	s_ashr_i32 s6, s3, 5
	s_and_b32 s3, s3, 0xffe0
	s_sub_i32 s2, s2, s3
	s_lshl_b32 s3, s6, 2
	s_bfe_i32 s6, s2, 0x80000
	s_bfe_u32 s6, s6, 0x2000d
	s_add_i32 s7, s2, s6
	s_bfe_i32 s6, s7, 0x80000
	s_and_b32 s7, s7, 0xfc
	s_sub_i32 s2, s2, s7
	s_sext_i32_i8 s2, s2
	s_add_i32 s2, s3, s2
	s_sext_i32_i16 s8, s6
	s_ashr_i32 s3, s2, 31
	s_lshr_b32 s6, s8, 2
	s_ashr_i32 s40, s8, 2
	s_lshl_b64 s[8:9], s[2:3], 19
	s_add_u32 s38, s49, s8
	s_addc_u32 s39, s50, s9
	s_bfe_i64 s[6:7], s[6:7], 0x100000
	s_lshl_b64 s[6:7], s[6:7], 19
	s_add_u32 s44, s51, s6
	s_addc_u32 s45, s52, s7
	s_andn2_b64 vcc, exec, s[4:5]
	s_cbranch_vccz .LBB0_482
	s_branch .LBB0_597

; #define PG8_STAGE(bufoff, gbase, voff) do { _Pragma("unroll") for (int _i = 0; _i < 2; ++_i) \
;         __builtin_amdgcn_global_load_lds((const unsigned*)((const char*)(gbase) + (voff)[_i]), (PG8_LAS unsigned*)(lds + (bufoff) + ldsw + _i * 8192), 16, 0, 0); } while (0)
; #define PG8_LDA(dst, b, h) do { _Pragma("unroll") for (int m = 0; m < 4; ++m) _Pragma("unroll") for (int k = 0; k < 2; ++k) dst[m][k] = *(const PG8_LAS bf16x8*)(lds + PG8_SA(b, h) + aoff + m * 2048 + k * 1024); } while (0)
; #define PG8_LDB(dst, b, h) do { _Pragma("unroll") for (int n = 0; n < 2; ++n) _Pragma("unroll") for (int k = 0; k < 2; ++k) dst[n][k] = *(const PG8_LAS bf16x8*)(lds + PG8_SB(b, h) + boff + n * 2048 + k * 1024); } while (0)
; #define PG8_MMA(ai, bj, At, Bt) do { __builtin_amdgcn_s_setprio(1); _Pragma("unroll") for (int m = 0; m < 4; ++m) _Pragma("unroll") for (int n = 0; n < 2; ++n) _Pragma("unroll") for (int k = 0; k < 2; ++k) \
;         acc[ai][bj][m][n] = __builtin_amdgcn_mfma_f32_16x16x32_bf16(Bt[n][k], At[m][k], acc[ai][bj][m][n], 0, 0, 0); __builtin_amdgcn_s_setprio(0); } while (0)
; #define PG8_WAIT_V(n) asm volatile("s_waitcnt vmcnt(" #n ")" ::: "memory")
; #define PG8_WAIT_L(n) asm volatile("s_waitcnt lgkmcnt(" #n ")" ::: "memory")
; #define PG8_BAR __builtin_amdgcn_s_barrier()
; #define PG8_SCHED __builtin_amdgcn_sched_barrier(0)
; template <class Epi, class Sched, bool ALIGN_EPI = false, bool SP2 = false>
; __device__ __forceinline__ void gemm_phase(PG8_LAS unsigned char* lds, const Gemm g, const Sched& S, const Epi& E, const int wv0) {
;     ...
;             PG8_LDB(B0, 0, 0); PG8_LDB(B1, 0, 1); PG8_SCHED; PG8_LDA(At, 0, 0); PG8_STAGE(PG8_SA(1, 1), a1 + hstepA, voffA);
;             PG8_WAIT_V(8); PG8_WAIT_L(0); PG8_BAR; PG8_MMA(0, 0, At, B0); PG8_MMA(0, 1, At, B1); PG8_BAR; PG8_SCHED;
.LBB0_494:
	v_add_u32_e32 v158, s61, v207
	v_add_u32_e32 v174, s62, v207
	ds_read_b128 v[146:149], v158
	ds_read_b128 v[150:153], v158 offset:1024
	ds_read_b128 v[154:157], v158 offset:2048
	ds_read_b128 v[158:161], v158 offset:3072
	ds_read_b128 v[162:165], v174
	ds_read_b128 v[166:169], v174 offset:1024
	ds_read_b128 v[170:173], v174 offset:2048
	ds_read_b128 v[174:177], v174 offset:3072
	s_add_u32 s41, s38, 0xfffc0080
	s_addc_u32 s44, s39, -1
	s_cmp_eq_u32 s29, 12
	s_cselect_b32 s47, s5, s44
	s_cselect_b32 s46, s4, s41
	s_cselect_b32 s45, s37, s27
	s_cselect_b32 s44, s36, s25
	v_lshl_add_u64 v[202:203], s[38:39], 0, v[140:141]
	s_add_i32 m0, s55, 0xc000
	ds_read_b128 v[178:181], v209
	ds_read_b128 v[182:185], v209 offset:1024
	ds_read_b128 v[186:189], v209 offset:2048
	ds_read_b128 v[190:193], v209 offset:3072
	ds_read_b128 v[194:197], v209 offset:4096
	ds_read_b128 v[198:201], v209 offset:5120
	ds_read_b128 v[210:213], v209 offset:6144
	ds_read_b128 v[214:217], v209 offset:7168
	global_load_lds_dwordx4 v[202:203], off
	v_lshl_add_u64 v[202:203], s[38:39], 0, v[138:139]
	s_add_i32 m0, s55, 0xe000
	s_nop 0
	global_load_lds_dwordx4 v[202:203], off
	s_waitcnt vmcnt(8)
	s_waitcnt lgkmcnt(0)
	s_barrier
	v_mfma_f32_16x16x32_bf16 v[124:127], v[146:149], v[178:181], v[124:127]
	v_mfma_f32_16x16x32_bf16 v[120:123], v[154:157], v[178:181], v[120:123]
	v_mfma_f32_16x16x32_bf16 v[108:111], v[146:149], v[186:189], v[108:111]
	v_mfma_f32_16x16x32_bf16 v[104:107], v[154:157], v[186:189], v[104:107]
	v_mfma_f32_16x16x32_bf16 v[92:95], v[146:149], v[194:197], v[92:95]
	v_mfma_f32_16x16x32_bf16 v[88:91], v[154:157], v[194:197], v[88:91]
	v_mfma_f32_16x16x32_bf16 v[76:79], v[146:149], v[210:213], v[76:79]
	v_mfma_f32_16x16x32_bf16 v[72:75], v[154:157], v[210:213], v[72:75]
	v_mfma_f32_16x16x32_bf16 v[124:127], v[150:153], v[182:185], v[124:127]
	v_mfma_f32_16x16x32_bf16 v[120:123], v[158:161], v[182:185], v[120:123]
	v_mfma_f32_16x16x32_bf16 v[108:111], v[150:153], v[190:193], v[108:111]
	v_mfma_f32_16x16x32_bf16 v[104:107], v[158:161], v[190:193], v[104:107]
	v_mfma_f32_16x16x32_bf16 v[92:95], v[150:153], v[198:201], v[92:95]
	v_mfma_f32_16x16x32_bf16 v[88:91], v[158:161], v[198:201], v[88:91]
	v_mfma_f32_16x16x32_bf16 v[76:79], v[150:153], v[214:217], v[76:79]
	v_mfma_f32_16x16x32_bf16 v[72:75], v[158:161], v[214:217], v[72:75]
	v_mfma_f32_16x16x32_bf16 v[116:119], v[162:165], v[178:181], v[116:119]
	v_mfma_f32_16x16x32_bf16 v[112:115], v[170:173], v[178:181], v[112:115]
	v_mfma_f32_16x16x32_bf16 v[100:103], v[162:165], v[186:189], v[100:103]
	v_mfma_f32_16x16x32_bf16 v[96:99], v[170:173], v[186:189], v[96:99]
	v_mfma_f32_16x16x32_bf16 v[84:87], v[162:165], v[194:197], v[84:87]
	v_mfma_f32_16x16x32_bf16 v[80:83], v[170:173], v[194:197], v[80:83]
	v_mfma_f32_16x16x32_bf16 v[68:71], v[162:165], v[210:213], v[68:71]
	v_mfma_f32_16x16x32_bf16 v[64:67], v[170:173], v[210:213], v[64:67]
	v_mfma_f32_16x16x32_bf16 v[116:119], v[166:169], v[182:185], v[116:119]
	v_mfma_f32_16x16x32_bf16 v[112:115], v[174:177], v[182:185], v[112:115]
	v_mfma_f32_16x16x32_bf16 v[100:103], v[166:169], v[190:193], v[100:103]
	v_mfma_f32_16x16x32_bf16 v[96:99], v[174:177], v[190:193], v[96:99]
	v_mfma_f32_16x16x32_bf16 v[84:87], v[166:169], v[198:201], v[84:87]
	v_mfma_f32_16x16x32_bf16 v[80:83], v[174:177], v[198:201], v[80:83]
	v_mfma_f32_16x16x32_bf16 v[68:71], v[166:169], v[214:217], v[68:71]
	v_mfma_f32_16x16x32_bf16 v[64:67], v[174:177], v[214:217], v[64:67]
	s_barrier
	s_add_i32 s41, s61, s54
	v_lshl_add_u64 v[202:203], s[44:45], 0, v[130:131]
	s_mov_b32 m0, s41
	ds_read_b128 v[178:181], v209 offset:16384
	ds_read_b128 v[182:185], v209 offset:17408
	ds_read_b128 v[186:189], v209 offset:18432
	ds_read_b128 v[190:193], v209 offset:19456
	ds_read_b128 v[194:197], v209 offset:20480
	ds_read_b128 v[198:201], v209 offset:21504
	ds_read_b128 v[210:213], v209 offset:22528
	ds_read_b128 v[214:217], v209 offset:23552
	global_load_lds_dwordx4 v[202:203], off
	s_add_i32 m0, s41, 0x2000
	s_add_u32 s64, s44, 0x40000
	v_lshl_add_u64 v[218:219], s[44:45], 0, v[134:135]
	s_addc_u32 s65, s45, 0
	s_add_i32 s41, s62, s54
	global_load_lds_dwordx4 v[218:219], off
	v_lshl_add_u64 v[220:221], s[64:65], 0, v[130:131]
	s_mov_b32 m0, s41
	v_lshl_add_u64 v[222:223], s[46:47], 0, v[132:133]
	global_load_lds_dwordx4 v[220:221], off
	v_lshl_add_u64 v[220:221], s[64:65], 0, v[134:135]
	s_add_i32 m0, s41, 0x2000
	s_nop 0
	global_load_lds_dwordx4 v[220:221], off
	v_lshl_add_u64 v[220:221], s[46:47], 0, v[128:129]
	s_mov_b32 m0, s55
	s_nop 0
	global_load_lds_dwordx4 v[220:221], off
	s_mov_b32 m0, s56
	s_nop 0
	global_load_lds_dwordx4 v[222:223], off
	s_waitcnt vmcnt(8)
	s_waitcnt lgkmcnt(0)
	s_barrier
; #define PG8_STAGE(bufoff, gbase, voff) do { _Pragma("unroll") for (int _i = 0; _i < 2; ++_i) \
;         __builtin_amdgcn_global_load_lds((const unsigned*)((const char*)(gbase) + (voff)[_i]), (PG8_LAS unsigned*)(lds + (bufoff) + ldsw + _i * 8192), 16, 0, 0); } while (0)
; #define PG8_LDA(dst, b, h) do { _Pragma("unroll") for (int m = 0; m < 4; ++m) _Pragma("unroll") for (int k = 0; k < 2; ++k) dst[m][k] = *(const PG8_LAS bf16x8*)(lds + PG8_SA(b, h) + aoff + m * 2048 + k * 1024); } while (0)
; #define PG8_LDB(dst, b, h) do { _Pragma("unroll") for (int n = 0; n < 2; ++n) _Pragma("unroll") for (int k = 0; k < 2; ++k) dst[n][k] = *(const PG8_LAS bf16x8*)(lds + PG8_SB(b, h) + boff + n * 2048 + k * 1024); } while (0)
; #define PG8_MMA(ai, bj, At, Bt) do { __builtin_amdgcn_s_setprio(1); _Pragma("unroll") for (int m = 0; m < 4; ++m) _Pragma("unroll") for (int n = 0; n < 2; ++n) _Pragma("unroll") for (int k = 0; k < 2; ++k) \
;         acc[ai][bj][m][n] = __builtin_amdgcn_mfma_f32_16x16x32_bf16(Bt[n][k], At[m][k], acc[ai][bj][m][n], 0, 0, 0); __builtin_amdgcn_s_setprio(0); } while (0)
; #define PG8_WAIT_V(n) asm volatile("s_waitcnt vmcnt(" #n ")" ::: "memory")
; #define PG8_WAIT_L(n) asm volatile("s_waitcnt lgkmcnt(" #n ")" ::: "memory")
; #define PG8_BAR __builtin_amdgcn_s_barrier()
; #define PG8_SCHED __builtin_amdgcn_sched_barrier(0)
; template <class Epi, class Sched, bool ALIGN_EPI = false, bool SP2 = false>
; __device__ __forceinline__ void gemm_phase(PG8_LAS unsigned char* lds, const Gemm g, const Sched& S, const Epi& E, const int wv0) {
;     ...
;             PG8_WAIT_V(8); PG8_WAIT_L(0); PG8_BAR; PG8_MMA(1, 0, At, B0); PG8_MMA(1, 1, At, B1); PG8_BAR; PG8_SCHED;
;             PG8_LDB(B0, 1, 0); PG8_LDB(B1, 1, 1); PG8_SCHED; PG8_LDA(At, 1, 0); PG8_STAGE(PG8_SA(0, 1), a2 + hstepA, voffA);
;             PG8_WAIT_V(8); PG8_WAIT_L(0); PG8_BAR; PG8_MMA(0, 0, At, B0); PG8_MMA(0, 1, At, B1); PG8_BAR; PG8_SCHED;
	v_mfma_f32_16x16x32_bf16 v[60:63], v[146:149], v[178:181], v[60:63]
	v_mfma_f32_16x16x32_bf16 v[56:59], v[154:157], v[178:181], v[56:59]
	v_mfma_f32_16x16x32_bf16 v[44:47], v[146:149], v[186:189], v[44:47]
	v_mfma_f32_16x16x32_bf16 v[40:43], v[154:157], v[186:189], v[40:43]
	v_mfma_f32_16x16x32_bf16 v[28:31], v[146:149], v[194:197], v[28:31]
	v_mfma_f32_16x16x32_bf16 v[24:27], v[154:157], v[194:197], v[24:27]
	v_mfma_f32_16x16x32_bf16 v[12:15], v[146:149], v[210:213], v[12:15]
	v_mfma_f32_16x16x32_bf16 v[8:11], v[154:157], v[210:213], v[8:11]
	v_mfma_f32_16x16x32_bf16 v[60:63], v[150:153], v[182:185], v[60:63]
	v_mfma_f32_16x16x32_bf16 v[56:59], v[158:161], v[182:185], v[56:59]
	v_mfma_f32_16x16x32_bf16 v[44:47], v[150:153], v[190:193], v[44:47]
	v_mfma_f32_16x16x32_bf16 v[40:43], v[158:161], v[190:193], v[40:43]
	v_mfma_f32_16x16x32_bf16 v[28:31], v[150:153], v[198:201], v[28:31]
	v_mfma_f32_16x16x32_bf16 v[24:27], v[158:161], v[198:201], v[24:27]
	v_mfma_f32_16x16x32_bf16 v[12:15], v[150:153], v[214:217], v[12:15]
	v_mfma_f32_16x16x32_bf16 v[8:11], v[158:161], v[214:217], v[8:11]
	v_mfma_f32_16x16x32_bf16 v[52:55], v[162:165], v[178:181], v[52:55]
	v_mfma_f32_16x16x32_bf16 v[48:51], v[170:173], v[178:181], v[48:51]
	v_mfma_f32_16x16x32_bf16 v[36:39], v[162:165], v[186:189], v[36:39]
	v_mfma_f32_16x16x32_bf16 v[32:35], v[170:173], v[186:189], v[32:35]
	v_mfma_f32_16x16x32_bf16 v[20:23], v[162:165], v[194:197], v[20:23]
	v_mfma_f32_16x16x32_bf16 v[16:19], v[170:173], v[194:197], v[16:19]
	v_mfma_f32_16x16x32_bf16 v[4:7], v[162:165], v[210:213], v[4:7]
	v_mfma_f32_16x16x32_bf16 v[0:3], v[170:173], v[210:213], v[0:3]
	v_mfma_f32_16x16x32_bf16 v[52:55], v[166:169], v[182:185], v[52:55]
	v_mfma_f32_16x16x32_bf16 v[48:51], v[174:177], v[182:185], v[48:51]
	v_mfma_f32_16x16x32_bf16 v[36:39], v[166:169], v[190:193], v[36:39]
	v_mfma_f32_16x16x32_bf16 v[32:35], v[174:177], v[190:193], v[32:35]
	v_mfma_f32_16x16x32_bf16 v[20:23], v[166:169], v[198:201], v[20:23]
	v_mfma_f32_16x16x32_bf16 v[16:19], v[174:177], v[198:201], v[16:19]
	v_mfma_f32_16x16x32_bf16 v[4:7], v[166:169], v[214:217], v[4:7]
	v_mfma_f32_16x16x32_bf16 v[0:3], v[174:177], v[214:217], v[0:3]
	s_barrier
	s_add_i32 s41, 0, 0x18000
	s_add_i32 s64, 0, 0x1c000
	v_add_u32_e32 v158, s41, v207
	v_add_u32_e32 v174, s64, v207
	ds_read_b128 v[146:149], v158
	ds_read_b128 v[150:153], v158 offset:1024
	ds_read_b128 v[154:157], v158 offset:2048
	ds_read_b128 v[158:161], v158 offset:3072
	ds_read_b128 v[162:165], v174
	ds_read_b128 v[166:169], v174 offset:1024
	ds_read_b128 v[170:173], v174 offset:2048
	ds_read_b128 v[174:177], v174 offset:3072
	s_add_u32 s46, s46, 0x40000
	s_addc_u32 s47, s47, 0
	s_mov_b32 m0, s57
	v_lshl_add_u64 v[224:225], s[46:47], 0, v[128:129]
	ds_read_b128 v[178:181], v209 offset:32768
	ds_read_b128 v[182:185], v209 offset:33792
	ds_read_b128 v[186:189], v209 offset:34816
	ds_read_b128 v[190:193], v209 offset:35840
	ds_read_b128 v[194:197], v209 offset:36864
	ds_read_b128 v[198:201], v209 offset:37888
	ds_read_b128 v[210:213], v209 offset:38912
	ds_read_b128 v[214:217], v209 offset:39936
	global_load_lds_dwordx4 v[224:225], off
	v_lshl_add_u64 v[224:225], s[46:47], 0, v[132:133]
	s_mov_b32 m0, s58
	s_nop 0
	global_load_lds_dwordx4 v[224:225], off
	s_waitcnt vmcnt(8)
	s_waitcnt lgkmcnt(0)
	s_barrier
	v_mfma_f32_16x16x32_bf16 v[124:127], v[146:149], v[178:181], v[124:127]
	v_mfma_f32_16x16x32_bf16 v[120:123], v[154:157], v[178:181], v[120:123]
	v_mfma_f32_16x16x32_bf16 v[108:111], v[146:149], v[186:189], v[108:111]
	v_mfma_f32_16x16x32_bf16 v[104:107], v[154:157], v[186:189], v[104:107]
	v_mfma_f32_16x16x32_bf16 v[92:95], v[146:149], v[194:197], v[92:95]
	v_mfma_f32_16x16x32_bf16 v[88:91], v[154:157], v[194:197], v[88:91]
	v_mfma_f32_16x16x32_bf16 v[76:79], v[146:149], v[210:213], v[76:79]
	v_mfma_f32_16x16x32_bf16 v[72:75], v[154:157], v[210:213], v[72:75]
	v_mfma_f32_16x16x32_bf16 v[124:127], v[150:153], v[182:185], v[124:127]
	v_mfma_f32_16x16x32_bf16 v[120:123], v[158:161], v[182:185], v[120:123]
	v_mfma_f32_16x16x32_bf16 v[108:111], v[150:153], v[190:193], v[108:111]
	v_mfma_f32_16x16x32_bf16 v[104:107], v[158:161], v[190:193], v[104:107]
	v_mfma_f32_16x16x32_bf16 v[92:95], v[150:153], v[198:201], v[92:95]
	v_mfma_f32_16x16x32_bf16 v[88:91], v[158:161], v[198:201], v[88:91]
	v_mfma_f32_16x16x32_bf16 v[76:79], v[150:153], v[214:217], v[76:79]
	v_mfma_f32_16x16x32_bf16 v[72:75], v[158:161], v[214:217], v[72:75]
	v_mfma_f32_16x16x32_bf16 v[116:119], v[162:165], v[178:181], v[116:119]
	v_mfma_f32_16x16x32_bf16 v[112:115], v[170:173], v[178:181], v[112:115]
	v_mfma_f32_16x16x32_bf16 v[100:103], v[162:165], v[186:189], v[100:103]
	v_mfma_f32_16x16x32_bf16 v[96:99], v[170:173], v[186:189], v[96:99]
	v_mfma_f32_16x16x32_bf16 v[84:87], v[162:165], v[194:197], v[84:87]
	v_mfma_f32_16x16x32_bf16 v[80:83], v[170:173], v[194:197], v[80:83]
	v_mfma_f32_16x16x32_bf16 v[68:71], v[162:165], v[210:213], v[68:71]
	v_mfma_f32_16x16x32_bf16 v[64:67], v[170:173], v[210:213], v[64:67]
	v_mfma_f32_16x16x32_bf16 v[116:119], v[166:169], v[182:185], v[116:119]
	v_mfma_f32_16x16x32_bf16 v[112:115], v[174:177], v[182:185], v[112:115]
	v_mfma_f32_16x16x32_bf16 v[100:103], v[166:169], v[190:193], v[100:103]
	v_mfma_f32_16x16x32_bf16 v[96:99], v[174:177], v[190:193], v[96:99]
	v_mfma_f32_16x16x32_bf16 v[84:87], v[166:169], v[198:201], v[84:87]
	v_mfma_f32_16x16x32_bf16 v[80:83], v[174:177], v[198:201], v[80:83]
	v_mfma_f32_16x16x32_bf16 v[68:71], v[166:169], v[214:217], v[68:71]
	v_mfma_f32_16x16x32_bf16 v[64:67], v[174:177], v[214:217], v[64:67]
	s_barrier
; #define PG8_STAGE(bufoff, gbase, voff) do { _Pragma("unroll") for (int _i = 0; _i < 2; ++_i) \
;         __builtin_amdgcn_global_load_lds((const unsigned*)((const char*)(gbase) + (voff)[_i]), (PG8_LAS unsigned*)(lds + (bufoff) + ldsw + _i * 8192), 16, 0, 0); } while (0)
; #define PG8_LDA(dst, b, h) do { _Pragma("unroll") for (int m = 0; m < 4; ++m) _Pragma("unroll") for (int k = 0; k < 2; ++k) dst[m][k] = *(const PG8_LAS bf16x8*)(lds + PG8_SA(b, h) + aoff + m * 2048 + k * 1024); } while (0)
; #define PG8_MMA(ai, bj, At, Bt) do { __builtin_amdgcn_s_setprio(1); _Pragma("unroll") for (int m = 0; m < 4; ++m) _Pragma("unroll") for (int n = 0; n < 2; ++n) _Pragma("unroll") for (int k = 0; k < 2; ++k) \
;         acc[ai][bj][m][n] = __builtin_amdgcn_mfma_f32_16x16x32_bf16(Bt[n][k], At[m][k], acc[ai][bj][m][n], 0, 0, 0); __builtin_amdgcn_s_setprio(0); } while (0)
; #define PG8_WAIT_V(n) asm volatile("s_waitcnt vmcnt(" #n ")" ::: "memory")
; #define PG8_WAIT_L(n) asm volatile("s_waitcnt lgkmcnt(" #n ")" ::: "memory")
; #define PG8_BAR __builtin_amdgcn_s_barrier()
; #define PG8_SCHED __builtin_amdgcn_sched_barrier(0)
; template <class Epi, class Sched, bool ALIGN_EPI = false, bool SP2 = false>
; __device__ __forceinline__ void gemm_phase(PG8_LAS unsigned char* lds, const Gemm g, const Sched& S, const Epi& E, const int wv0) {
;     ...
;         for (int t = 0; t < nt; t += 2) {
;             const bool last = (t == nt - 2);
;             const char* a1 = cA + (size_t)(t + 1) * kstep;
;             const char* a2 = last ? nA : cA + (size_t)(t + 2) * kstep; const char* b2 = last ? nB : cB + (size_t)(t + 2) * kstep;
;     ...
;             PG8_LDA(At, 1, 1); PG8_STAGE(PG8_SB(1, 0), b3, voffB); PG8_STAGE(PG8_SB(1, 1), b3 + hstepB, voffB); PG8_STAGE(PG8_SA(1, 0), a3, voffA);
;             PG8_WAIT_V(8); PG8_WAIT_L(0); PG8_BAR; PG8_MMA(1, 0, At, B0); PG8_MMA(1, 1, At, B1); PG8_BAR; PG8_SCHED;
	s_add_i32 s41, s41, s54
	v_lshl_add_u64 v[202:203], v[202:203], 0, s[10:11]
	s_mov_b32 m0, s41
	ds_read_b128 v[178:181], v209 offset:49152
	ds_read_b128 v[182:185], v209 offset:50176
	ds_read_b128 v[186:189], v209 offset:51200
	ds_read_b128 v[190:193], v209 offset:52224
	ds_read_b128 v[194:197], v209 offset:53248
	ds_read_b128 v[198:201], v209 offset:54272
	ds_read_b128 v[210:213], v209 offset:55296
	ds_read_b128 v[214:217], v209 offset:56320
	global_load_lds_dwordx4 v[202:203], off
	s_add_i32 m0, s41, 0x2000
	s_add_u32 s44, s44, 0x40080
	v_lshl_add_u64 v[202:203], v[218:219], 0, s[10:11]
	s_addc_u32 s45, s45, 0
	s_add_i32 s41, s64, s54
	global_load_lds_dwordx4 v[202:203], off
	v_lshl_add_u64 v[202:203], s[44:45], 0, v[130:131]
	s_mov_b32 m0, s41
	s_nop 0
	global_load_lds_dwordx4 v[202:203], off
	v_lshl_add_u64 v[202:203], s[44:45], 0, v[134:135]
	s_add_i32 m0, s41, 0x2000
	s_nop 0
	global_load_lds_dwordx4 v[202:203], off
	v_lshl_add_u64 v[202:203], v[220:221], 0, s[10:11]
	s_mov_b32 m0, s59
	s_nop 0
	global_load_lds_dwordx4 v[202:203], off
	v_lshl_add_u64 v[202:203], v[222:223], 0, s[10:11]
	s_mov_b32 m0, s60
	s_nop 0
	global_load_lds_dwordx4 v[202:203], off
	s_waitcnt vmcnt(8)
	s_waitcnt lgkmcnt(0)
	s_barrier
	v_mfma_f32_16x16x32_bf16 v[60:63], v[146:149], v[178:181], v[60:63]
	v_mfma_f32_16x16x32_bf16 v[56:59], v[154:157], v[178:181], v[56:59]
	v_mfma_f32_16x16x32_bf16 v[44:47], v[146:149], v[186:189], v[44:47]
	v_mfma_f32_16x16x32_bf16 v[40:43], v[154:157], v[186:189], v[40:43]
	v_mfma_f32_16x16x32_bf16 v[28:31], v[146:149], v[194:197], v[28:31]
	v_mfma_f32_16x16x32_bf16 v[24:27], v[154:157], v[194:197], v[24:27]
	v_mfma_f32_16x16x32_bf16 v[12:15], v[146:149], v[210:213], v[12:15]
	v_mfma_f32_16x16x32_bf16 v[8:11], v[154:157], v[210:213], v[8:11]
	v_mfma_f32_16x16x32_bf16 v[60:63], v[150:153], v[182:185], v[60:63]
	v_mfma_f32_16x16x32_bf16 v[56:59], v[158:161], v[182:185], v[56:59]
	v_mfma_f32_16x16x32_bf16 v[44:47], v[150:153], v[190:193], v[44:47]
	v_mfma_f32_16x16x32_bf16 v[40:43], v[158:161], v[190:193], v[40:43]
	v_mfma_f32_16x16x32_bf16 v[28:31], v[150:153], v[198:201], v[28:31]
	v_mfma_f32_16x16x32_bf16 v[24:27], v[158:161], v[198:201], v[24:27]
	v_mfma_f32_16x16x32_bf16 v[12:15], v[150:153], v[214:217], v[12:15]
	v_mfma_f32_16x16x32_bf16 v[8:11], v[158:161], v[214:217], v[8:11]
	v_mfma_f32_16x16x32_bf16 v[52:55], v[162:165], v[178:181], v[52:55]
	v_mfma_f32_16x16x32_bf16 v[48:51], v[170:173], v[178:181], v[48:51]
	v_mfma_f32_16x16x32_bf16 v[36:39], v[162:165], v[186:189], v[36:39]
	v_mfma_f32_16x16x32_bf16 v[32:35], v[170:173], v[186:189], v[32:35]
	v_mfma_f32_16x16x32_bf16 v[20:23], v[162:165], v[194:197], v[20:23]
	v_mfma_f32_16x16x32_bf16 v[16:19], v[170:173], v[194:197], v[16:19]
	v_mfma_f32_16x16x32_bf16 v[4:7], v[162:165], v[210:213], v[4:7]
	v_mfma_f32_16x16x32_bf16 v[0:3], v[170:173], v[210:213], v[0:3]
	v_mfma_f32_16x16x32_bf16 v[52:55], v[166:169], v[182:185], v[52:55]
	v_mfma_f32_16x16x32_bf16 v[48:51], v[174:177], v[182:185], v[48:51]
	v_mfma_f32_16x16x32_bf16 v[36:39], v[166:169], v[190:193], v[36:39]
	v_mfma_f32_16x16x32_bf16 v[32:35], v[174:177], v[190:193], v[32:35]
	v_mfma_f32_16x16x32_bf16 v[20:23], v[166:169], v[198:201], v[20:23]
	v_mfma_f32_16x16x32_bf16 v[16:19], v[174:177], v[198:201], v[16:19]
	v_mfma_f32_16x16x32_bf16 v[4:7], v[166:169], v[214:217], v[4:7]
	v_mfma_f32_16x16x32_bf16 v[0:3], v[174:177], v[214:217], v[0:3]
	s_barrier
	s_add_i32 s29, s29, 2
	s_add_u32 s25, s25, 0x100
	s_addc_u32 s27, s27, 0
	s_add_u32 s38, s38, 0x100
	s_addc_u32 s39, s39, 0
	s_cmp_gt_u32 s29, 13
	s_cbranch_scc0 .LBB0_494
	s_and_b64 vcc, exec, s[12:13]
	s_cbranch_vccz .LBB0_497
	s_barrier

; #define TID() (wv0 * 64 + (int)__builtin_amdgcn_mbcnt_hi(~0u, __builtin_amdgcn_mbcnt_lo(~0u, 0u)))
; __device__ __forceinline__ int opaque(int x) { asm volatile("" : "+v"(x)); return x; }
; #define PG8_WAIT_V(n) asm volatile("s_waitcnt vmcnt(" #n ")" ::: "memory")
; #define PG8_BAR __builtin_amdgcn_s_barrier()
; template <class Epi, class Sched, bool ALIGN_EPI = false, bool SP2 = false>
; __device__ __forceinline__ void gemm_phase(PG8_LAS unsigned char* lds, const Gemm g, const Sched& S, const Epi& E, const int wv0) {
;     ...
;     PG8_WAIT_V(0);
;     if constexpr (!ALIGN_EPI) { if (wr == 0) PG8_BAR; }
;     PG8_BAR;
; __device__ __forceinline__ void xcd_barrier(const XcdBarrier& b, const int wv0) {
;     const bool TID0 = (opaque(TID()) == 0);
;     asm volatile("s_waitcnt vmcnt(0)" ::: "memory");
;     __syncthreads();
;     if (TID0) {
;         unsigned* bar = b.bar;
;         __builtin_amdgcn_s_waitcnt(0);
;         unsigned nloc = b.st[0], nx = b.st[1];
;         if (nloc == 0u) { xcd_barrier_complete(bar, b.x, nloc, nx); b.st[0] = nloc; b.st[1] = nx; }
.LBB0_597:
	s_barrier
	s_setprio 0
	v_mov_b32 v0, s77
	ds_read_b64 v[0:1], v0 offset:168
	s_getreg_b32 s4, hwreg(HW_REG_XCC_ID, 0, 4)
	s_waitcnt lgkmcnt(0)
	v_readfirstlane_b32 s2, v0
	v_mov_b32_e32 v0, v204
	v_readfirstlane_b32 s3, v1
	v_mov_b32 v1, s78
	s_waitcnt vmcnt(0)
	s_nop 0
	v_cmp_eq_u32_e32 vcc, 0, v0
	s_barrier
	s_and_saveexec_b64 s[0:1], vcc
	s_xor_b64 s[0:1], exec, s[0:1]
	s_cbranch_execz .LBB0_650
	s_waitcnt vmcnt(0) expcnt(0) lgkmcnt(0)
	ds_read_b32 v2, v1
	ds_read_b32 v0, v1 offset:4
	s_and_b32 s40, s4, 15
	s_waitcnt lgkmcnt(1)
	v_cmp_eq_u32_e32 vcc, 0, v2
	s_and_saveexec_b64 s[4:5], vcc
	s_cbranch_execz .LBB0_613
	s_add_u32 s6, s2, 0x2e400200
	s_addc_u32 s7, s3, 0
	s_add_u32 s8, s2, 0x2e400400
	s_addc_u32 s9, s3, 0
	s_add_u32 s10, s2, 0x2e400500
	s_addc_u32 s11, s3, 0
	s_add_u32 s12, s2, 0x2e400600
	s_addc_u32 s13, s3, 0
	s_add_u32 s14, s2, 0x2e400700
	s_addc_u32 s15, s3, 0
	s_add_u32 s16, s2, 0x2e400800
	s_addc_u32 s17, s3, 0
	s_add_u32 s18, s2, 0x2e400900
	s_addc_u32 s19, s3, 0
	s_add_u32 s20, s2, 0x2e400a00
	s_addc_u32 s21, s3, 0
	s_add_u32 s22, s2, 0x2e400b00
	s_addc_u32 s23, s3, 0
	s_add_u32 s24, s2, 0x2e400c00
	s_addc_u32 s25, s3, 0
	s_add_u32 s26, s2, 0x2e400d00
	s_addc_u32 s27, s3, 0
	s_add_u32 s28, s2, 0x2e400e00
	s_addc_u32 s29, s3, 0
	s_add_u32 s30, s2, 0x2e400f00
	s_addc_u32 s31, s3, 0
	s_add_u32 s34, s2, 0x2e401000
	s_addc_u32 s35, s3, 0
	s_add_u32 s36, s2, 0x2e401100
	s_addc_u32 s37, s3, 0
	s_add_u32 s38, s2, 0x2e401200
	s_addc_u32 s39, s3, 0
	s_mul_i32 s41, s43, s76
	s_add_u32 s44, s2, 0x2e401300
	s_mul_i32 s41, s41, s42
	s_addc_u32 s45, s3, 0
	s_mov_b32 s52, 1
	v_mov_b32_e32 v17, 0
	s_branch .LBB0_601

;     __device__ __forceinline__ const float* in(int k) const { return (const float*)(const __attribute__((address_space(1))) float*)get(k); }
;     __device__ __forceinline__ unsigned char* ws() const { return (unsigned char*)(__attribute__((address_space(1))) unsigned char*)get(21); }
;     __device__ __forceinline__ bool get(long L, int& pm, int& pn) const {
;         if (L >= nwg) return false;
;         int wgid = (int)L; { const int q = nwg / NXCD, r = nwg % NXCD, xcd = wgid % NXCD, off = wgid / NXCD; wgid = (xcd < r ? xcd * (q + 1) : r * (q + 1) + (xcd - r) * q) + off; }
;         const int nig = WGM * nN, gid = wgid / nig, fm = gid * WGM, gsz = (nM - fm) < WGM ? (nM - fm) : WGM;
;         pm = fm + ((wgid % nig) % gsz); pn = (wgid % nig) / gsz; return true;
;     }
; template <int l>
; __device__ __forceinline__ void layer_body(const Ptrs& A, LAS unsigned char* lds, unsigned char* lds_raw, const int wv0) {
;     ...
;             pg8::Gemm g{DM, DM, DM}; pg8::SchedGrid S; S.to.init(T / 256, DM / 256); S.G = G; S.c = c; S.A = (const char*)(ws + WS_GV); S.B = (const char*)(ws + WS_WO); S.ta = (size_t)256 * DM * 2; S.tb = (size_t)256 * DM * 2;
;             if constexpr (l == 0) { pg8::EpiRes<false, true> E{(const void*)A.in(0), (void*)(ws + WS_X)}; pg8::gemm_phase<pg8::EpiRes<false, true>, pg8::SchedGrid, true, true>(lds, g, S, E, wv0); }
.Lprio_skip_7:
	v_mov_b32 v0, s77
	ds_read_b64 v[0:1], v0 offset:168
	s_mov_b32 s28, s76
	s_mov_b32 s29, s33
	v_mov_b32_e32 v8, v204
	s_waitcnt lgkmcnt(0)
	v_readfirstlane_b32 s1, v1
	v_readfirstlane_b32 s0, v0
	v_mov_b32_e32 v0, v204
	s_cmpk_gt_i32 s29, 0x1ff
	v_mov_b32 v0, s77
	ds_read_b64 v[0:1], v0
	s_waitcnt lgkmcnt(0)
	v_readfirstlane_b32 s3, v1
	v_readfirstlane_b32 s2, v0
	v_readfirstlane_b32 s11, v8
	s_cbranch_scc1 .LBB0_674
	s_ashr_i32 s30, s29, 31
	s_lshr_b32 s4, s30, 29
	s_add_i32 s8, s29, s4
	s_and_b32 s4, s8, -8
	s_sub_i32 s7, s29, s4
	s_cmp_gt_i32 s7, -1
	s_cbranch_scc0 .LBB0_653
	s_lshl_b32 s6, s7, 6
	s_ashr_i32 s4, s8, 3
	s_cbranch_execz .LBB0_654
	s_branch .LBB0_655

; #define PG8_STAGE(bufoff, gbase, voff) do { _Pragma("unroll") for (int _i = 0; _i < 2; ++_i) \
;         __builtin_amdgcn_global_load_lds((const unsigned*)((const char*)(gbase) + (voff)[_i]), (PG8_LAS unsigned*)(lds + (bufoff) + ldsw + _i * 8192), 16, 0, 0); } while (0)
; #define PG8_LDA(dst, b, h) do { _Pragma("unroll") for (int m = 0; m < 4; ++m) _Pragma("unroll") for (int k = 0; k < 2; ++k) dst[m][k] = *(const PG8_LAS bf16x8*)(lds + PG8_SA(b, h) + aoff + m * 2048 + k * 1024); } while (0)
; #define PG8_LDB(dst, b, h) do { _Pragma("unroll") for (int n = 0; n < 2; ++n) _Pragma("unroll") for (int k = 0; k < 2; ++k) dst[n][k] = *(const PG8_LAS bf16x8*)(lds + PG8_SB(b, h) + boff + n * 2048 + k * 1024); } while (0)
; #define PG8_MMA(ai, bj, At, Bt) do { __builtin_amdgcn_s_setprio(1); _Pragma("unroll") for (int m = 0; m < 4; ++m) _Pragma("unroll") for (int n = 0; n < 2; ++n) _Pragma("unroll") for (int k = 0; k < 2; ++k) \
;         acc[ai][bj][m][n] = __builtin_amdgcn_mfma_f32_16x16x32_bf16(Bt[n][k], At[m][k], acc[ai][bj][m][n], 0, 0, 0); __builtin_amdgcn_s_setprio(0); } while (0)
; #define PG8_WAIT_V(n) asm volatile("s_waitcnt vmcnt(" #n ")" ::: "memory")
; #define PG8_WAIT_L(n) asm volatile("s_waitcnt lgkmcnt(" #n ")" ::: "memory")
; #define PG8_BAR __builtin_amdgcn_s_barrier()
; #define PG8_SCHED __builtin_amdgcn_sched_barrier(0)
; template <class Epi, class Sched, bool ALIGN_EPI = false, bool SP2 = false>
; __device__ __forceinline__ void gemm_phase(PG8_LAS unsigned char* lds, const Gemm g, const Sched& S, const Epi& E, const int wv0) {
;     ...
;             PG8_LDB(B0, 0, 0); PG8_LDB(B1, 0, 1); PG8_SCHED; PG8_LDA(At, 0, 0); PG8_STAGE(PG8_SA(1, 1), a1 + hstepA, voffA);
;             PG8_WAIT_V(8); PG8_WAIT_L(0); PG8_BAR; PG8_MMA(0, 0, At, B0); PG8_MMA(0, 1, At, B1); PG8_BAR; PG8_SCHED;
.LBB0_667:
	ds_read_b128 v[144:147], v153
	ds_read_b128 v[156:159], v153 offset:1024
	ds_read_b128 v[160:163], v153 offset:2048
	ds_read_b128 v[164:167], v153 offset:3072
	ds_read_b128 v[168:171], v154
	ds_read_b128 v[172:175], v154 offset:1024
	ds_read_b128 v[176:179], v154 offset:2048
	ds_read_b128 v[180:183], v154 offset:3072
	s_add_u32 s24, s22, 0xfff80080
	s_addc_u32 s25, s23, -1
	s_cmp_eq_u32 s50, 28
	s_cselect_b32 s27, s17, s25
	s_cselect_b32 s26, s16, s24
	s_cselect_b32 s25, s19, s15
	s_cselect_b32 s24, s18, s13
	v_lshl_add_u64 v[148:149], s[22:23], 0, v[138:139]
	s_add_i32 m0, s21, 0xc000
	ds_read_b128 v[184:187], v155
	ds_read_b128 v[188:191], v155 offset:1024
	ds_read_b128 v[192:195], v155 offset:2048
	ds_read_b128 v[196:199], v155 offset:3072
	ds_read_b128 v[200:203], v155 offset:4096
	ds_read_b128 v[206:209], v155 offset:5120
	ds_read_b128 v[210:213], v155 offset:6144
	ds_read_b128 v[214:217], v155 offset:7168
	global_load_lds_dwordx4 v[148:149], off
	v_lshl_add_u64 v[148:149], s[22:23], 0, v[136:137]
	s_add_i32 m0, s21, 0xe000
	s_nop 0
	global_load_lds_dwordx4 v[148:149], off
	s_waitcnt vmcnt(8)
	s_waitcnt lgkmcnt(0)
	s_barrier
	v_mfma_f32_16x16x32_bf16 v[124:127], v[144:147], v[184:187], v[124:127]
	v_mfma_f32_16x16x32_bf16 v[120:123], v[160:163], v[184:187], v[120:123]
	v_mfma_f32_16x16x32_bf16 v[116:119], v[144:147], v[192:195], v[116:119]
	v_mfma_f32_16x16x32_bf16 v[112:115], v[160:163], v[192:195], v[112:115]
	v_mfma_f32_16x16x32_bf16 v[92:95], v[144:147], v[200:203], v[92:95]
	v_mfma_f32_16x16x32_bf16 v[88:91], v[160:163], v[200:203], v[88:91]
	v_mfma_f32_16x16x32_bf16 v[84:87], v[144:147], v[210:213], v[84:87]
	v_mfma_f32_16x16x32_bf16 v[80:83], v[160:163], v[210:213], v[80:83]
	v_mfma_f32_16x16x32_bf16 v[124:127], v[156:159], v[188:191], v[124:127]
	v_mfma_f32_16x16x32_bf16 v[120:123], v[164:167], v[188:191], v[120:123]
	v_mfma_f32_16x16x32_bf16 v[116:119], v[156:159], v[196:199], v[116:119]
	v_mfma_f32_16x16x32_bf16 v[112:115], v[164:167], v[196:199], v[112:115]
	v_mfma_f32_16x16x32_bf16 v[92:95], v[156:159], v[206:209], v[92:95]
	v_mfma_f32_16x16x32_bf16 v[88:91], v[164:167], v[206:209], v[88:91]
	v_mfma_f32_16x16x32_bf16 v[84:87], v[156:159], v[214:217], v[84:87]
	v_mfma_f32_16x16x32_bf16 v[80:83], v[164:167], v[214:217], v[80:83]
	v_mfma_f32_16x16x32_bf16 v[108:111], v[168:171], v[184:187], v[108:111]
	v_mfma_f32_16x16x32_bf16 v[104:107], v[176:179], v[184:187], v[104:107]
	v_mfma_f32_16x16x32_bf16 v[100:103], v[168:171], v[192:195], v[100:103]
	v_mfma_f32_16x16x32_bf16 v[96:99], v[176:179], v[192:195], v[96:99]
	v_mfma_f32_16x16x32_bf16 v[76:79], v[168:171], v[200:203], v[76:79]
	v_mfma_f32_16x16x32_bf16 v[72:75], v[176:179], v[200:203], v[72:75]
	v_mfma_f32_16x16x32_bf16 v[68:71], v[168:171], v[210:213], v[68:71]
	v_mfma_f32_16x16x32_bf16 v[64:67], v[176:179], v[210:213], v[64:67]
	v_mfma_f32_16x16x32_bf16 v[108:111], v[172:175], v[188:191], v[108:111]
	v_mfma_f32_16x16x32_bf16 v[104:107], v[180:183], v[188:191], v[104:107]
	v_mfma_f32_16x16x32_bf16 v[100:103], v[172:175], v[196:199], v[100:103]
	v_mfma_f32_16x16x32_bf16 v[96:99], v[180:183], v[196:199], v[96:99]
	v_mfma_f32_16x16x32_bf16 v[76:79], v[172:175], v[206:209], v[76:79]
	v_mfma_f32_16x16x32_bf16 v[72:75], v[180:183], v[206:209], v[72:75]
	v_mfma_f32_16x16x32_bf16 v[68:71], v[172:175], v[214:217], v[68:71]
	v_mfma_f32_16x16x32_bf16 v[64:67], v[180:183], v[214:217], v[64:67]
	s_barrier
	s_add_i32 s51, s47, s37
	v_lshl_add_u64 v[148:149], s[24:25], 0, v[130:131]
	s_mov_b32 m0, s51
	ds_read_b128 v[184:187], v155 offset:16384
	ds_read_b128 v[188:191], v155 offset:17408
	ds_read_b128 v[192:195], v155 offset:18432
	ds_read_b128 v[196:199], v155 offset:19456
	ds_read_b128 v[200:203], v155 offset:20480
	ds_read_b128 v[206:209], v155 offset:21504
	ds_read_b128 v[210:213], v155 offset:22528
	ds_read_b128 v[214:217], v155 offset:23552
	global_load_lds_dwordx4 v[148:149], off
	s_add_i32 m0, s51, 0x2000
	s_add_u32 s52, s24, 0x80000
	v_lshl_add_u64 v[218:219], s[24:25], 0, v[134:135]
	s_addc_u32 s53, s25, 0
	s_add_i32 s51, s48, s37
	global_load_lds_dwordx4 v[218:219], off
	v_lshl_add_u64 v[220:221], s[52:53], 0, v[130:131]
	s_mov_b32 m0, s51
	v_lshl_add_u64 v[222:223], s[26:27], 0, v[132:133]
	global_load_lds_dwordx4 v[220:221], off
	v_lshl_add_u64 v[220:221], s[52:53], 0, v[134:135]
	s_add_i32 m0, s51, 0x2000
	s_nop 0
	global_load_lds_dwordx4 v[220:221], off
	v_lshl_add_u64 v[220:221], s[26:27], 0, v[128:129]
	s_mov_b32 m0, s21
	s_nop 0
	global_load_lds_dwordx4 v[220:221], off
	s_mov_b32 m0, s38
	s_nop 0
	global_load_lds_dwordx4 v[222:223], off
	s_waitcnt vmcnt(8)
	s_waitcnt lgkmcnt(0)
	s_barrier
; #define PG8_STAGE(bufoff, gbase, voff) do { _Pragma("unroll") for (int _i = 0; _i < 2; ++_i) \
;         __builtin_amdgcn_global_load_lds((const unsigned*)((const char*)(gbase) + (voff)[_i]), (PG8_LAS unsigned*)(lds + (bufoff) + ldsw + _i * 8192), 16, 0, 0); } while (0)
; #define PG8_LDA(dst, b, h) do { _Pragma("unroll") for (int m = 0; m < 4; ++m) _Pragma("unroll") for (int k = 0; k < 2; ++k) dst[m][k] = *(const PG8_LAS bf16x8*)(lds + PG8_SA(b, h) + aoff + m * 2048 + k * 1024); } while (0)
; #define PG8_LDB(dst, b, h) do { _Pragma("unroll") for (int n = 0; n < 2; ++n) _Pragma("unroll") for (int k = 0; k < 2; ++k) dst[n][k] = *(const PG8_LAS bf16x8*)(lds + PG8_SB(b, h) + boff + n * 2048 + k * 1024); } while (0)
; #define PG8_MMA(ai, bj, At, Bt) do { __builtin_amdgcn_s_setprio(1); _Pragma("unroll") for (int m = 0; m < 4; ++m) _Pragma("unroll") for (int n = 0; n < 2; ++n) _Pragma("unroll") for (int k = 0; k < 2; ++k) \
;         acc[ai][bj][m][n] = __builtin_amdgcn_mfma_f32_16x16x32_bf16(Bt[n][k], At[m][k], acc[ai][bj][m][n], 0, 0, 0); __builtin_amdgcn_s_setprio(0); } while (0)
; #define PG8_WAIT_V(n) asm volatile("s_waitcnt vmcnt(" #n ")" ::: "memory")
; #define PG8_WAIT_L(n) asm volatile("s_waitcnt lgkmcnt(" #n ")" ::: "memory")
; #define PG8_BAR __builtin_amdgcn_s_barrier()
; #define PG8_SCHED __builtin_amdgcn_sched_barrier(0)
; template <class Epi, class Sched, bool ALIGN_EPI = false, bool SP2 = false>
; __device__ __forceinline__ void gemm_phase(PG8_LAS unsigned char* lds, const Gemm g, const Sched& S, const Epi& E, const int wv0) {
;     ...
;             PG8_WAIT_V(8); PG8_WAIT_L(0); PG8_BAR; PG8_MMA(1, 0, At, B0); PG8_MMA(1, 1, At, B1); PG8_BAR; PG8_SCHED;
;             PG8_LDB(B0, 1, 0); PG8_LDB(B1, 1, 1); PG8_SCHED; PG8_LDA(At, 1, 0); PG8_STAGE(PG8_SA(0, 1), a2 + hstepA, voffA);
;             PG8_WAIT_V(8); PG8_WAIT_L(0); PG8_BAR; PG8_MMA(0, 0, At, B0); PG8_MMA(0, 1, At, B1); PG8_BAR; PG8_SCHED;
	v_mfma_f32_16x16x32_bf16 v[60:63], v[144:147], v[184:187], v[60:63]
	v_mfma_f32_16x16x32_bf16 v[56:59], v[160:163], v[184:187], v[56:59]
	v_mfma_f32_16x16x32_bf16 v[52:55], v[144:147], v[192:195], v[52:55]
	v_mfma_f32_16x16x32_bf16 v[48:51], v[160:163], v[192:195], v[48:51]
	v_mfma_f32_16x16x32_bf16 v[28:31], v[144:147], v[200:203], v[28:31]
	v_mfma_f32_16x16x32_bf16 v[24:27], v[160:163], v[200:203], v[24:27]
	v_mfma_f32_16x16x32_bf16 v[20:23], v[144:147], v[210:213], v[20:23]
	v_mfma_f32_16x16x32_bf16 v[16:19], v[160:163], v[210:213], v[16:19]
	v_mfma_f32_16x16x32_bf16 v[60:63], v[156:159], v[188:191], v[60:63]
	v_mfma_f32_16x16x32_bf16 v[56:59], v[164:167], v[188:191], v[56:59]
	v_mfma_f32_16x16x32_bf16 v[52:55], v[156:159], v[196:199], v[52:55]
	v_mfma_f32_16x16x32_bf16 v[48:51], v[164:167], v[196:199], v[48:51]
	v_mfma_f32_16x16x32_bf16 v[28:31], v[156:159], v[206:209], v[28:31]
	v_mfma_f32_16x16x32_bf16 v[24:27], v[164:167], v[206:209], v[24:27]
	v_mfma_f32_16x16x32_bf16 v[20:23], v[156:159], v[214:217], v[20:23]
	v_mfma_f32_16x16x32_bf16 v[16:19], v[164:167], v[214:217], v[16:19]
	v_mfma_f32_16x16x32_bf16 v[44:47], v[168:171], v[184:187], v[44:47]
	v_mfma_f32_16x16x32_bf16 v[40:43], v[176:179], v[184:187], v[40:43]
	v_mfma_f32_16x16x32_bf16 v[36:39], v[168:171], v[192:195], v[36:39]
	v_mfma_f32_16x16x32_bf16 v[32:35], v[176:179], v[192:195], v[32:35]
	v_mfma_f32_16x16x32_bf16 v[12:15], v[168:171], v[200:203], v[12:15]
	v_mfma_f32_16x16x32_bf16 v[8:11], v[176:179], v[200:203], v[8:11]
	v_mfma_f32_16x16x32_bf16 v[4:7], v[168:171], v[210:213], v[4:7]
	v_mfma_f32_16x16x32_bf16 v[0:3], v[176:179], v[210:213], v[0:3]
	v_mfma_f32_16x16x32_bf16 v[44:47], v[172:175], v[188:191], v[44:47]
	v_mfma_f32_16x16x32_bf16 v[40:43], v[180:183], v[188:191], v[40:43]
	v_mfma_f32_16x16x32_bf16 v[36:39], v[172:175], v[196:199], v[36:39]
	v_mfma_f32_16x16x32_bf16 v[32:35], v[180:183], v[196:199], v[32:35]
	v_mfma_f32_16x16x32_bf16 v[12:15], v[172:175], v[206:209], v[12:15]
	v_mfma_f32_16x16x32_bf16 v[8:11], v[180:183], v[206:209], v[8:11]
	v_mfma_f32_16x16x32_bf16 v[4:7], v[172:175], v[214:217], v[4:7]
	v_mfma_f32_16x16x32_bf16 v[0:3], v[180:183], v[214:217], v[0:3]
	s_barrier
	s_add_i32 s51, 0, 0x18000
	s_add_i32 s52, 0, 0x1c000
	v_add_u32_e32 v164, s51, v151
	v_add_u32_e32 v180, s52, v151
	ds_read_b128 v[144:147], v164
	ds_read_b128 v[156:159], v164 offset:1024
	ds_read_b128 v[160:163], v164 offset:2048
	ds_read_b128 v[164:167], v164 offset:3072
	ds_read_b128 v[168:171], v180
	ds_read_b128 v[172:175], v180 offset:1024
	ds_read_b128 v[176:179], v180 offset:2048
	ds_read_b128 v[180:183], v180 offset:3072
	s_add_u32 s26, s26, 0x80000
	s_addc_u32 s27, s27, 0
	s_mov_b32 m0, s39
	v_lshl_add_u64 v[224:225], s[26:27], 0, v[128:129]
	ds_read_b128 v[184:187], v155 offset:32768
	ds_read_b128 v[188:191], v155 offset:33792
	ds_read_b128 v[192:195], v155 offset:34816
	ds_read_b128 v[196:199], v155 offset:35840
	ds_read_b128 v[200:203], v155 offset:36864
	ds_read_b128 v[206:209], v155 offset:37888
	ds_read_b128 v[210:213], v155 offset:38912
	ds_read_b128 v[214:217], v155 offset:39936
	global_load_lds_dwordx4 v[224:225], off
	v_lshl_add_u64 v[224:225], s[26:27], 0, v[132:133]
	s_mov_b32 m0, s40
	s_nop 0
	global_load_lds_dwordx4 v[224:225], off
	s_waitcnt vmcnt(8)
	s_waitcnt lgkmcnt(0)
	s_barrier
	v_mfma_f32_16x16x32_bf16 v[124:127], v[144:147], v[184:187], v[124:127]
	v_mfma_f32_16x16x32_bf16 v[120:123], v[160:163], v[184:187], v[120:123]
	v_mfma_f32_16x16x32_bf16 v[116:119], v[144:147], v[192:195], v[116:119]
	v_mfma_f32_16x16x32_bf16 v[112:115], v[160:163], v[192:195], v[112:115]
	v_mfma_f32_16x16x32_bf16 v[92:95], v[144:147], v[200:203], v[92:95]
	v_mfma_f32_16x16x32_bf16 v[88:91], v[160:163], v[200:203], v[88:91]
	v_mfma_f32_16x16x32_bf16 v[84:87], v[144:147], v[210:213], v[84:87]
	v_mfma_f32_16x16x32_bf16 v[80:83], v[160:163], v[210:213], v[80:83]
	v_mfma_f32_16x16x32_bf16 v[124:127], v[156:159], v[188:191], v[124:127]
	v_mfma_f32_16x16x32_bf16 v[120:123], v[164:167], v[188:191], v[120:123]
	v_mfma_f32_16x16x32_bf16 v[116:119], v[156:159], v[196:199], v[116:119]
	v_mfma_f32_16x16x32_bf16 v[112:115], v[164:167], v[196:199], v[112:115]
	v_mfma_f32_16x16x32_bf16 v[92:95], v[156:159], v[206:209], v[92:95]
	v_mfma_f32_16x16x32_bf16 v[88:91], v[164:167], v[206:209], v[88:91]
	v_mfma_f32_16x16x32_bf16 v[84:87], v[156:159], v[214:217], v[84:87]
	v_mfma_f32_16x16x32_bf16 v[80:83], v[164:167], v[214:217], v[80:83]
	v_mfma_f32_16x16x32_bf16 v[108:111], v[168:171], v[184:187], v[108:111]
	v_mfma_f32_16x16x32_bf16 v[104:107], v[176:179], v[184:187], v[104:107]
	v_mfma_f32_16x16x32_bf16 v[100:103], v[168:171], v[192:195], v[100:103]
	v_mfma_f32_16x16x32_bf16 v[96:99], v[176:179], v[192:195], v[96:99]
	v_mfma_f32_16x16x32_bf16 v[76:79], v[168:171], v[200:203], v[76:79]
	v_mfma_f32_16x16x32_bf16 v[72:75], v[176:179], v[200:203], v[72:75]
	v_mfma_f32_16x16x32_bf16 v[68:71], v[168:171], v[210:213], v[68:71]
	v_mfma_f32_16x16x32_bf16 v[64:67], v[176:179], v[210:213], v[64:67]
	v_mfma_f32_16x16x32_bf16 v[108:111], v[172:175], v[188:191], v[108:111]
	v_mfma_f32_16x16x32_bf16 v[104:107], v[180:183], v[188:191], v[104:107]
	v_mfma_f32_16x16x32_bf16 v[100:103], v[172:175], v[196:199], v[100:103]
	v_mfma_f32_16x16x32_bf16 v[96:99], v[180:183], v[196:199], v[96:99]
	v_mfma_f32_16x16x32_bf16 v[76:79], v[172:175], v[206:209], v[76:79]
	v_mfma_f32_16x16x32_bf16 v[72:75], v[180:183], v[206:209], v[72:75]
	v_mfma_f32_16x16x32_bf16 v[68:71], v[172:175], v[214:217], v[68:71]
	v_mfma_f32_16x16x32_bf16 v[64:67], v[180:183], v[214:217], v[64:67]
	s_barrier
; #define PG8_STAGE(bufoff, gbase, voff) do { _Pragma("unroll") for (int _i = 0; _i < 2; ++_i) \
;         __builtin_amdgcn_global_load_lds((const unsigned*)((const char*)(gbase) + (voff)[_i]), (PG8_LAS unsigned*)(lds + (bufoff) + ldsw + _i * 8192), 16, 0, 0); } while (0)
; #define PG8_LDA(dst, b, h) do { _Pragma("unroll") for (int m = 0; m < 4; ++m) _Pragma("unroll") for (int k = 0; k < 2; ++k) dst[m][k] = *(const PG8_LAS bf16x8*)(lds + PG8_SA(b, h) + aoff + m * 2048 + k * 1024); } while (0)
; #define PG8_MMA(ai, bj, At, Bt) do { __builtin_amdgcn_s_setprio(1); _Pragma("unroll") for (int m = 0; m < 4; ++m) _Pragma("unroll") for (int n = 0; n < 2; ++n) _Pragma("unroll") for (int k = 0; k < 2; ++k) \
;         acc[ai][bj][m][n] = __builtin_amdgcn_mfma_f32_16x16x32_bf16(Bt[n][k], At[m][k], acc[ai][bj][m][n], 0, 0, 0); __builtin_amdgcn_s_setprio(0); } while (0)
; #define PG8_WAIT_V(n) asm volatile("s_waitcnt vmcnt(" #n ")" ::: "memory")
; #define PG8_WAIT_L(n) asm volatile("s_waitcnt lgkmcnt(" #n ")" ::: "memory")
; #define PG8_BAR __builtin_amdgcn_s_barrier()
; #define PG8_SCHED __builtin_amdgcn_sched_barrier(0)
; template <class Epi, class Sched, bool ALIGN_EPI = false, bool SP2 = false>
; __device__ __forceinline__ void gemm_phase(PG8_LAS unsigned char* lds, const Gemm g, const Sched& S, const Epi& E, const int wv0) {
;     ...
;         for (int t = 0; t < nt; t += 2) {
;             const bool last = (t == nt - 2);
;             const char* a1 = cA + (size_t)(t + 1) * kstep;
;             const char* a2 = last ? nA : cA + (size_t)(t + 2) * kstep; const char* b2 = last ? nB : cB + (size_t)(t + 2) * kstep;
;     ...
;             PG8_LDA(At, 1, 1); PG8_STAGE(PG8_SB(1, 0), b3, voffB); PG8_STAGE(PG8_SB(1, 1), b3 + hstepB, voffB); PG8_STAGE(PG8_SA(1, 0), a3, voffA);
;             PG8_WAIT_V(8); PG8_WAIT_L(0); PG8_BAR; PG8_MMA(1, 0, At, B0); PG8_MMA(1, 1, At, B1); PG8_BAR; PG8_SCHED;
	s_add_i32 s26, s51, s37
	v_lshl_add_u64 v[148:149], v[148:149], 0, s[8:9]
	s_mov_b32 m0, s26
	ds_read_b128 v[184:187], v155 offset:49152
	ds_read_b128 v[188:191], v155 offset:50176
	ds_read_b128 v[192:195], v155 offset:51200
	ds_read_b128 v[196:199], v155 offset:52224
	ds_read_b128 v[200:203], v155 offset:53248
	ds_read_b128 v[206:209], v155 offset:54272
	ds_read_b128 v[210:213], v155 offset:55296
	ds_read_b128 v[214:217], v155 offset:56320
	global_load_lds_dwordx4 v[148:149], off
	s_add_i32 m0, s26, 0x2000
	s_add_u32 s24, s24, 0x80080
	v_lshl_add_u64 v[148:149], v[218:219], 0, s[8:9]
	s_addc_u32 s25, s25, 0
	s_add_i32 s26, s52, s37
	global_load_lds_dwordx4 v[148:149], off
	v_lshl_add_u64 v[148:149], s[24:25], 0, v[130:131]
	s_mov_b32 m0, s26
	s_nop 0
	global_load_lds_dwordx4 v[148:149], off
	v_lshl_add_u64 v[148:149], s[24:25], 0, v[134:135]
	s_add_i32 m0, s26, 0x2000
	s_nop 0
	global_load_lds_dwordx4 v[148:149], off
	v_lshl_add_u64 v[148:149], v[220:221], 0, s[8:9]
	s_mov_b32 m0, s44
	s_nop 0
	global_load_lds_dwordx4 v[148:149], off
	v_lshl_add_u64 v[148:149], v[222:223], 0, s[8:9]
	s_mov_b32 m0, s45
	s_nop 0
	global_load_lds_dwordx4 v[148:149], off
	s_waitcnt vmcnt(8)
	s_waitcnt lgkmcnt(0)
	s_barrier
	v_mfma_f32_16x16x32_bf16 v[60:63], v[144:147], v[184:187], v[60:63]
	v_mfma_f32_16x16x32_bf16 v[56:59], v[160:163], v[184:187], v[56:59]
	v_mfma_f32_16x16x32_bf16 v[52:55], v[144:147], v[192:195], v[52:55]
	v_mfma_f32_16x16x32_bf16 v[48:51], v[160:163], v[192:195], v[48:51]
	v_mfma_f32_16x16x32_bf16 v[28:31], v[144:147], v[200:203], v[28:31]
	v_mfma_f32_16x16x32_bf16 v[24:27], v[160:163], v[200:203], v[24:27]
	v_mfma_f32_16x16x32_bf16 v[20:23], v[144:147], v[210:213], v[20:23]
	v_mfma_f32_16x16x32_bf16 v[16:19], v[160:163], v[210:213], v[16:19]
	v_mfma_f32_16x16x32_bf16 v[60:63], v[156:159], v[188:191], v[60:63]
	v_mfma_f32_16x16x32_bf16 v[56:59], v[164:167], v[188:191], v[56:59]
	v_mfma_f32_16x16x32_bf16 v[52:55], v[156:159], v[196:199], v[52:55]
	v_mfma_f32_16x16x32_bf16 v[48:51], v[164:167], v[196:199], v[48:51]
	v_mfma_f32_16x16x32_bf16 v[28:31], v[156:159], v[206:209], v[28:31]
	v_mfma_f32_16x16x32_bf16 v[24:27], v[164:167], v[206:209], v[24:27]
	v_mfma_f32_16x16x32_bf16 v[20:23], v[156:159], v[214:217], v[20:23]
	v_mfma_f32_16x16x32_bf16 v[16:19], v[164:167], v[214:217], v[16:19]
	v_mfma_f32_16x16x32_bf16 v[44:47], v[168:171], v[184:187], v[44:47]
	v_mfma_f32_16x16x32_bf16 v[40:43], v[176:179], v[184:187], v[40:43]
	v_mfma_f32_16x16x32_bf16 v[36:39], v[168:171], v[192:195], v[36:39]
	v_mfma_f32_16x16x32_bf16 v[32:35], v[176:179], v[192:195], v[32:35]
	v_mfma_f32_16x16x32_bf16 v[12:15], v[168:171], v[200:203], v[12:15]
	v_mfma_f32_16x16x32_bf16 v[8:11], v[176:179], v[200:203], v[8:11]
	v_mfma_f32_16x16x32_bf16 v[4:7], v[168:171], v[210:213], v[4:7]
	v_mfma_f32_16x16x32_bf16 v[0:3], v[176:179], v[210:213], v[0:3]
	v_mfma_f32_16x16x32_bf16 v[44:47], v[172:175], v[188:191], v[44:47]
	v_mfma_f32_16x16x32_bf16 v[40:43], v[180:183], v[188:191], v[40:43]
	v_mfma_f32_16x16x32_bf16 v[36:39], v[172:175], v[196:199], v[36:39]
	v_mfma_f32_16x16x32_bf16 v[32:35], v[180:183], v[196:199], v[32:35]
	v_mfma_f32_16x16x32_bf16 v[12:15], v[172:175], v[206:209], v[12:15]
	v_mfma_f32_16x16x32_bf16 v[8:11], v[180:183], v[206:209], v[8:11]
	v_mfma_f32_16x16x32_bf16 v[4:7], v[172:175], v[214:217], v[4:7]
	v_mfma_f32_16x16x32_bf16 v[0:3], v[180:183], v[214:217], v[0:3]
	s_barrier
	s_add_i32 s50, s50, 2
	s_add_u32 s13, s13, 0x100
	s_addc_u32 s15, s15, 0
	s_add_u32 s22, s22, 0x100
	s_addc_u32 s23, s23, 0
	s_cmp_gt_u32 s50, 29
	s_cbranch_scc0 .LBB0_667
	s_and_b64 vcc, exec, s[10:11]
	s_cbranch_vccz .LBB0_670
	s_barrier

; #define TID() (wv0 * 64 + (int)__builtin_amdgcn_mbcnt_hi(~0u, __builtin_amdgcn_mbcnt_lo(~0u, 0u)))
; __device__ __forceinline__ int opaque(int x) { asm volatile("" : "+v"(x)); return x; }
; #define PG8_WAIT_V(n) asm volatile("s_waitcnt vmcnt(" #n ")" ::: "memory")
; #define PG8_BAR __builtin_amdgcn_s_barrier()
; template <class Epi, class Sched, bool ALIGN_EPI = false, bool SP2 = false>
; __device__ __forceinline__ void gemm_phase(PG8_LAS unsigned char* lds, const Gemm g, const Sched& S, const Epi& E, const int wv0) {
;     ...
;     PG8_WAIT_V(0);
;     if constexpr (!ALIGN_EPI) { if (wr == 0) PG8_BAR; }
;     PG8_BAR;
; __device__ __forceinline__ void xcd_barrier(const XcdBarrier& b, const int wv0) {
;     const bool TID0 = (opaque(TID()) == 0);
;     asm volatile("s_waitcnt vmcnt(0)" ::: "memory");
;     __syncthreads();
;     if (TID0) {
;         unsigned* bar = b.bar;
;         __builtin_amdgcn_s_waitcnt(0);
;         unsigned nloc = b.st[0], nx = b.st[1];
;         if (nloc == 0u) { xcd_barrier_complete(bar, b.x, nloc, nx); b.st[0] = nloc; b.st[1] = nx; }
.LBB0_674:
	s_setprio 0
	v_mov_b32 v0, s77
	ds_read_b64 v[2:3], v0 offset:168
	v_mov_b32_e32 v0, v204
	s_getreg_b32 s4, hwreg(HW_REG_XCC_ID, 0, 4)
	v_mov_b32 v1, s78
	s_waitcnt vmcnt(0)
	s_waitcnt lgkmcnt(0)
	v_readfirstlane_b32 s3, v3
	v_readfirstlane_b32 s2, v2
	v_cmp_eq_u32_e32 vcc, 0, v0
	s_barrier
	s_and_saveexec_b64 s[0:1], vcc
	s_cbranch_execz .LBB0_726
	s_waitcnt vmcnt(0) expcnt(0) lgkmcnt(0)
	ds_read_b32 v2, v1
	ds_read_b32 v0, v1 offset:4
	s_and_b32 s40, s4, 15
	s_waitcnt lgkmcnt(1)
	v_cmp_eq_u32_e32 vcc, 0, v2
	s_and_saveexec_b64 s[4:5], vcc
	s_cbranch_execz .LBB0_690
	s_add_u32 s6, s2, 0x2e400200
	s_addc_u32 s7, s3, 0
	s_add_u32 s8, s2, 0x2e400400
	s_addc_u32 s9, s3, 0
	s_add_u32 s10, s2, 0x2e400500
	s_addc_u32 s11, s3, 0
	s_add_u32 s12, s2, 0x2e400600
	s_addc_u32 s13, s3, 0
	s_add_u32 s14, s2, 0x2e400700
	s_addc_u32 s15, s3, 0
	s_add_u32 s16, s2, 0x2e400800
	s_addc_u32 s17, s3, 0
	s_add_u32 s18, s2, 0x2e400900
	s_addc_u32 s19, s3, 0
	s_add_u32 s20, s2, 0x2e400a00
	s_addc_u32 s21, s3, 0
	s_add_u32 s22, s2, 0x2e400b00
	s_addc_u32 s23, s3, 0
	s_add_u32 s24, s2, 0x2e400c00
	s_addc_u32 s25, s3, 0
	s_add_u32 s26, s2, 0x2e400d00
	s_addc_u32 s27, s3, 0
	s_add_u32 s28, s2, 0x2e400e00
	s_addc_u32 s29, s3, 0
	s_add_u32 s30, s2, 0x2e400f00
	s_addc_u32 s31, s3, 0
	s_add_u32 s34, s2, 0x2e401000
	s_addc_u32 s35, s3, 0
	s_add_u32 s36, s2, 0x2e401100
	s_addc_u32 s37, s3, 0
	s_add_u32 s38, s2, 0x2e401200
	s_addc_u32 s39, s3, 0
	s_mul_i32 s41, s43, s76
	s_add_u32 s44, s2, 0x2e401300
	s_mul_i32 s41, s41, s42
	s_addc_u32 s45, s3, 0
	s_mov_b32 s52, 1
	v_mov_b32_e32 v17, 0
	s_branch .LBB0_678

; #define PG8_BAR __builtin_amdgcn_s_barrier()
; template <class Epi, class Sched, bool ALIGN_EPI = false, bool SP2 = false>
; __device__ __forceinline__ void gemm_phase(PG8_LAS unsigned char* lds, const Gemm g, const Sched& S, const Epi& E, const int wv0) {
;     const int tid = opaque(TID()), wid = __builtin_amdgcn_readfirstlane(tid >> 6), lane = tid & 63, wr = wid >> 2, wc = wid & 3, fr = lane & 15, fq = lane >> 4;
;     const int K = g.K, nt = K / BK;
;     unsigned voffA[2], voffB[2];
; #pragma unroll
;     for (int i = 0; i < 2; ++i) { int R, C; stage_rc(tid * 16 + i * 8192, R, C); const int Rb = Epi::PERM ? ((R & ~31) + perm32(R & 31)) : R;
;         voffA[i] = (unsigned)(R * g.lda + C) * 2u; voffB[i] = (unsigned)(Rb * g.ldb + C) * 2u; }
;     const size_t kstep = (size_t)(BK * 2);
;     const size_t hstepA = (size_t)HALF * g.lda * 2, hstepB = (size_t)HALF * g.ldb * 2;
;     const unsigned ldsw = (unsigned)wid * 1024u;
;     const int aoff = lds_byte(wr * 64 + fr, fq * 8), boff = lds_byte(wc * 32 + fr, fq * 8);
;     ...
;     Unit cur, nxt; int ui = 0;
;     if (!S.next(0, cur)) return;
;     f32x4 acc[2][2][4][2];
; #pragma unroll
;     for (int a = 0; a < 2; ++a)
; #pragma unroll
;         for (int b = 0; b < 2; ++b)
; #pragma unroll
;             for (int m = 0; m < 4; ++m)
; #pragma unroll
;                 for (int n = 0; n < 2; ++n) acc[a][b][m][n] = (f32x4){0.f, 0.f, 0.f, 0.f};
;     bf16x8 At[4][2], B0[2][2], B1[2][2];
;     const char* cA = cur.a; const char* cB = cur.b;
;     if constexpr (SP2) {
;         PG8_STAGE(PG8_SB(0, 0), cB, voffB); PG8_STAGE(PG8_SB(0, 1), cB + hstepB, voffB); PG8_STAGE(PG8_SA(0, 0), cA, voffA); PG8_STAGE(PG8_SA(0, 1), cA + hstepA, voffA);
;         if (wr == 1) PG8_BAR;
;         PG8_WAIT_V(2); PG8_BAR;
; template <int l>
; __device__ __forceinline__ void layer_body(const Ptrs& A, LAS unsigned char* lds, unsigned char* lds_raw, const int wv0) {
;     ...
;             pg8::Gemm g{DM, DM, DM}; pg8::SchedGrid S; S.to.init(T / 256, 2 * DFF / 256); S.G = G; S.c = c; S.A = (const char*)(ws + WS_H); S.B = (const char*)(ws + WS_WGU); S.ta = (size_t)256 * DM * 2; S.tb = (size_t)256 * DM * 2;
;             pg8::EpiSwiglu E{(bf16*)(ws + WS_GATES)};
; #pragma unroll 1
;             for (int rep = 0; rep < 1 + DUP_GEMM; ++rep) { pg8::gemm_phase<pg8::EpiSwiglu, pg8::SchedGrid, true, true>(lds, g, S, E, wv0); __syncthreads(); }
.Lprio_skip_6:
	v_mov_b32 v0, s77
	ds_read_b64 v[0:1], v0 offset:168
	s_mov_b32 s26, s76
	s_mov_b32 s27, s33
	v_mov_b32_e32 v8, v204
	s_waitcnt lgkmcnt(0)
	v_readfirstlane_b32 s1, v1
	v_readfirstlane_b32 s0, v0
	v_mov_b32_e32 v0, v204
	s_cmpk_lt_i32 s27, 0xb00
	s_nop 0
	v_readfirstlane_b32 s9, v8
	s_cbranch_scc0 .LBB0_797
	v_lshlrev_b32_e32 v0, 4, v8
	v_add_u32_e32 v1, 0x2000, v0
	v_ashrrev_i32_e32 v2, 31, v1
	v_lshrrev_b32_e32 v2, 22, v2
	v_add_u32_e32 v2, v1, v2
	v_ashrrev_i32_e32 v9, 10, v2
	v_mul_i32_i24_e32 v2, 0x400, v9
	v_sub_u32_e32 v1, v1, v2
	v_lshrrev_b32_e32 v2, 4, v1
	v_bitop3_b32 v1, v2, v1, 32 bitop3:0x6c
	v_ashrrev_i32_e32 v2, 31, v1
	v_lshrrev_b32_e32 v2, 26, v2
	v_add_u32_e32 v2, v1, v2
	v_lshlrev_b32_e32 v3, 3, v9
	v_ashrrev_i32_e32 v10, 6, v2
	v_and_b32_e32 v3, -16, v3
	v_add_u32_e32 v3, v10, v3
	v_and_b32_e32 v4, 3, v10
	s_mov_b32 s2, 0xfffe0
	v_lshrrev_b32_e32 v5, 2, v3
	v_lshlrev_b32_e32 v6, 1, v3
	v_and_b32_e32 v2, 0xc0, v2
	v_and_or_b32 v4, v3, s2, v4
	v_and_b32_e32 v5, 4, v5
	v_and_b32_e32 v6, 24, v6
	v_sub_u32_e32 v1, v1, v2
	v_mov_b32_e32 v2, 1
	v_or3_b32 v4, v4, v5, v6
	v_lshlrev_b32_e32 v5, 5, v9
	v_ashrrev_i16_sdwa v1, v2, sext(v1) dst_sel:DWORD dst_unused:UNUSED_PAD src0_sel:DWORD src1_sel:BYTE_0
	v_and_b32_e32 v5, 32, v5
	v_bfe_i32 v11, v1, 0, 16
	v_add_lshl_u32 v1, v5, v11, 1
	v_lshl_add_u32 v128, v4, 12, v1
	v_lshl_add_u32 v130, v3, 12, v1
	v_bfe_i32 v1, v8, 27, 1
	v_lshrrev_b32_e32 v1, 22, v1
	v_add_u32_e32 v1, v0, v1
	v_and_b32_e32 v1, 0xfffffc00, v1
	v_sub_u32_e32 v0, v0, v1
	v_lshrrev_b32_e32 v1, 4, v0
	v_bitop3_b32 v1, v1, v0, 32 bitop3:0x6c
	v_ashrrev_i32_e32 v0, 31, v0
	v_lshrrev_b32_e32 v0, 26, v0
	v_add_u32_e32 v0, v1, v0
	v_ashrrev_i32_e32 v12, 6, v0
	v_ashrrev_i32_e32 v0, 31, v8
	v_lshrrev_b32_e32 v0, 26, v0
	v_add_u32_e32 v0, v8, v0
	s_add_u32 s28, s0, 0x9a00000
	v_ashrrev_i32_e32 v13, 6, v0
	s_addc_u32 s29, s1, 0
	v_lshlrev_b32_e32 v0, 3, v13
	s_add_u32 s30, s0, 0x4800000
	v_and_b32_e32 v0, -16, v0
	s_addc_u32 s31, s1, 0
	s_ashr_i32 s34, s27, 31
	v_add_u32_e32 v0, v12, v0
	v_and_b32_e32 v3, 3, v12
	v_and_or_b32 v3, v0, s2, v3
	s_lshr_b32 s2, s34, 29
	s_add_i32 s2, s27, s2
	s_ashr_i32 s6, s9, 6
	s_ashr_i32 s3, s2, 3
	s_and_b32 s2, s2, -8
	s_ashr_i32 s10, s9, 8
	s_lshl_b32 s35, s6, 10
	s_sub_i32 s2, s27, s2
	s_cmp_lt_i32 s2, 0
	s_movk_i32 s36, 0x161
	s_cselect_b32 s4, s36, 0x160
	s_mul_i32 s2, s4, s2
	s_add_i32 s2, s2, s3
	s_mul_hi_i32 s3, s2, 0x2e8ba2e9
	s_lshr_b32 s4, s3, 31
	s_ashr_i32 s3, s3, 5
	s_add_i32 s3, s3, s4
	s_mul_i32 s4, s3, 0xb0
	s_sub_i32 s2, s2, s4
	s_bfe_u32 s4, s2, 0x2001d
	s_add_i32 s4, s2, s4
	s_sext_i32_i16 s5, s4
	s_and_b32 s4, s4, 0xfffc
	s_sub_i32 s2, s2, s4
	s_lshl_b32 s3, s3, 2
	s_sext_i32_i16 s2, s2
	s_add_i32 s18, s3, s2
	v_lshrrev_b32_e32 v4, 2, v0
	v_lshlrev_b32_e32 v5, 1, v0
	s_ashr_i32 s19, s18, 31
	v_and_b32_e32 v4, 4, v4
	v_and_b32_e32 v5, 24, v5
	s_lshr_b32 s8, s5, 2
	s_lshl_b64 s[2:3], s[18:19], 20
	v_or3_b32 v3, v3, v4, v5
	v_mul_i32_i24_e32 v5, 64, v12
	s_add_u32 s20, s28, s2
	v_sub_u32_e32 v1, v1, v5
	s_addc_u32 s21, s29, s3
	s_bfe_i64 s[2:3], s[8:9], 0x100000
	v_lshlrev_b32_e32 v4, 5, v13
	v_ashrrev_i16_sdwa v1, v2, sext(v1) dst_sel:DWORD dst_unused:UNUSED_PAD src0_sel:DWORD src1_sel:BYTE_0
	s_lshl_b64 s[2:3], s[2:3], 20
	v_and_b32_e32 v4, 32, v4
	v_bfe_i32 v14, v1, 0, 16
	s_add_u32 s22, s30, s2
	v_add_lshl_u32 v1, v4, v14, 1
	s_addc_u32 s23, s31, s3
	s_add_i32 s19, s35, 0
	v_lshl_add_u32 v132, v3, 12, v1
	s_add_i32 m0, s19, 0x10000
	v_lshl_add_u32 v134, v0, 12, v1
	global_load_lds_dwordx4 v132, s[22:23]
	s_add_i32 m0, s19, 0x12000
	s_add_u32 s2, s22, 0x80000
	global_load_lds_dwordx4 v128, s[22:23]
	s_addc_u32 s3, s23, 0
	s_add_i32 m0, s19, 0x14000
	s_add_i32 s37, s19, 0x2000
	global_load_lds_dwordx4 v132, s[2:3]
	s_add_i32 m0, s19, 0x16000
	v_mov_b32_e32 v133, 0
	global_load_lds_dwordx4 v128, s[2:3]
	s_mov_b32 m0, s19
	s_add_u32 s2, s20, 0x80000
	global_load_lds_dwordx4 v134, s[20:21]
	s_mov_b32 m0, s37
	s_addc_u32 s3, s21, 0
	s_add_i32 s38, s19, 0x4000
	global_load_lds_dwordx4 v130, s[20:21]
	s_mov_b32 m0, s38
	s_add_i32 s39, s19, 0x6000
	global_load_lds_dwordx4 v134, s[2:3]
	s_mov_b32 m0, s39
	v_mov_b32_e32 v129, v133
	global_load_lds_dwordx4 v130, s[2:3]
	v_mov_b32_e32 v135, v133
	v_mov_b32_e32 v131, v133
	s_cmp_eq_u32 s10, 1
	v_lshl_add_u64 v[6:7], s[22:23], 0, v[132:133]
	v_lshl_add_u64 v[4:5], s[22:23], 0, v[128:129]
	v_lshl_add_u64 v[0:1], s[20:21], 0, v[134:135]
	s_cselect_b64 s[2:3], -1, 0
	s_cmp_lg_u32 s10, 1
	v_lshl_add_u64 v[2:3], s[20:21], 0, v[130:131]
	s_cbranch_scc1 .LBB0_784
	s_barrier

; #define PG8_STAGE(bufoff, gbase, voff) do { _Pragma("unroll") for (int _i = 0; _i < 2; ++_i) \
;         __builtin_amdgcn_global_load_lds((const unsigned*)((const char*)(gbase) + (voff)[_i]), (PG8_LAS unsigned*)(lds + (bufoff) + ldsw + _i * 8192), 16, 0, 0); } while (0)
; #define PG8_LDA(dst, b, h) do { _Pragma("unroll") for (int m = 0; m < 4; ++m) _Pragma("unroll") for (int k = 0; k < 2; ++k) dst[m][k] = *(const PG8_LAS bf16x8*)(lds + PG8_SA(b, h) + aoff + m * 2048 + k * 1024); } while (0)
; #define PG8_LDB(dst, b, h) do { _Pragma("unroll") for (int n = 0; n < 2; ++n) _Pragma("unroll") for (int k = 0; k < 2; ++k) dst[n][k] = *(const PG8_LAS bf16x8*)(lds + PG8_SB(b, h) + boff + n * 2048 + k * 1024); } while (0)
; #define PG8_MMA(ai, bj, At, Bt) do { __builtin_amdgcn_s_setprio(1); _Pragma("unroll") for (int m = 0; m < 4; ++m) _Pragma("unroll") for (int n = 0; n < 2; ++n) _Pragma("unroll") for (int k = 0; k < 2; ++k) \
;         acc[ai][bj][m][n] = __builtin_amdgcn_mfma_f32_16x16x32_bf16(Bt[n][k], At[m][k], acc[ai][bj][m][n], 0, 0, 0); __builtin_amdgcn_s_setprio(0); } while (0)
; #define PG8_WAIT_V(n) asm volatile("s_waitcnt vmcnt(" #n ")" ::: "memory")
; #define PG8_WAIT_L(n) asm volatile("s_waitcnt lgkmcnt(" #n ")" ::: "memory")
; #define PG8_BAR __builtin_amdgcn_s_barrier()
; #define PG8_SCHED __builtin_amdgcn_sched_barrier(0)
; template <class Epi, class Sched, bool ALIGN_EPI = false, bool SP2 = false>
; __device__ __forceinline__ void gemm_phase(PG8_LAS unsigned char* lds, const Gemm g, const Sched& S, const Epi& E, const int wv0) {
;     ...
;             PG8_LDB(B0, 0, 0); PG8_LDB(B1, 0, 1); PG8_SCHED; PG8_LDA(At, 0, 0); PG8_STAGE(PG8_SA(1, 1), a1 + hstepA, voffA);
;             PG8_WAIT_V(8); PG8_WAIT_L(0); PG8_BAR; PG8_MMA(0, 0, At, B0); PG8_MMA(0, 1, At, B1); PG8_BAR; PG8_SCHED;
.LBB0_790:
	ds_read_b128 v[152:155], v149
	ds_read_b128 v[156:159], v149 offset:1024
	ds_read_b128 v[160:163], v149 offset:2048
	ds_read_b128 v[164:167], v149 offset:3072
	ds_read_b128 v[168:171], v150
	ds_read_b128 v[172:175], v150 offset:1024
	ds_read_b128 v[176:179], v150 offset:2048
	ds_read_b128 v[180:183], v150 offset:3072
	s_add_u32 s22, s20, 0xfff80080
	s_addc_u32 s23, s21, -1
	s_cmp_eq_u32 s50, 28
	s_cselect_b32 s25, s15, s23
	s_cselect_b32 s24, s14, s22
	s_cselect_b32 s23, s17, s13
	s_cselect_b32 s22, s16, s11
	v_lshl_add_u64 v[144:145], s[20:21], 0, v[138:139]
	s_add_i32 m0, s19, 0xc000
	ds_read_b128 v[184:187], v151
	ds_read_b128 v[188:191], v151 offset:1024
	ds_read_b128 v[192:195], v151 offset:2048
	ds_read_b128 v[196:199], v151 offset:3072
	ds_read_b128 v[200:203], v151 offset:4096
	ds_read_b128 v[206:209], v151 offset:5120
	ds_read_b128 v[210:213], v151 offset:6144
	ds_read_b128 v[214:217], v151 offset:7168
	global_load_lds_dwordx4 v[144:145], off
	v_lshl_add_u64 v[144:145], s[20:21], 0, v[136:137]
	s_add_i32 m0, s19, 0xe000
	s_nop 0
	global_load_lds_dwordx4 v[144:145], off
	s_waitcnt vmcnt(8)
	s_waitcnt lgkmcnt(0)
	s_barrier
	v_mfma_f32_16x16x32_bf16 v[124:127], v[152:155], v[184:187], v[124:127]
	v_mfma_f32_16x16x32_bf16 v[120:123], v[160:163], v[184:187], v[120:123]
	v_mfma_f32_16x16x32_bf16 v[108:111], v[152:155], v[192:195], v[108:111]
	v_mfma_f32_16x16x32_bf16 v[104:107], v[160:163], v[192:195], v[104:107]
	v_mfma_f32_16x16x32_bf16 v[92:95], v[152:155], v[200:203], v[92:95]
	v_mfma_f32_16x16x32_bf16 v[88:91], v[160:163], v[200:203], v[88:91]
	v_mfma_f32_16x16x32_bf16 v[76:79], v[152:155], v[210:213], v[76:79]
	v_mfma_f32_16x16x32_bf16 v[72:75], v[160:163], v[210:213], v[72:75]
	v_mfma_f32_16x16x32_bf16 v[124:127], v[156:159], v[188:191], v[124:127]
	v_mfma_f32_16x16x32_bf16 v[120:123], v[164:167], v[188:191], v[120:123]
	v_mfma_f32_16x16x32_bf16 v[108:111], v[156:159], v[196:199], v[108:111]
	v_mfma_f32_16x16x32_bf16 v[104:107], v[164:167], v[196:199], v[104:107]
	v_mfma_f32_16x16x32_bf16 v[92:95], v[156:159], v[206:209], v[92:95]
	v_mfma_f32_16x16x32_bf16 v[88:91], v[164:167], v[206:209], v[88:91]
	v_mfma_f32_16x16x32_bf16 v[76:79], v[156:159], v[214:217], v[76:79]
	v_mfma_f32_16x16x32_bf16 v[72:75], v[164:167], v[214:217], v[72:75]
	v_mfma_f32_16x16x32_bf16 v[116:119], v[168:171], v[184:187], v[116:119]
	v_mfma_f32_16x16x32_bf16 v[112:115], v[176:179], v[184:187], v[112:115]
	v_mfma_f32_16x16x32_bf16 v[100:103], v[168:171], v[192:195], v[100:103]
	v_mfma_f32_16x16x32_bf16 v[96:99], v[176:179], v[192:195], v[96:99]
	v_mfma_f32_16x16x32_bf16 v[84:87], v[168:171], v[200:203], v[84:87]
	v_mfma_f32_16x16x32_bf16 v[80:83], v[176:179], v[200:203], v[80:83]
	v_mfma_f32_16x16x32_bf16 v[68:71], v[168:171], v[210:213], v[68:71]
	v_mfma_f32_16x16x32_bf16 v[64:67], v[176:179], v[210:213], v[64:67]
	v_mfma_f32_16x16x32_bf16 v[116:119], v[172:175], v[188:191], v[116:119]
	v_mfma_f32_16x16x32_bf16 v[112:115], v[180:183], v[188:191], v[112:115]
	v_mfma_f32_16x16x32_bf16 v[100:103], v[172:175], v[196:199], v[100:103]
	v_mfma_f32_16x16x32_bf16 v[96:99], v[180:183], v[196:199], v[96:99]
	v_mfma_f32_16x16x32_bf16 v[84:87], v[172:175], v[206:209], v[84:87]
	v_mfma_f32_16x16x32_bf16 v[80:83], v[180:183], v[206:209], v[80:83]
	v_mfma_f32_16x16x32_bf16 v[68:71], v[172:175], v[214:217], v[68:71]
	v_mfma_f32_16x16x32_bf16 v[64:67], v[180:183], v[214:217], v[64:67]
	s_barrier
	s_add_i32 s51, s46, s35
	v_lshl_add_u64 v[144:145], s[22:23], 0, v[132:133]
	s_mov_b32 m0, s51
	ds_read_b128 v[184:187], v151 offset:16384
	ds_read_b128 v[188:191], v151 offset:17408
	ds_read_b128 v[192:195], v151 offset:18432
	ds_read_b128 v[196:199], v151 offset:19456
	ds_read_b128 v[200:203], v151 offset:20480
	ds_read_b128 v[206:209], v151 offset:21504
	ds_read_b128 v[210:213], v151 offset:22528
	ds_read_b128 v[214:217], v151 offset:23552
	global_load_lds_dwordx4 v[144:145], off
	s_add_i32 m0, s51, 0x2000
	s_add_u32 s52, s22, 0x80000
	v_lshl_add_u64 v[218:219], s[22:23], 0, v[128:129]
	s_addc_u32 s53, s23, 0
	s_add_i32 s51, s47, s35
	global_load_lds_dwordx4 v[218:219], off
	v_lshl_add_u64 v[220:221], s[52:53], 0, v[132:133]
	s_mov_b32 m0, s51
	v_lshl_add_u64 v[222:223], s[24:25], 0, v[130:131]
	global_load_lds_dwordx4 v[220:221], off
	v_lshl_add_u64 v[220:221], s[52:53], 0, v[128:129]
	s_add_i32 m0, s51, 0x2000
	s_nop 0
	global_load_lds_dwordx4 v[220:221], off
	v_lshl_add_u64 v[220:221], s[24:25], 0, v[134:135]
	s_mov_b32 m0, s19
	s_nop 0
	global_load_lds_dwordx4 v[220:221], off
	s_mov_b32 m0, s37
	s_nop 0
	global_load_lds_dwordx4 v[222:223], off
	s_waitcnt vmcnt(8)
	s_waitcnt lgkmcnt(0)
	s_barrier
; #define PG8_STAGE(bufoff, gbase, voff) do { _Pragma("unroll") for (int _i = 0; _i < 2; ++_i) \
;         __builtin_amdgcn_global_load_lds((const unsigned*)((const char*)(gbase) + (voff)[_i]), (PG8_LAS unsigned*)(lds + (bufoff) + ldsw + _i * 8192), 16, 0, 0); } while (0)
; #define PG8_LDA(dst, b, h) do { _Pragma("unroll") for (int m = 0; m < 4; ++m) _Pragma("unroll") for (int k = 0; k < 2; ++k) dst[m][k] = *(const PG8_LAS bf16x8*)(lds + PG8_SA(b, h) + aoff + m * 2048 + k * 1024); } while (0)
; #define PG8_LDB(dst, b, h) do { _Pragma("unroll") for (int n = 0; n < 2; ++n) _Pragma("unroll") for (int k = 0; k < 2; ++k) dst[n][k] = *(const PG8_LAS bf16x8*)(lds + PG8_SB(b, h) + boff + n * 2048 + k * 1024); } while (0)
; #define PG8_MMA(ai, bj, At, Bt) do { __builtin_amdgcn_s_setprio(1); _Pragma("unroll") for (int m = 0; m < 4; ++m) _Pragma("unroll") for (int n = 0; n < 2; ++n) _Pragma("unroll") for (int k = 0; k < 2; ++k) \
;         acc[ai][bj][m][n] = __builtin_amdgcn_mfma_f32_16x16x32_bf16(Bt[n][k], At[m][k], acc[ai][bj][m][n], 0, 0, 0); __builtin_amdgcn_s_setprio(0); } while (0)
; #define PG8_WAIT_V(n) asm volatile("s_waitcnt vmcnt(" #n ")" ::: "memory")
; #define PG8_WAIT_L(n) asm volatile("s_waitcnt lgkmcnt(" #n ")" ::: "memory")
; template <class Epi, class Sched, bool ALIGN_EPI = false, bool SP2 = false>
; __device__ __forceinline__ void gemm_phase(PG8_LAS unsigned char* lds, const Gemm g, const Sched& S, const Epi& E, const int wv0) {
;     ...
;             PG8_WAIT_V(8); PG8_WAIT_L(0); PG8_BAR; PG8_MMA(0, 0, At, B0); PG8_MMA(0, 1, At, B1); PG8_BAR; PG8_SCHED;
;             PG8_LDA(At, 0, 1); PG8_STAGE(PG8_SB(0, 0), b2, voffB); PG8_STAGE(PG8_SB(0, 1), b2 + hstepB, voffB); PG8_STAGE(PG8_SA(0, 0), a2, voffA);
;             PG8_WAIT_V(8); PG8_WAIT_L(0); PG8_BAR; PG8_MMA(1, 0, At, B0); PG8_MMA(1, 1, At, B1); PG8_BAR; PG8_SCHED;
;             PG8_LDB(B0, 1, 0); PG8_LDB(B1, 1, 1); PG8_SCHED; PG8_LDA(At, 1, 0); PG8_STAGE(PG8_SA(0, 1), a2 + hstepA, voffA);
;             PG8_WAIT_V(8); PG8_WAIT_L(0); PG8_BAR; PG8_MMA(0, 0, At, B0); PG8_MMA(0, 1, At, B1); PG8_BAR; PG8_SCHED;
;             PG8_LDA(At, 1, 1); PG8_STAGE(PG8_SB(1, 0), b3, voffB); PG8_STAGE(PG8_SB(1, 1), b3 + hstepB, voffB); PG8_STAGE(PG8_SA(1, 0), a3, voffA);
;             PG8_WAIT_V(8); PG8_WAIT_L(0); PG8_BAR; PG8_MMA(1, 0, At, B0); PG8_MMA(1, 1, At, B1); PG8_BAR; PG8_SCHED;
	v_mfma_f32_16x16x32_bf16 v[60:63], v[152:155], v[184:187], v[60:63]
	v_mfma_f32_16x16x32_bf16 v[56:59], v[160:163], v[184:187], v[56:59]
	v_mfma_f32_16x16x32_bf16 v[44:47], v[152:155], v[192:195], v[44:47]
	v_mfma_f32_16x16x32_bf16 v[40:43], v[160:163], v[192:195], v[40:43]
	v_mfma_f32_16x16x32_bf16 v[28:31], v[152:155], v[200:203], v[28:31]
	v_mfma_f32_16x16x32_bf16 v[24:27], v[160:163], v[200:203], v[24:27]
	v_mfma_f32_16x16x32_bf16 v[12:15], v[152:155], v[210:213], v[12:15]
	v_mfma_f32_16x16x32_bf16 v[8:11], v[160:163], v[210:213], v[8:11]
	v_mfma_f32_16x16x32_bf16 v[60:63], v[156:159], v[188:191], v[60:63]
	v_mfma_f32_16x16x32_bf16 v[56:59], v[164:167], v[188:191], v[56:59]
	v_mfma_f32_16x16x32_bf16 v[44:47], v[156:159], v[196:199], v[44:47]
	v_mfma_f32_16x16x32_bf16 v[40:43], v[164:167], v[196:199], v[40:43]
	v_mfma_f32_16x16x32_bf16 v[28:31], v[156:159], v[206:209], v[28:31]
	v_mfma_f32_16x16x32_bf16 v[24:27], v[164:167], v[206:209], v[24:27]
	v_mfma_f32_16x16x32_bf16 v[12:15], v[156:159], v[214:217], v[12:15]
	v_mfma_f32_16x16x32_bf16 v[8:11], v[164:167], v[214:217], v[8:11]
	v_mfma_f32_16x16x32_bf16 v[52:55], v[168:171], v[184:187], v[52:55]
	v_mfma_f32_16x16x32_bf16 v[48:51], v[176:179], v[184:187], v[48:51]
	v_mfma_f32_16x16x32_bf16 v[36:39], v[168:171], v[192:195], v[36:39]
	v_mfma_f32_16x16x32_bf16 v[32:35], v[176:179], v[192:195], v[32:35]
	v_mfma_f32_16x16x32_bf16 v[20:23], v[168:171], v[200:203], v[20:23]
	v_mfma_f32_16x16x32_bf16 v[16:19], v[176:179], v[200:203], v[16:19]
	v_mfma_f32_16x16x32_bf16 v[4:7], v[168:171], v[210:213], v[4:7]
	v_mfma_f32_16x16x32_bf16 v[0:3], v[176:179], v[210:213], v[0:3]
	v_mfma_f32_16x16x32_bf16 v[52:55], v[172:175], v[188:191], v[52:55]
	v_mfma_f32_16x16x32_bf16 v[48:51], v[180:183], v[188:191], v[48:51]
	v_mfma_f32_16x16x32_bf16 v[36:39], v[172:175], v[196:199], v[36:39]
	v_mfma_f32_16x16x32_bf16 v[32:35], v[180:183], v[196:199], v[32:35]
	v_mfma_f32_16x16x32_bf16 v[20:23], v[172:175], v[206:209], v[20:23]
	v_mfma_f32_16x16x32_bf16 v[16:19], v[180:183], v[206:209], v[16:19]
	v_mfma_f32_16x16x32_bf16 v[4:7], v[172:175], v[214:217], v[4:7]
	v_mfma_f32_16x16x32_bf16 v[0:3], v[180:183], v[214:217], v[0:3]
	s_barrier
	s_add_i32 s51, 0, 0x18000
	s_add_i32 s52, 0, 0x1c000
	v_add_u32_e32 v164, s51, v147
	v_add_u32_e32 v180, s52, v147
	ds_read_b128 v[152:155], v164
	ds_read_b128 v[156:159], v164 offset:1024
	ds_read_b128 v[160:163], v164 offset:2048
	ds_read_b128 v[164:167], v164 offset:3072
	ds_read_b128 v[168:171], v180
	ds_read_b128 v[172:175], v180 offset:1024
	ds_read_b128 v[176:179], v180 offset:2048
	ds_read_b128 v[180:183], v180 offset:3072
	s_add_u32 s24, s24, 0x80000
	s_addc_u32 s25, s25, 0
	s_mov_b32 m0, s38
	v_lshl_add_u64 v[224:225], s[24:25], 0, v[134:135]
	ds_read_b128 v[184:187], v151 offset:32768
	ds_read_b128 v[188:191], v151 offset:33792
	ds_read_b128 v[192:195], v151 offset:34816
	ds_read_b128 v[196:199], v151 offset:35840
	ds_read_b128 v[200:203], v151 offset:36864
	ds_read_b128 v[206:209], v151 offset:37888
	ds_read_b128 v[210:213], v151 offset:38912
	ds_read_b128 v[214:217], v151 offset:39936
	global_load_lds_dwordx4 v[224:225], off
	v_lshl_add_u64 v[224:225], s[24:25], 0, v[130:131]
	s_mov_b32 m0, s39
	s_nop 0
	global_load_lds_dwordx4 v[224:225], off
	s_waitcnt vmcnt(8)
	s_waitcnt lgkmcnt(0)
	s_barrier
	v_mfma_f32_16x16x32_bf16 v[124:127], v[152:155], v[184:187], v[124:127]
	v_mfma_f32_16x16x32_bf16 v[120:123], v[160:163], v[184:187], v[120:123]
	v_mfma_f32_16x16x32_bf16 v[108:111], v[152:155], v[192:195], v[108:111]
	v_mfma_f32_16x16x32_bf16 v[104:107], v[160:163], v[192:195], v[104:107]
	v_mfma_f32_16x16x32_bf16 v[92:95], v[152:155], v[200:203], v[92:95]
	v_mfma_f32_16x16x32_bf16 v[88:91], v[160:163], v[200:203], v[88:91]
	v_mfma_f32_16x16x32_bf16 v[76:79], v[152:155], v[210:213], v[76:79]
	v_mfma_f32_16x16x32_bf16 v[72:75], v[160:163], v[210:213], v[72:75]
	v_mfma_f32_16x16x32_bf16 v[124:127], v[156:159], v[188:191], v[124:127]
	v_mfma_f32_16x16x32_bf16 v[120:123], v[164:167], v[188:191], v[120:123]
	v_mfma_f32_16x16x32_bf16 v[108:111], v[156:159], v[196:199], v[108:111]
	v_mfma_f32_16x16x32_bf16 v[104:107], v[164:167], v[196:199], v[104:107]
	v_mfma_f32_16x16x32_bf16 v[92:95], v[156:159], v[206:209], v[92:95]
	v_mfma_f32_16x16x32_bf16 v[88:91], v[164:167], v[206:209], v[88:91]
	v_mfma_f32_16x16x32_bf16 v[76:79], v[156:159], v[214:217], v[76:79]
	v_mfma_f32_16x16x32_bf16 v[72:75], v[164:167], v[214:217], v[72:75]
	v_mfma_f32_16x16x32_bf16 v[116:119], v[168:171], v[184:187], v[116:119]
	v_mfma_f32_16x16x32_bf16 v[112:115], v[176:179], v[184:187], v[112:115]
	v_mfma_f32_16x16x32_bf16 v[100:103], v[168:171], v[192:195], v[100:103]
	v_mfma_f32_16x16x32_bf16 v[96:99], v[176:179], v[192:195], v[96:99]
	v_mfma_f32_16x16x32_bf16 v[84:87], v[168:171], v[200:203], v[84:87]
	v_mfma_f32_16x16x32_bf16 v[80:83], v[176:179], v[200:203], v[80:83]
	v_mfma_f32_16x16x32_bf16 v[68:71], v[168:171], v[210:213], v[68:71]
	v_mfma_f32_16x16x32_bf16 v[64:67], v[176:179], v[210:213], v[64:67]
	v_mfma_f32_16x16x32_bf16 v[116:119], v[172:175], v[188:191], v[116:119]
	v_mfma_f32_16x16x32_bf16 v[112:115], v[180:183], v[188:191], v[112:115]
	v_mfma_f32_16x16x32_bf16 v[100:103], v[172:175], v[196:199], v[100:103]
	v_mfma_f32_16x16x32_bf16 v[96:99], v[180:183], v[196:199], v[96:99]
	v_mfma_f32_16x16x32_bf16 v[84:87], v[172:175], v[206:209], v[84:87]
	v_mfma_f32_16x16x32_bf16 v[80:83], v[180:183], v[206:209], v[80:83]
	v_mfma_f32_16x16x32_bf16 v[68:71], v[172:175], v[214:217], v[68:71]
	v_mfma_f32_16x16x32_bf16 v[64:67], v[180:183], v[214:217], v[64:67]
	s_barrier
; #define PG8_STAGE(bufoff, gbase, voff) do { _Pragma("unroll") for (int _i = 0; _i < 2; ++_i) \
;         __builtin_amdgcn_global_load_lds((const unsigned*)((const char*)(gbase) + (voff)[_i]), (PG8_LAS unsigned*)(lds + (bufoff) + ldsw + _i * 8192), 16, 0, 0); } while (0)
; #define PG8_LDA(dst, b, h) do { _Pragma("unroll") for (int m = 0; m < 4; ++m) _Pragma("unroll") for (int k = 0; k < 2; ++k) dst[m][k] = *(const PG8_LAS bf16x8*)(lds + PG8_SA(b, h) + aoff + m * 2048 + k * 1024); } while (0)
; #define PG8_MMA(ai, bj, At, Bt) do { __builtin_amdgcn_s_setprio(1); _Pragma("unroll") for (int m = 0; m < 4; ++m) _Pragma("unroll") for (int n = 0; n < 2; ++n) _Pragma("unroll") for (int k = 0; k < 2; ++k) \
;         acc[ai][bj][m][n] = __builtin_amdgcn_mfma_f32_16x16x32_bf16(Bt[n][k], At[m][k], acc[ai][bj][m][n], 0, 0, 0); __builtin_amdgcn_s_setprio(0); } while (0)
; #define PG8_WAIT_V(n) asm volatile("s_waitcnt vmcnt(" #n ")" ::: "memory")
; #define PG8_WAIT_L(n) asm volatile("s_waitcnt lgkmcnt(" #n ")" ::: "memory")
; #define PG8_BAR __builtin_amdgcn_s_barrier()
; #define PG8_SCHED __builtin_amdgcn_sched_barrier(0)
; template <class Epi, class Sched, bool ALIGN_EPI = false, bool SP2 = false>
; __device__ __forceinline__ void gemm_phase(PG8_LAS unsigned char* lds, const Gemm g, const Sched& S, const Epi& E, const int wv0) {
;     ...
;         for (int t = 0; t < nt; t += 2) {
;             const bool last = (t == nt - 2);
;             const char* a1 = cA + (size_t)(t + 1) * kstep;
;             const char* a2 = last ? nA : cA + (size_t)(t + 2) * kstep; const char* b2 = last ? nB : cB + (size_t)(t + 2) * kstep;
;     ...
;             PG8_LDA(At, 1, 1); PG8_STAGE(PG8_SB(1, 0), b3, voffB); PG8_STAGE(PG8_SB(1, 1), b3 + hstepB, voffB); PG8_STAGE(PG8_SA(1, 0), a3, voffA);
;             PG8_WAIT_V(8); PG8_WAIT_L(0); PG8_BAR; PG8_MMA(1, 0, At, B0); PG8_MMA(1, 1, At, B1); PG8_BAR; PG8_SCHED;
	s_add_i32 s24, s51, s35
	v_lshl_add_u64 v[144:145], v[144:145], 0, s[6:7]
	s_mov_b32 m0, s24
	ds_read_b128 v[184:187], v151 offset:49152
	ds_read_b128 v[188:191], v151 offset:50176
	ds_read_b128 v[192:195], v151 offset:51200
	ds_read_b128 v[196:199], v151 offset:52224
	ds_read_b128 v[200:203], v151 offset:53248
	ds_read_b128 v[206:209], v151 offset:54272
	ds_read_b128 v[210:213], v151 offset:55296
	ds_read_b128 v[214:217], v151 offset:56320
	global_load_lds_dwordx4 v[144:145], off
	s_add_i32 m0, s24, 0x2000
	s_add_u32 s22, s22, 0x80080
	v_lshl_add_u64 v[144:145], v[218:219], 0, s[6:7]
	s_addc_u32 s23, s23, 0
	s_add_i32 s24, s52, s35
	global_load_lds_dwordx4 v[144:145], off
	v_lshl_add_u64 v[144:145], s[22:23], 0, v[132:133]
	s_mov_b32 m0, s24
	s_nop 0
	global_load_lds_dwordx4 v[144:145], off
	v_lshl_add_u64 v[144:145], s[22:23], 0, v[128:129]
	s_add_i32 m0, s24, 0x2000
	s_nop 0
	global_load_lds_dwordx4 v[144:145], off
	v_lshl_add_u64 v[144:145], v[220:221], 0, s[6:7]
	s_mov_b32 m0, s41
	s_nop 0
	global_load_lds_dwordx4 v[144:145], off
	v_lshl_add_u64 v[144:145], v[222:223], 0, s[6:7]
	s_mov_b32 m0, s44
	s_nop 0
	global_load_lds_dwordx4 v[144:145], off
	s_waitcnt vmcnt(8)
	s_waitcnt lgkmcnt(0)
	s_barrier
	v_mfma_f32_16x16x32_bf16 v[60:63], v[152:155], v[184:187], v[60:63]
	v_mfma_f32_16x16x32_bf16 v[56:59], v[160:163], v[184:187], v[56:59]
	v_mfma_f32_16x16x32_bf16 v[44:47], v[152:155], v[192:195], v[44:47]
	v_mfma_f32_16x16x32_bf16 v[40:43], v[160:163], v[192:195], v[40:43]
	v_mfma_f32_16x16x32_bf16 v[28:31], v[152:155], v[200:203], v[28:31]
	v_mfma_f32_16x16x32_bf16 v[24:27], v[160:163], v[200:203], v[24:27]
	v_mfma_f32_16x16x32_bf16 v[12:15], v[152:155], v[210:213], v[12:15]
	v_mfma_f32_16x16x32_bf16 v[8:11], v[160:163], v[210:213], v[8:11]
	v_mfma_f32_16x16x32_bf16 v[60:63], v[156:159], v[188:191], v[60:63]
	v_mfma_f32_16x16x32_bf16 v[56:59], v[164:167], v[188:191], v[56:59]
	v_mfma_f32_16x16x32_bf16 v[44:47], v[156:159], v[196:199], v[44:47]
	v_mfma_f32_16x16x32_bf16 v[40:43], v[164:167], v[196:199], v[40:43]
	v_mfma_f32_16x16x32_bf16 v[28:31], v[156:159], v[206:209], v[28:31]
	v_mfma_f32_16x16x32_bf16 v[24:27], v[164:167], v[206:209], v[24:27]
	v_mfma_f32_16x16x32_bf16 v[12:15], v[156:159], v[214:217], v[12:15]
	v_mfma_f32_16x16x32_bf16 v[8:11], v[164:167], v[214:217], v[8:11]
	v_mfma_f32_16x16x32_bf16 v[52:55], v[168:171], v[184:187], v[52:55]
	v_mfma_f32_16x16x32_bf16 v[48:51], v[176:179], v[184:187], v[48:51]
	v_mfma_f32_16x16x32_bf16 v[36:39], v[168:171], v[192:195], v[36:39]
	v_mfma_f32_16x16x32_bf16 v[32:35], v[176:179], v[192:195], v[32:35]
	v_mfma_f32_16x16x32_bf16 v[20:23], v[168:171], v[200:203], v[20:23]
	v_mfma_f32_16x16x32_bf16 v[16:19], v[176:179], v[200:203], v[16:19]
	v_mfma_f32_16x16x32_bf16 v[4:7], v[168:171], v[210:213], v[4:7]
	v_mfma_f32_16x16x32_bf16 v[0:3], v[176:179], v[210:213], v[0:3]
	v_mfma_f32_16x16x32_bf16 v[52:55], v[172:175], v[188:191], v[52:55]
	v_mfma_f32_16x16x32_bf16 v[48:51], v[180:183], v[188:191], v[48:51]
	v_mfma_f32_16x16x32_bf16 v[36:39], v[172:175], v[196:199], v[36:39]
	v_mfma_f32_16x16x32_bf16 v[32:35], v[180:183], v[196:199], v[32:35]
	v_mfma_f32_16x16x32_bf16 v[20:23], v[172:175], v[206:209], v[20:23]
	v_mfma_f32_16x16x32_bf16 v[16:19], v[180:183], v[206:209], v[16:19]
	v_mfma_f32_16x16x32_bf16 v[4:7], v[172:175], v[214:217], v[4:7]
	v_mfma_f32_16x16x32_bf16 v[0:3], v[180:183], v[214:217], v[0:3]
	s_barrier
	s_add_i32 s50, s50, 2
	s_add_u32 s11, s11, 0x100
	s_addc_u32 s13, s13, 0
	s_add_u32 s20, s20, 0x100
	s_addc_u32 s21, s21, 0
	s_cmp_gt_u32 s50, 29
	s_cbranch_scc0 .LBB0_790
	s_and_b64 vcc, exec, s[8:9]
	s_cbranch_vccz .LBB0_793
	s_barrier

; #define TID() (wv0 * 64 + (int)__builtin_amdgcn_mbcnt_hi(~0u, __builtin_amdgcn_mbcnt_lo(~0u, 0u)))
; __device__ __forceinline__ int opaque(int x) { asm volatile("" : "+v"(x)); return x; }
; #define PG8_WAIT_V(n) asm volatile("s_waitcnt vmcnt(" #n ")" ::: "memory")
; #define PG8_BAR __builtin_amdgcn_s_barrier()
; __device__ __forceinline__ unsigned xb_add(unsigned* p, unsigned v) { return __hip_atomic_fetch_add(p, v, __ATOMIC_RELAXED, __HIP_MEMORY_SCOPE_AGENT); }
; template <class Epi, class Sched, bool ALIGN_EPI = false, bool SP2 = false>
; __device__ __forceinline__ void gemm_phase(PG8_LAS unsigned char* lds, const Gemm g, const Sched& S, const Epi& E, const int wv0) {
;     ...
;     PG8_WAIT_V(0);
;     if constexpr (!ALIGN_EPI) { if (wr == 0) PG8_BAR; }
;     PG8_BAR;
; __device__ __forceinline__ void xcd_barrier(const XcdBarrier& b, const int wv0) {
;     const bool TID0 = (opaque(TID()) == 0);
;     asm volatile("s_waitcnt vmcnt(0)" ::: "memory");
;     __syncthreads();
;     if (TID0) {
;         unsigned* bar = b.bar;
;         __builtin_amdgcn_s_waitcnt(0);
;         unsigned nloc = b.st[0], nx = b.st[1];
;         if (nloc == 0u) { xcd_barrier_complete(bar, b.x, nloc, nx); b.st[0] = nloc; b.st[1] = nx; }
;         const unsigned old = xb_add(&bar[XB_XSUB(b.x)], 1u);
.LBB0_797:
	s_waitcnt vmcnt(0)
	s_barrier
	s_setprio 0
	v_mov_b32 v0, s77
	ds_read_b64 v[0:1], v0 offset:168
	s_getreg_b32 s4, hwreg(HW_REG_XCC_ID, 0, 4)
	s_waitcnt lgkmcnt(0)
	v_readfirstlane_b32 s2, v0
	v_mov_b32_e32 v0, v204
	v_readfirstlane_b32 s3, v1
	v_mov_b32 v1, s78
	s_waitcnt vmcnt(0)
	s_nop 0
	v_cmp_eq_u32_e32 vcc, 0, v0
	s_barrier
	s_and_saveexec_b64 s[0:1], vcc
	s_xor_b64 s[0:1], exec, s[0:1]
	s_cbranch_execz .LBB0_850
	s_waitcnt vmcnt(0) expcnt(0) lgkmcnt(0)
	ds_read_b32 v2, v1
	ds_read_b32 v0, v1 offset:4
	s_and_b32 s40, s4, 15
	s_waitcnt lgkmcnt(1)
	v_cmp_eq_u32_e32 vcc, 0, v2
	s_and_saveexec_b64 s[4:5], vcc
	s_cbranch_execz .LBB0_813
	s_add_u32 s6, s2, 0x2e400200
	s_addc_u32 s7, s3, 0
	s_add_u32 s8, s2, 0x2e400400
	s_addc_u32 s9, s3, 0
	s_add_u32 s10, s2, 0x2e400500
	s_addc_u32 s11, s3, 0
	s_add_u32 s12, s2, 0x2e400600
	s_addc_u32 s13, s3, 0
	s_add_u32 s14, s2, 0x2e400700
	s_addc_u32 s15, s3, 0
	s_add_u32 s16, s2, 0x2e400800
	s_addc_u32 s17, s3, 0
	s_add_u32 s18, s2, 0x2e400900
	s_addc_u32 s19, s3, 0
	s_add_u32 s20, s2, 0x2e400a00
	s_addc_u32 s21, s3, 0
	s_add_u32 s22, s2, 0x2e400b00
	s_addc_u32 s23, s3, 0
	s_add_u32 s24, s2, 0x2e400c00
	s_addc_u32 s25, s3, 0
	s_add_u32 s26, s2, 0x2e400d00
	s_addc_u32 s27, s3, 0
	s_add_u32 s28, s2, 0x2e400e00
	s_addc_u32 s29, s3, 0
	s_add_u32 s30, s2, 0x2e400f00
	s_addc_u32 s31, s3, 0
	s_add_u32 s34, s2, 0x2e401000
	s_addc_u32 s35, s3, 0
	s_add_u32 s36, s2, 0x2e401100
	s_addc_u32 s37, s3, 0
	s_add_u32 s38, s2, 0x2e401200
	s_addc_u32 s39, s3, 0
	s_mul_i32 s41, s43, s76
	s_add_u32 s44, s2, 0x2e401300
	s_mul_i32 s41, s41, s42
	s_addc_u32 s45, s3, 0
	s_mov_b32 s52, 1
	v_mov_b32_e32 v17, 0
	s_branch .LBB0_801

;     __device__ __forceinline__ bool next(int i, Unit& u) const { int pm, pn; if (!to.get((long)i * G + c, pm, pn)) return false; u.pm = pm; u.pn = pn; u.aux = 0; u.a = A + (size_t)pm * ta; u.b = B + (size_t)pn * tb; return true; }
;     __device__ __forceinline__ bool next(int i, Unit& u) const { if (i != 0) return false; u = one; return true; }
;     __device__ __forceinline__ bool get(long L, int& pm, int& pn) const {
;         if (L >= nwg) return false;
;         int wgid = (int)L; { const int q = nwg / NXCD, r = nwg % NXCD, xcd = wgid % NXCD, off = wgid / NXCD; wgid = (xcd < r ? xcd * (q + 1) : r * (q + 1) + (xcd - r) * q) + off; }
;         const int nig = WGM * nN, gid = wgid / nig, fm = gid * WGM, gsz = (nM - fm) < WGM ? (nM - fm) : WGM;
;         pm = fm + ((wgid % nig) % gsz); pn = (wgid % nig) / gsz; return true;
; template <class Epi, class Sched, bool ALIGN_EPI = false, bool SP2 = false>
; __device__ __forceinline__ void gemm_phase(PG8_LAS unsigned char* lds, const Gemm g, const Sched& S, const Epi& E, const int wv0) {
;     ...
;     if (!S.next(0, cur)) return;
.Lprio_skip_5:
	v_mov_b32 v0, s77
	ds_read_b64 v[0:1], v0 offset:168
	s_mov_b32 s30, s76
	s_mov_b32 s31, s33
	v_mov_b32_e32 v8, v204
	s_waitcnt lgkmcnt(0)
	v_readfirstlane_b32 s1, v1
	v_readfirstlane_b32 s0, v0
	v_mov_b32_e32 v0, v204
	s_cmpk_gt_i32 s31, 0x1ff
	v_readfirstlane_b32 s8, v8
	s_cbranch_scc1 .LBB0_874
	s_ashr_i32 s34, s31, 31
	s_lshr_b32 s2, s34, 29
	s_add_i32 s6, s31, s2
	s_and_b32 s2, s6, -8
	s_sub_i32 s5, s31, s2
	s_cmp_gt_i32 s5, -1
	s_cbranch_scc0 .LBB0_853
	s_lshl_b32 s4, s5, 6
	s_ashr_i32 s2, s6, 3
	s_cbranch_execz .LBB0_854
	s_branch .LBB0_855

; #define PG8_STAGE(bufoff, gbase, voff) do { _Pragma("unroll") for (int _i = 0; _i < 2; ++_i) \
;         __builtin_amdgcn_global_load_lds((const unsigned*)((const char*)(gbase) + (voff)[_i]), (PG8_LAS unsigned*)(lds + (bufoff) + ldsw + _i * 8192), 16, 0, 0); } while (0)
; #define PG8_LDA(dst, b, h) do { _Pragma("unroll") for (int m = 0; m < 4; ++m) _Pragma("unroll") for (int k = 0; k < 2; ++k) dst[m][k] = *(const PG8_LAS bf16x8*)(lds + PG8_SA(b, h) + aoff + m * 2048 + k * 1024); } while (0)
; #define PG8_LDB(dst, b, h) do { _Pragma("unroll") for (int n = 0; n < 2; ++n) _Pragma("unroll") for (int k = 0; k < 2; ++k) dst[n][k] = *(const PG8_LAS bf16x8*)(lds + PG8_SB(b, h) + boff + n * 2048 + k * 1024); } while (0)
; #define PG8_MMA(ai, bj, At, Bt) do { __builtin_amdgcn_s_setprio(1); _Pragma("unroll") for (int m = 0; m < 4; ++m) _Pragma("unroll") for (int n = 0; n < 2; ++n) _Pragma("unroll") for (int k = 0; k < 2; ++k) \
;         acc[ai][bj][m][n] = __builtin_amdgcn_mfma_f32_16x16x32_bf16(Bt[n][k], At[m][k], acc[ai][bj][m][n], 0, 0, 0); __builtin_amdgcn_s_setprio(0); } while (0)
; #define PG8_WAIT_V(n) asm volatile("s_waitcnt vmcnt(" #n ")" ::: "memory")
; #define PG8_WAIT_L(n) asm volatile("s_waitcnt lgkmcnt(" #n ")" ::: "memory")
; #define PG8_BAR __builtin_amdgcn_s_barrier()
; #define PG8_SCHED __builtin_amdgcn_sched_barrier(0)
; template <class Epi, class Sched, bool ALIGN_EPI = false, bool SP2 = false>
; __device__ __forceinline__ void gemm_phase(PG8_LAS unsigned char* lds, const Gemm g, const Sched& S, const Epi& E, const int wv0) {
;     ...
;             PG8_LDB(B0, 0, 0); PG8_LDB(B1, 0, 1); PG8_SCHED; PG8_LDA(At, 0, 0); PG8_STAGE(PG8_SA(1, 1), a1 + hstepA, voffA);
;             PG8_WAIT_V(8); PG8_WAIT_L(0); PG8_BAR; PG8_MMA(0, 0, At, B0); PG8_MMA(0, 1, At, B1); PG8_BAR; PG8_SCHED;
;             PG8_LDA(At, 0, 1); PG8_STAGE(PG8_SB(0, 0), b2, voffB); PG8_STAGE(PG8_SB(0, 1), b2 + hstepB, voffB); PG8_STAGE(PG8_SA(0, 0), a2, voffA);
;             PG8_WAIT_V(8); PG8_WAIT_L(0); PG8_BAR; PG8_MMA(1, 0, At, B0); PG8_MMA(1, 1, At, B1); PG8_BAR; PG8_SCHED;
.LBB0_867:
	ds_read_b128 v[144:147], v155
	ds_read_b128 v[148:151], v155 offset:1024
	ds_read_b128 v[158:161], v155 offset:2048
	ds_read_b128 v[162:165], v155 offset:3072
	ds_read_b128 v[166:169], v156
	ds_read_b128 v[170:173], v156 offset:1024
	ds_read_b128 v[174:177], v156 offset:2048
	ds_read_b128 v[178:181], v156 offset:3072
	s_add_u32 s24, s22, 0x100
	s_addc_u32 s25, s23, 0
	s_cmpk_eq_i32 s58, 0x54
	s_cselect_b32 s29, s19, s25
	s_cselect_b32 s28, s18, s24
	s_cselect_b32 s27, s21, s57
	s_cselect_b32 s26, s20, s56
	v_lshl_add_u64 v[202:203], s[22:23], 0, v[138:139]
	s_add_i32 m0, s40, 0xc000
	ds_read_b128 v[182:185], v157
	ds_read_b128 v[186:189], v157 offset:1024
	ds_read_b128 v[190:193], v157 offset:2048
	ds_read_b128 v[194:197], v157 offset:3072
	ds_read_b128 v[198:201], v157 offset:4096
	ds_read_b128 v[206:209], v157 offset:5120
	ds_read_b128 v[210:213], v157 offset:6144
	ds_read_b128 v[214:217], v157 offset:7168
	global_load_lds_dwordx4 v[202:203], off
	v_lshl_add_u64 v[202:203], s[22:23], 0, v[136:137]
	s_add_i32 m0, s40, 0xe000
	s_nop 0
	global_load_lds_dwordx4 v[202:203], off
	s_waitcnt vmcnt(8)
	s_waitcnt lgkmcnt(0)
	s_barrier
	v_mfma_f32_16x16x32_bf16 v[124:127], v[144:147], v[182:185], v[124:127]
	v_mfma_f32_16x16x32_bf16 v[120:123], v[158:161], v[182:185], v[120:123]
	v_mfma_f32_16x16x32_bf16 v[116:119], v[144:147], v[190:193], v[116:119]
	v_mfma_f32_16x16x32_bf16 v[112:115], v[158:161], v[190:193], v[112:115]
	v_mfma_f32_16x16x32_bf16 v[92:95], v[144:147], v[198:201], v[92:95]
	v_mfma_f32_16x16x32_bf16 v[88:91], v[158:161], v[198:201], v[88:91]
	v_mfma_f32_16x16x32_bf16 v[84:87], v[144:147], v[210:213], v[84:87]
	v_mfma_f32_16x16x32_bf16 v[80:83], v[158:161], v[210:213], v[80:83]
	v_mfma_f32_16x16x32_bf16 v[124:127], v[148:151], v[186:189], v[124:127]
	v_mfma_f32_16x16x32_bf16 v[120:123], v[162:165], v[186:189], v[120:123]
	v_mfma_f32_16x16x32_bf16 v[116:119], v[148:151], v[194:197], v[116:119]
	v_mfma_f32_16x16x32_bf16 v[112:115], v[162:165], v[194:197], v[112:115]
	v_mfma_f32_16x16x32_bf16 v[92:95], v[148:151], v[206:209], v[92:95]
	v_mfma_f32_16x16x32_bf16 v[88:91], v[162:165], v[206:209], v[88:91]
	v_mfma_f32_16x16x32_bf16 v[84:87], v[148:151], v[214:217], v[84:87]
	v_mfma_f32_16x16x32_bf16 v[80:83], v[162:165], v[214:217], v[80:83]
	v_mfma_f32_16x16x32_bf16 v[108:111], v[166:169], v[182:185], v[108:111]
	v_mfma_f32_16x16x32_bf16 v[104:107], v[174:177], v[182:185], v[104:107]
	v_mfma_f32_16x16x32_bf16 v[100:103], v[166:169], v[190:193], v[100:103]
	v_mfma_f32_16x16x32_bf16 v[96:99], v[174:177], v[190:193], v[96:99]
	v_mfma_f32_16x16x32_bf16 v[76:79], v[166:169], v[198:201], v[76:79]
	v_mfma_f32_16x16x32_bf16 v[72:75], v[174:177], v[198:201], v[72:75]
	v_mfma_f32_16x16x32_bf16 v[68:71], v[166:169], v[210:213], v[68:71]
	v_mfma_f32_16x16x32_bf16 v[64:67], v[174:177], v[210:213], v[64:67]
	v_mfma_f32_16x16x32_bf16 v[108:111], v[170:173], v[186:189], v[108:111]
	v_mfma_f32_16x16x32_bf16 v[104:107], v[178:181], v[186:189], v[104:107]
	v_mfma_f32_16x16x32_bf16 v[100:103], v[170:173], v[194:197], v[100:103]
	v_mfma_f32_16x16x32_bf16 v[96:99], v[178:181], v[194:197], v[96:99]
	v_mfma_f32_16x16x32_bf16 v[76:79], v[170:173], v[206:209], v[76:79]
	v_mfma_f32_16x16x32_bf16 v[72:75], v[178:181], v[206:209], v[72:75]
	v_mfma_f32_16x16x32_bf16 v[68:71], v[170:173], v[214:217], v[68:71]
	v_mfma_f32_16x16x32_bf16 v[64:67], v[178:181], v[214:217], v[64:67]
	s_barrier
	s_add_i32 s22, s50, s39
	v_lshl_add_u64 v[202:203], s[26:27], 0, v[130:131]
	s_mov_b32 m0, s22
	ds_read_b128 v[182:185], v157 offset:16384
	ds_read_b128 v[186:189], v157 offset:17408
	ds_read_b128 v[190:193], v157 offset:18432
	ds_read_b128 v[194:197], v157 offset:19456
	ds_read_b128 v[198:201], v157 offset:20480
	ds_read_b128 v[206:209], v157 offset:21504
	ds_read_b128 v[210:213], v157 offset:22528
	ds_read_b128 v[214:217], v157 offset:23552
	global_load_lds_dwordx4 v[202:203], off
	s_add_i32 m0, s22, 0x2000
	s_add_u32 s22, s26, 0x160000
	v_lshl_add_u64 v[218:219], s[26:27], 0, v[134:135]
	s_addc_u32 s23, s27, 0
	s_add_i32 s59, s51, s39
	global_load_lds_dwordx4 v[218:219], off
	v_lshl_add_u64 v[220:221], s[22:23], 0, v[130:131]
	s_mov_b32 m0, s59
	v_lshl_add_u64 v[222:223], s[28:29], 0, v[132:133]
	global_load_lds_dwordx4 v[220:221], off
	v_lshl_add_u64 v[220:221], s[22:23], 0, v[134:135]
	s_add_i32 m0, s59, 0x2000
	s_nop 0
	global_load_lds_dwordx4 v[220:221], off
	v_lshl_add_u64 v[220:221], s[28:29], 0, v[128:129]
	s_mov_b32 m0, s40
	s_nop 0
	global_load_lds_dwordx4 v[220:221], off
	s_mov_b32 m0, s41
	s_nop 0
	global_load_lds_dwordx4 v[222:223], off
	s_waitcnt vmcnt(8)
	s_waitcnt lgkmcnt(0)
	s_barrier
; #define PG8_STAGE(bufoff, gbase, voff) do { _Pragma("unroll") for (int _i = 0; _i < 2; ++_i) \
;         __builtin_amdgcn_global_load_lds((const unsigned*)((const char*)(gbase) + (voff)[_i]), (PG8_LAS unsigned*)(lds + (bufoff) + ldsw + _i * 8192), 16, 0, 0); } while (0)
; #define PG8_LDA(dst, b, h) do { _Pragma("unroll") for (int m = 0; m < 4; ++m) _Pragma("unroll") for (int k = 0; k < 2; ++k) dst[m][k] = *(const PG8_LAS bf16x8*)(lds + PG8_SA(b, h) + aoff + m * 2048 + k * 1024); } while (0)
; #define PG8_LDB(dst, b, h) do { _Pragma("unroll") for (int n = 0; n < 2; ++n) _Pragma("unroll") for (int k = 0; k < 2; ++k) dst[n][k] = *(const PG8_LAS bf16x8*)(lds + PG8_SB(b, h) + boff + n * 2048 + k * 1024); } while (0)
; #define PG8_MMA(ai, bj, At, Bt) do { __builtin_amdgcn_s_setprio(1); _Pragma("unroll") for (int m = 0; m < 4; ++m) _Pragma("unroll") for (int n = 0; n < 2; ++n) _Pragma("unroll") for (int k = 0; k < 2; ++k) \
;         acc[ai][bj][m][n] = __builtin_amdgcn_mfma_f32_16x16x32_bf16(Bt[n][k], At[m][k], acc[ai][bj][m][n], 0, 0, 0); __builtin_amdgcn_s_setprio(0); } while (0)
; #define PG8_WAIT_V(n) asm volatile("s_waitcnt vmcnt(" #n ")" ::: "memory")
; #define PG8_WAIT_L(n) asm volatile("s_waitcnt lgkmcnt(" #n ")" ::: "memory")
; #define PG8_BAR __builtin_amdgcn_s_barrier()
; #define PG8_SCHED __builtin_amdgcn_sched_barrier(0)
; template <class Epi, class Sched, bool ALIGN_EPI = false, bool SP2 = false>
; __device__ __forceinline__ void gemm_phase(PG8_LAS unsigned char* lds, const Gemm g, const Sched& S, const Epi& E, const int wv0) {
;     ...
;             PG8_WAIT_V(8); PG8_WAIT_L(0); PG8_BAR; PG8_MMA(1, 0, At, B0); PG8_MMA(1, 1, At, B1); PG8_BAR; PG8_SCHED;
;             PG8_LDB(B0, 1, 0); PG8_LDB(B1, 1, 1); PG8_SCHED; PG8_LDA(At, 1, 0); PG8_STAGE(PG8_SA(0, 1), a2 + hstepA, voffA);
;             PG8_WAIT_V(8); PG8_WAIT_L(0); PG8_BAR; PG8_MMA(0, 0, At, B0); PG8_MMA(0, 1, At, B1); PG8_BAR; PG8_SCHED;
	v_mfma_f32_16x16x32_bf16 v[60:63], v[144:147], v[182:185], v[60:63]
	v_mfma_f32_16x16x32_bf16 v[56:59], v[158:161], v[182:185], v[56:59]
	v_mfma_f32_16x16x32_bf16 v[52:55], v[144:147], v[190:193], v[52:55]
	v_mfma_f32_16x16x32_bf16 v[48:51], v[158:161], v[190:193], v[48:51]
	v_mfma_f32_16x16x32_bf16 v[28:31], v[144:147], v[198:201], v[28:31]
	v_mfma_f32_16x16x32_bf16 v[24:27], v[158:161], v[198:201], v[24:27]
	v_mfma_f32_16x16x32_bf16 v[20:23], v[144:147], v[210:213], v[20:23]
	v_mfma_f32_16x16x32_bf16 v[16:19], v[158:161], v[210:213], v[16:19]
	v_mfma_f32_16x16x32_bf16 v[60:63], v[148:151], v[186:189], v[60:63]
	v_mfma_f32_16x16x32_bf16 v[56:59], v[162:165], v[186:189], v[56:59]
	v_mfma_f32_16x16x32_bf16 v[52:55], v[148:151], v[194:197], v[52:55]
	v_mfma_f32_16x16x32_bf16 v[48:51], v[162:165], v[194:197], v[48:51]
	v_mfma_f32_16x16x32_bf16 v[28:31], v[148:151], v[206:209], v[28:31]
	v_mfma_f32_16x16x32_bf16 v[24:27], v[162:165], v[206:209], v[24:27]
	v_mfma_f32_16x16x32_bf16 v[20:23], v[148:151], v[214:217], v[20:23]
	v_mfma_f32_16x16x32_bf16 v[16:19], v[162:165], v[214:217], v[16:19]
	v_mfma_f32_16x16x32_bf16 v[44:47], v[166:169], v[182:185], v[44:47]
	v_mfma_f32_16x16x32_bf16 v[40:43], v[174:177], v[182:185], v[40:43]
	v_mfma_f32_16x16x32_bf16 v[36:39], v[166:169], v[190:193], v[36:39]
	v_mfma_f32_16x16x32_bf16 v[32:35], v[174:177], v[190:193], v[32:35]
	v_mfma_f32_16x16x32_bf16 v[12:15], v[166:169], v[198:201], v[12:15]
	v_mfma_f32_16x16x32_bf16 v[8:11], v[174:177], v[198:201], v[8:11]
	v_mfma_f32_16x16x32_bf16 v[4:7], v[166:169], v[210:213], v[4:7]
	v_mfma_f32_16x16x32_bf16 v[0:3], v[174:177], v[210:213], v[0:3]
	v_mfma_f32_16x16x32_bf16 v[44:47], v[170:173], v[186:189], v[44:47]
	v_mfma_f32_16x16x32_bf16 v[40:43], v[178:181], v[186:189], v[40:43]
	v_mfma_f32_16x16x32_bf16 v[36:39], v[170:173], v[194:197], v[36:39]
	v_mfma_f32_16x16x32_bf16 v[32:35], v[178:181], v[194:197], v[32:35]
	v_mfma_f32_16x16x32_bf16 v[12:15], v[170:173], v[206:209], v[12:15]
	v_mfma_f32_16x16x32_bf16 v[8:11], v[178:181], v[206:209], v[8:11]
	v_mfma_f32_16x16x32_bf16 v[4:7], v[170:173], v[214:217], v[4:7]
	v_mfma_f32_16x16x32_bf16 v[0:3], v[178:181], v[214:217], v[0:3]
	s_barrier
	s_add_i32 s59, 0, 0x18000
	s_add_i32 s60, 0, 0x1c000
	v_add_u32_e32 v162, s59, v153
	v_add_u32_e32 v178, s60, v153
	ds_read_b128 v[144:147], v162
	ds_read_b128 v[148:151], v162 offset:1024
	ds_read_b128 v[158:161], v162 offset:2048
	ds_read_b128 v[162:165], v162 offset:3072
	ds_read_b128 v[166:169], v178
	ds_read_b128 v[170:173], v178 offset:1024
	ds_read_b128 v[174:177], v178 offset:2048
	ds_read_b128 v[178:181], v178 offset:3072
	s_add_u32 s22, s28, 0x160000
	s_addc_u32 s23, s29, 0
	s_mov_b32 m0, s44
	v_lshl_add_u64 v[224:225], s[22:23], 0, v[128:129]
	ds_read_b128 v[182:185], v157 offset:32768
	ds_read_b128 v[186:189], v157 offset:33792
	ds_read_b128 v[190:193], v157 offset:34816
	ds_read_b128 v[194:197], v157 offset:35840
	ds_read_b128 v[198:201], v157 offset:36864
	ds_read_b128 v[206:209], v157 offset:37888
	ds_read_b128 v[210:213], v157 offset:38912
	ds_read_b128 v[214:217], v157 offset:39936
	global_load_lds_dwordx4 v[224:225], off
	v_lshl_add_u64 v[224:225], s[22:23], 0, v[132:133]
	s_mov_b32 m0, s45
	s_nop 0
	global_load_lds_dwordx4 v[224:225], off
	s_waitcnt vmcnt(8)
	s_waitcnt lgkmcnt(0)
	s_barrier
	v_mfma_f32_16x16x32_bf16 v[124:127], v[144:147], v[182:185], v[124:127]
	v_mfma_f32_16x16x32_bf16 v[120:123], v[158:161], v[182:185], v[120:123]
	v_mfma_f32_16x16x32_bf16 v[116:119], v[144:147], v[190:193], v[116:119]
	v_mfma_f32_16x16x32_bf16 v[112:115], v[158:161], v[190:193], v[112:115]
	v_mfma_f32_16x16x32_bf16 v[92:95], v[144:147], v[198:201], v[92:95]
	v_mfma_f32_16x16x32_bf16 v[88:91], v[158:161], v[198:201], v[88:91]
	v_mfma_f32_16x16x32_bf16 v[84:87], v[144:147], v[210:213], v[84:87]
	v_mfma_f32_16x16x32_bf16 v[80:83], v[158:161], v[210:213], v[80:83]
	v_mfma_f32_16x16x32_bf16 v[124:127], v[148:151], v[186:189], v[124:127]
	v_mfma_f32_16x16x32_bf16 v[120:123], v[162:165], v[186:189], v[120:123]
	v_mfma_f32_16x16x32_bf16 v[116:119], v[148:151], v[194:197], v[116:119]
	v_mfma_f32_16x16x32_bf16 v[112:115], v[162:165], v[194:197], v[112:115]
	v_mfma_f32_16x16x32_bf16 v[92:95], v[148:151], v[206:209], v[92:95]
	v_mfma_f32_16x16x32_bf16 v[88:91], v[162:165], v[206:209], v[88:91]
	v_mfma_f32_16x16x32_bf16 v[84:87], v[148:151], v[214:217], v[84:87]
	v_mfma_f32_16x16x32_bf16 v[80:83], v[162:165], v[214:217], v[80:83]
	v_mfma_f32_16x16x32_bf16 v[108:111], v[166:169], v[182:185], v[108:111]
	v_mfma_f32_16x16x32_bf16 v[104:107], v[174:177], v[182:185], v[104:107]
	v_mfma_f32_16x16x32_bf16 v[100:103], v[166:169], v[190:193], v[100:103]
	v_mfma_f32_16x16x32_bf16 v[96:99], v[174:177], v[190:193], v[96:99]
	v_mfma_f32_16x16x32_bf16 v[76:79], v[166:169], v[198:201], v[76:79]
	v_mfma_f32_16x16x32_bf16 v[72:75], v[174:177], v[198:201], v[72:75]
	v_mfma_f32_16x16x32_bf16 v[68:71], v[166:169], v[210:213], v[68:71]
	v_mfma_f32_16x16x32_bf16 v[64:67], v[174:177], v[210:213], v[64:67]
	v_mfma_f32_16x16x32_bf16 v[108:111], v[170:173], v[186:189], v[108:111]
	v_mfma_f32_16x16x32_bf16 v[104:107], v[178:181], v[186:189], v[104:107]
	v_mfma_f32_16x16x32_bf16 v[100:103], v[170:173], v[194:197], v[100:103]
	v_mfma_f32_16x16x32_bf16 v[96:99], v[178:181], v[194:197], v[96:99]
	v_mfma_f32_16x16x32_bf16 v[76:79], v[170:173], v[206:209], v[76:79]
	v_mfma_f32_16x16x32_bf16 v[72:75], v[178:181], v[206:209], v[72:75]
	v_mfma_f32_16x16x32_bf16 v[68:71], v[170:173], v[214:217], v[68:71]
	v_mfma_f32_16x16x32_bf16 v[64:67], v[178:181], v[214:217], v[64:67]
	s_barrier
; #define PG8_STAGE(bufoff, gbase, voff) do { _Pragma("unroll") for (int _i = 0; _i < 2; ++_i) \
;         __builtin_amdgcn_global_load_lds((const unsigned*)((const char*)(gbase) + (voff)[_i]), (PG8_LAS unsigned*)(lds + (bufoff) + ldsw + _i * 8192), 16, 0, 0); } while (0)
; #define PG8_LDA(dst, b, h) do { _Pragma("unroll") for (int m = 0; m < 4; ++m) _Pragma("unroll") for (int k = 0; k < 2; ++k) dst[m][k] = *(const PG8_LAS bf16x8*)(lds + PG8_SA(b, h) + aoff + m * 2048 + k * 1024); } while (0)
; #define PG8_MMA(ai, bj, At, Bt) do { __builtin_amdgcn_s_setprio(1); _Pragma("unroll") for (int m = 0; m < 4; ++m) _Pragma("unroll") for (int n = 0; n < 2; ++n) _Pragma("unroll") for (int k = 0; k < 2; ++k) \
;         acc[ai][bj][m][n] = __builtin_amdgcn_mfma_f32_16x16x32_bf16(Bt[n][k], At[m][k], acc[ai][bj][m][n], 0, 0, 0); __builtin_amdgcn_s_setprio(0); } while (0)
; #define PG8_WAIT_V(n) asm volatile("s_waitcnt vmcnt(" #n ")" ::: "memory")
; #define PG8_WAIT_L(n) asm volatile("s_waitcnt lgkmcnt(" #n ")" ::: "memory")
; #define PG8_BAR __builtin_amdgcn_s_barrier()
; #define PG8_SCHED __builtin_amdgcn_sched_barrier(0)
; template <class Epi, class Sched, bool ALIGN_EPI = false, bool SP2 = false>
; __device__ __forceinline__ void gemm_phase(PG8_LAS unsigned char* lds, const Gemm g, const Sched& S, const Epi& E, const int wv0) {
;     ...
;             PG8_LDA(At, 1, 1); PG8_STAGE(PG8_SB(1, 0), b3, voffB); PG8_STAGE(PG8_SB(1, 1), b3 + hstepB, voffB); PG8_STAGE(PG8_SA(1, 0), a3, voffA);
;             PG8_WAIT_V(8); PG8_WAIT_L(0); PG8_BAR; PG8_MMA(1, 0, At, B0); PG8_MMA(1, 1, At, B1); PG8_BAR; PG8_SCHED;
	s_add_i32 s22, s59, s39
	v_lshl_add_u64 v[202:203], v[202:203], 0, s[6:7]
	s_mov_b32 m0, s22
	ds_read_b128 v[182:185], v157 offset:49152
	ds_read_b128 v[186:189], v157 offset:50176
	ds_read_b128 v[190:193], v157 offset:51200
	ds_read_b128 v[194:197], v157 offset:52224
	ds_read_b128 v[198:201], v157 offset:53248
	ds_read_b128 v[206:209], v157 offset:54272
	ds_read_b128 v[210:213], v157 offset:55296
	ds_read_b128 v[214:217], v157 offset:56320
	global_load_lds_dwordx4 v[202:203], off
	s_add_i32 m0, s22, 0x2000
	s_add_u32 s22, s26, 0x160080
	v_lshl_add_u64 v[202:203], v[218:219], 0, s[6:7]
	s_addc_u32 s23, s27, 0
	s_add_i32 s26, s60, s39
	global_load_lds_dwordx4 v[202:203], off
	v_lshl_add_u64 v[202:203], s[22:23], 0, v[130:131]
	s_mov_b32 m0, s26
	s_nop 0
	global_load_lds_dwordx4 v[202:203], off
	v_lshl_add_u64 v[202:203], s[22:23], 0, v[134:135]
	s_add_i32 m0, s26, 0x2000
	s_nop 0
	global_load_lds_dwordx4 v[202:203], off
	v_lshl_add_u64 v[202:203], v[220:221], 0, s[6:7]
	s_mov_b32 m0, s47
	s_nop 0
	global_load_lds_dwordx4 v[202:203], off
	v_lshl_add_u64 v[202:203], v[222:223], 0, s[6:7]
	s_mov_b32 m0, s48
	s_nop 0
	global_load_lds_dwordx4 v[202:203], off
	s_waitcnt vmcnt(8)
	s_waitcnt lgkmcnt(0)
	s_barrier
	v_mfma_f32_16x16x32_bf16 v[60:63], v[144:147], v[182:185], v[60:63]
	v_mfma_f32_16x16x32_bf16 v[56:59], v[158:161], v[182:185], v[56:59]
	v_mfma_f32_16x16x32_bf16 v[52:55], v[144:147], v[190:193], v[52:55]
	v_mfma_f32_16x16x32_bf16 v[48:51], v[158:161], v[190:193], v[48:51]
	v_mfma_f32_16x16x32_bf16 v[28:31], v[144:147], v[198:201], v[28:31]
	v_mfma_f32_16x16x32_bf16 v[24:27], v[158:161], v[198:201], v[24:27]
	v_mfma_f32_16x16x32_bf16 v[20:23], v[144:147], v[210:213], v[20:23]
	v_mfma_f32_16x16x32_bf16 v[16:19], v[158:161], v[210:213], v[16:19]
	v_mfma_f32_16x16x32_bf16 v[60:63], v[148:151], v[186:189], v[60:63]
	v_mfma_f32_16x16x32_bf16 v[56:59], v[162:165], v[186:189], v[56:59]
	v_mfma_f32_16x16x32_bf16 v[52:55], v[148:151], v[194:197], v[52:55]
	v_mfma_f32_16x16x32_bf16 v[48:51], v[162:165], v[194:197], v[48:51]
	v_mfma_f32_16x16x32_bf16 v[28:31], v[148:151], v[206:209], v[28:31]
	v_mfma_f32_16x16x32_bf16 v[24:27], v[162:165], v[206:209], v[24:27]
	v_mfma_f32_16x16x32_bf16 v[20:23], v[148:151], v[214:217], v[20:23]
	v_mfma_f32_16x16x32_bf16 v[16:19], v[162:165], v[214:217], v[16:19]
	v_mfma_f32_16x16x32_bf16 v[44:47], v[166:169], v[182:185], v[44:47]
	v_mfma_f32_16x16x32_bf16 v[40:43], v[174:177], v[182:185], v[40:43]
	v_mfma_f32_16x16x32_bf16 v[36:39], v[166:169], v[190:193], v[36:39]
	v_mfma_f32_16x16x32_bf16 v[32:35], v[174:177], v[190:193], v[32:35]
	v_mfma_f32_16x16x32_bf16 v[12:15], v[166:169], v[198:201], v[12:15]
	v_mfma_f32_16x16x32_bf16 v[8:11], v[174:177], v[198:201], v[8:11]
	v_mfma_f32_16x16x32_bf16 v[4:7], v[166:169], v[210:213], v[4:7]
	v_mfma_f32_16x16x32_bf16 v[0:3], v[174:177], v[210:213], v[0:3]
	v_mfma_f32_16x16x32_bf16 v[44:47], v[170:173], v[186:189], v[44:47]
	v_mfma_f32_16x16x32_bf16 v[40:43], v[178:181], v[186:189], v[40:43]
	v_mfma_f32_16x16x32_bf16 v[36:39], v[170:173], v[194:197], v[36:39]
	v_mfma_f32_16x16x32_bf16 v[32:35], v[178:181], v[194:197], v[32:35]
	v_mfma_f32_16x16x32_bf16 v[12:15], v[170:173], v[206:209], v[12:15]
	v_mfma_f32_16x16x32_bf16 v[8:11], v[178:181], v[206:209], v[8:11]
	v_mfma_f32_16x16x32_bf16 v[4:7], v[170:173], v[214:217], v[4:7]
	v_mfma_f32_16x16x32_bf16 v[0:3], v[178:181], v[214:217], v[0:3]
	s_barrier
	s_add_i32 s58, s58, 2
	s_add_u32 s56, s56, 0x100
	s_addc_u32 s57, s57, 0
	s_cmpk_gt_u32 s58, 0x55
	s_mov_b64 s[22:23], s[24:25]
	s_cbranch_scc0 .LBB0_867
	s_and_b64 vcc, exec, s[8:9]
	s_cbranch_vccz .LBB0_870
	s_barrier

;     __device__ __forceinline__ bool get(long L, int& pm, int& pn) const {
;     ...
;         int wgid = (int)L; { const int q = nwg / NXCD, r = nwg % NXCD, xcd = wgid % NXCD, off = wgid / NXCD; wgid = (xcd < r ? xcd * (q + 1) : r * (q + 1) + (xcd - r) * q) + off; }
;         const int nig = WGM * nN, gid = wgid / nig, fm = gid * WGM, gsz = (nM - fm) < WGM ? (nM - fm) : WGM;
;         pm = fm + ((wgid % nig) % gsz); pn = (wgid % nig) / gsz; return true;
; template <class Epi, class Sched, bool ALIGN_EPI = false, bool SP2 = false>
; __device__ __forceinline__ void gemm_phase(PG8_LAS unsigned char* lds, const Gemm g, const Sched& S, const Epi& E, const int wv0) {
;     const int tid = opaque(TID()), wid = __builtin_amdgcn_readfirstlane(tid >> 6), lane = tid & 63, wr = wid >> 2, wc = wid & 3, fr = lane & 15, fq = lane >> 4;
;     const int K = g.K, nt = K / BK;
;     unsigned voffA[2], voffB[2];
; #pragma unroll
;     for (int i = 0; i < 2; ++i) { int R, C; stage_rc(tid * 16 + i * 8192, R, C); const int Rb = Epi::PERM ? ((R & ~31) + perm32(R & 31)) : R;
;         voffA[i] = (unsigned)(R * g.lda + C) * 2u; voffB[i] = (unsigned)(Rb * g.ldb + C) * 2u; }
;     const size_t kstep = (size_t)(BK * 2);
;     const size_t hstepA = (size_t)HALF * g.lda * 2, hstepB = (size_t)HALF * g.ldb * 2;
;     const unsigned ldsw = (unsigned)wid * 1024u;
;     const int aoff = lds_byte(wr * 64 + fr, fq * 8), boff = lds_byte(wc * 32 + fr, fq * 8);
;     ...
;     Unit cur, nxt; int ui = 0;
;     if (!S.next(0, cur)) return;
;     f32x4 acc[2][2][4][2];
; #pragma unroll
;     for (int a = 0; a < 2; ++a)
; #pragma unroll
;         for (int b = 0; b < 2; ++b)
; #pragma unroll
;             for (int m = 0; m < 4; ++m)
; #pragma unroll
;                 for (int n = 0; n < 2; ++n) acc[a][b][m][n] = (f32x4){0.f, 0.f, 0.f, 0.f};
;     bf16x8 At[4][2], B0[2][2], B1[2][2];
;     const char* cA = cur.a; const char* cB = cur.b;
;     if constexpr (SP2) {
;         PG8_STAGE(PG8_SB(0, 0), cB, voffB); PG8_STAGE(PG8_SB(0, 1), cB + hstepB, voffB); PG8_STAGE(PG8_SA(0, 0), cA, voffA); PG8_STAGE(PG8_SA(0, 1), cA + hstepA, voffA);
;         if (wr == 1) PG8_BAR;
;         PG8_WAIT_V(2); PG8_BAR;
;         PG8_STAGE(PG8_SB(1, 0), cB + kstep, voffB); PG8_STAGE(PG8_SA(1, 0), cA + kstep, voffA); PG8_STAGE(PG8_SB(1, 1), cB + hstepB + kstep, voffB);
;         PG8_WAIT_V(6); PG8_BAR;
.Lprio_skip_4:
	v_mov_b32 v0, s77
	ds_read_b64 v[0:1], v0 offset:168
	s_mov_b32 s40, s76
	s_mov_b32 s41, s33
	v_mov_b32_e32 v9, v204
	s_waitcnt lgkmcnt(0)
	v_readfirstlane_b32 s3, v1
	v_readfirstlane_b32 s2, v0
	v_mov_b32_e32 v0, v204
	s_cmpk_lt_i32 s41, 0xd00
	s_nop 0
	v_readfirstlane_b32 s1, v9
	s_cbranch_scc0 .LBB0_1061
	v_lshlrev_b32_e32 v0, 4, v9
	v_add_u32_e32 v1, 0x2000, v0
	v_ashrrev_i32_e32 v2, 31, v1
	v_lshrrev_b32_e32 v2, 22, v2
	v_add_u32_e32 v2, v1, v2
	v_ashrrev_i32_e32 v8, 10, v2
	v_mul_i32_i24_e32 v2, 0x400, v8
	v_sub_u32_e32 v1, v1, v2
	v_lshrrev_b32_e32 v2, 4, v1
	v_bitop3_b32 v1, v2, v1, 32 bitop3:0x6c
	v_ashrrev_i32_e32 v2, 31, v1
	v_lshrrev_b32_e32 v2, 26, v2
	v_add_u32_e32 v2, v1, v2
	v_lshlrev_b32_e32 v3, 3, v8
	v_ashrrev_i32_e32 v10, 6, v2
	v_and_b32_e32 v3, -16, v3
	v_add_u32_e32 v3, v10, v3
	v_and_b32_e32 v4, 3, v10
	s_mov_b32 s0, 0xfffe0
	v_lshrrev_b32_e32 v5, 2, v3
	v_lshlrev_b32_e32 v6, 1, v3
	v_and_b32_e32 v2, 0xc0, v2
	v_and_or_b32 v4, v3, s0, v4
	v_and_b32_e32 v5, 4, v5
	v_and_b32_e32 v6, 24, v6
	v_sub_u32_e32 v1, v1, v2
	v_mov_b32_e32 v148, 1
	v_or3_b32 v4, v4, v5, v6
	v_lshlrev_b32_e32 v5, 5, v8
	v_ashrrev_i16_sdwa v1, v148, sext(v1) dst_sel:DWORD dst_unused:UNUSED_PAD src0_sel:DWORD src1_sel:BYTE_0
	v_and_b32_e32 v5, 32, v5
	v_bfe_i32 v11, v1, 0, 16
	v_add_lshl_u32 v1, v5, v11, 1
	v_lshl_add_u32 v128, v4, 12, v1
	v_lshl_add_u32 v130, v3, 12, v1
	v_bfe_i32 v1, v9, 27, 1
	v_lshrrev_b32_e32 v1, 22, v1
	v_add_u32_e32 v1, v0, v1
	v_and_b32_e32 v1, 0xfffffc00, v1
	v_sub_u32_e32 v0, v0, v1
	v_lshrrev_b32_e32 v1, 4, v0
	v_bitop3_b32 v1, v1, v0, 32 bitop3:0x6c
	v_ashrrev_i32_e32 v0, 31, v0
	v_lshrrev_b32_e32 v0, 26, v0
	v_add_u32_e32 v0, v1, v0
	v_ashrrev_i32_e32 v12, 6, v0
	v_ashrrev_i32_e32 v0, 31, v9
	v_lshrrev_b32_e32 v0, 26, v0
	v_add_u32_e32 v0, v9, v0
	v_ashrrev_i32_e32 v13, 6, v0
	v_lshlrev_b32_e32 v0, 3, v13
	s_add_u32 s44, s2, 0x9a00000
	v_and_b32_e32 v0, -16, v0
	s_addc_u32 s45, s3, 0
	s_ashr_i32 s46, s41, 31
	v_add_u32_e32 v0, v12, v0
	v_and_b32_e32 v2, 3, v12
	v_and_or_b32 v2, v0, s0, v2
	s_lshr_b32 s0, s46, 29
	s_add_i32 s0, s41, s0
	s_ashr_i32 s14, s1, 6
	s_ashr_i32 s4, s0, 3
	s_and_b32 s0, s0, -8
	s_ashr_i32 s17, s1, 8
	s_lshl_b32 s47, s14, 10
	s_sub_i32 s0, s41, s0
	s_cmp_lt_i32 s0, 0
	s_movk_i32 s48, 0x1a1
	s_cselect_b32 s5, s48, 0x1a0
	s_mul_i32 s0, s5, s0
	s_add_i32 s0, s0, s4
	s_mul_hi_i32 s4, s0, 0x4ec4ec4f
	s_lshr_b32 s5, s4, 31
	s_ashr_i32 s4, s4, 6
	s_add_i32 s4, s4, s5
	s_mul_i32 s5, s4, 0xd0
	s_sub_i32 s5, s0, s5
	s_bfe_u32 s0, s5, 0x2001d
	s_add_i32 s6, s5, s0
	s_sext_i32_i16 s0, s6
	s_and_b32 s6, s6, 0xfffc
	s_sub_i32 s5, s5, s6
	s_lshl_b32 s4, s4, 2
	s_sext_i32_i16 s5, s5
	s_add_i32 s28, s4, s5
	v_lshrrev_b32_e32 v3, 2, v0
	v_lshlrev_b32_e32 v4, 1, v0
	s_ashr_i32 s29, s28, 31
	v_and_b32_e32 v3, 4, v3
	v_and_b32_e32 v4, 24, v4
	s_lshr_b32 s0, s0, 2
	s_lshl_b64 s[4:5], s[28:29], 20
	v_or3_b32 v2, v2, v3, v4
	v_mul_i32_i24_e32 v4, 64, v12
	s_add_u32 s30, s44, s4
	v_sub_u32_e32 v1, v1, v4
	s_addc_u32 s31, s45, s5
	s_bfe_i64 s[4:5], s[0:1], 0x100000
	v_lshlrev_b32_e32 v3, 5, v13
	v_ashrrev_i16_sdwa v1, v148, sext(v1) dst_sel:DWORD dst_unused:UNUSED_PAD src0_sel:DWORD src1_sel:BYTE_0
	s_lshl_b64 s[4:5], s[4:5], 20
	v_and_b32_e32 v3, 32, v3
	v_bfe_i32 v14, v1, 0, 16
	s_add_u32 s34, s2, s4
	v_add_lshl_u32 v1, v3, v14, 1
	s_addc_u32 s35, s3, s5
	s_add_i32 s29, s47, 0
	v_lshl_add_u32 v132, v2, 12, v1
	s_add_i32 m0, s29, 0x10000
	v_lshl_add_u32 v134, v0, 12, v1
	global_load_lds_dwordx4 v132, s[34:35]
	s_add_i32 m0, s29, 0x12000
	s_add_u32 s4, s34, 0x80000
	global_load_lds_dwordx4 v128, s[34:35]
	s_addc_u32 s5, s35, 0
	s_add_i32 m0, s29, 0x14000
	s_add_i32 s49, s29, 0x2000
	global_load_lds_dwordx4 v132, s[4:5]
	s_add_i32 m0, s29, 0x16000
	v_mov_b32_e32 v133, 0
	global_load_lds_dwordx4 v128, s[4:5]
	s_mov_b32 m0, s29
	s_add_u32 s4, s30, 0x80000
	global_load_lds_dwordx4 v134, s[30:31]
	s_mov_b32 m0, s49
	s_addc_u32 s5, s31, 0
	s_add_i32 s50, s29, 0x4000
	global_load_lds_dwordx4 v130, s[30:31]
	s_mov_b32 m0, s50
	s_add_i32 s51, s29, 0x6000
	global_load_lds_dwordx4 v134, s[4:5]
	s_mov_b32 m0, s51
	v_mov_b32_e32 v129, v133
	global_load_lds_dwordx4 v130, s[4:5]
	v_mov_b32_e32 v135, v133
	v_mov_b32_e32 v131, v133
	s_cmp_eq_u32 s17, 1
	s_movk_i32 s52, 0x2000
	v_lshl_add_u64 v[6:7], s[34:35], 0, v[132:133]
	v_lshl_add_u64 v[4:5], s[34:35], 0, v[128:129]
	v_lshl_add_u64 v[2:3], s[30:31], 0, v[134:135]
	v_lshl_add_u64 v[0:1], s[30:31], 0, v[130:131]
	s_movk_i32 s53, 0x4000
	s_cselect_b64 s[4:5], -1, 0
	s_cmp_lg_u32 s17, 1
	s_movk_i32 s54, 0x6000
	s_cbranch_scc1 .LBB0_1028
	s_barrier

; #define TID() (wv0 * 64 + (int)__builtin_amdgcn_mbcnt_hi(~0u, __builtin_amdgcn_mbcnt_lo(~0u, 0u)))
; __device__ __forceinline__ int opaque(int x) { asm volatile("" : "+v"(x)); return x; }
; #define PG8_WAIT_V(n) asm volatile("s_waitcnt vmcnt(" #n ")" ::: "memory")
; #define PG8_BAR __builtin_amdgcn_s_barrier()
; __device__ __forceinline__ unsigned xb_add(unsigned* p, unsigned v) { return __hip_atomic_fetch_add(p, v, __ATOMIC_RELAXED, __HIP_MEMORY_SCOPE_AGENT); }
; template <class Epi, class Sched, bool ALIGN_EPI = false, bool SP2 = false>
; __device__ __forceinline__ void gemm_phase(PG8_LAS unsigned char* lds, const Gemm g, const Sched& S, const Epi& E, const int wv0) {
;     ...
;     PG8_WAIT_V(0);
;     if constexpr (!ALIGN_EPI) { if (wr == 0) PG8_BAR; }
;     PG8_BAR;
; __device__ __forceinline__ void xcd_barrier(const XcdBarrier& b, const int wv0) {
;     const bool TID0 = (opaque(TID()) == 0);
;     asm volatile("s_waitcnt vmcnt(0)" ::: "memory");
;     __syncthreads();
;     if (TID0) {
;         unsigned* bar = b.bar;
;         __builtin_amdgcn_s_waitcnt(0);
;         unsigned nloc = b.st[0], nx = b.st[1];
;         if (nloc == 0u) { xcd_barrier_complete(bar, b.x, nloc, nx); b.st[0] = nloc; b.st[1] = nx; }
;         const unsigned old = xb_add(&bar[XB_XSUB(b.x)], 1u);
.LBB0_1061:
	s_waitcnt vmcnt(0)
	s_barrier
	s_setprio 0
	v_mov_b32 v0, s77
	ds_read_b64 v[0:1], v0 offset:168
	s_getreg_b32 s4, hwreg(HW_REG_XCC_ID, 0, 4)
	s_waitcnt lgkmcnt(0)
	v_readfirstlane_b32 s2, v0
	v_mov_b32_e32 v0, v204
	v_readfirstlane_b32 s3, v1
	v_mov_b32 v1, s78
	s_waitcnt vmcnt(0)
	s_nop 0
	v_cmp_eq_u32_e32 vcc, 0, v0
	s_barrier
	s_and_saveexec_b64 s[0:1], vcc
	s_xor_b64 s[0:1], exec, s[0:1]
	s_cbranch_execz .LBB0_1114
	s_waitcnt vmcnt(0) expcnt(0) lgkmcnt(0)
	ds_read_b32 v2, v1
	ds_read_b32 v0, v1 offset:4
	s_and_b32 s40, s4, 15
	s_waitcnt lgkmcnt(1)
	v_cmp_eq_u32_e32 vcc, 0, v2
	s_and_saveexec_b64 s[4:5], vcc
	s_cbranch_execz .LBB0_1077
	s_load_dword s6, s[70:71], 0x14
	s_mov_b32 s41, 1
	v_mov_b32_e32 v17, 0
	s_waitcnt lgkmcnt(0)
	s_lshr_b32 s8, s6, 16
	s_and_b32 s6, s6, 0xffff
	s_cmp_lg_u32 s6, 0
	s_cselect_b64 s[6:7], -1, 0
	s_cmp_lg_u64 s[6:7], 0
	s_addc_u32 s6, s42, 0
	s_cmp_lg_u32 s8, 0
	s_mul_i32 s52, s6, s76
	s_cselect_b64 s[6:7], -1, 0
	s_cmp_lg_u64 s[6:7], 0
	s_addc_u32 s6, s43, 0
	s_mul_i32 s52, s52, s6
	s_add_u32 s6, s2, 0x2e400200
	s_addc_u32 s7, s3, 0
	s_add_u32 s8, s2, 0x2e400400
	s_addc_u32 s9, s3, 0
	s_add_u32 s10, s2, 0x2e400500
	s_addc_u32 s11, s3, 0
	s_add_u32 s12, s2, 0x2e400600
	s_addc_u32 s13, s3, 0
	s_add_u32 s14, s2, 0x2e400700
	s_addc_u32 s15, s3, 0
	s_add_u32 s16, s2, 0x2e400800
	s_addc_u32 s17, s3, 0
	s_add_u32 s18, s2, 0x2e400900
	s_addc_u32 s19, s3, 0
	s_add_u32 s20, s2, 0x2e400a00
	s_addc_u32 s21, s3, 0
	s_add_u32 s22, s2, 0x2e400b00
	s_addc_u32 s23, s3, 0
	s_add_u32 s24, s2, 0x2e400c00
	s_addc_u32 s25, s3, 0
	s_add_u32 s26, s2, 0x2e400d00
	s_addc_u32 s27, s3, 0
	s_add_u32 s28, s2, 0x2e400e00
	s_addc_u32 s29, s3, 0
	s_add_u32 s30, s2, 0x2e400f00
	s_addc_u32 s31, s3, 0
	s_add_u32 s34, s2, 0x2e401000
	s_addc_u32 s35, s3, 0
	s_add_u32 s36, s2, 0x2e401100
	s_addc_u32 s37, s3, 0
	s_add_u32 s38, s2, 0x2e401200
	s_addc_u32 s39, s3, 0
	s_add_u32 s44, s2, 0x2e401300
	s_addc_u32 s45, s3, 0
	s_branch .LBB0_1065

; #define TID() (wv0 * 64 + (int)__builtin_amdgcn_mbcnt_hi(~0u, __builtin_amdgcn_mbcnt_lo(~0u, 0u)))
; __device__ __forceinline__ int opaque(int x) { asm volatile("" : "+v"(x)); return x; }
; #define PG8_WAIT_V(n) asm volatile("s_waitcnt vmcnt(" #n ")" ::: "memory")
; #define PG8_BAR __builtin_amdgcn_s_barrier()
; __device__ __forceinline__ unsigned xb_add(unsigned* p, unsigned v) { return __hip_atomic_fetch_add(p, v, __ATOMIC_RELAXED, __HIP_MEMORY_SCOPE_AGENT); }
; template <class Epi, class Sched, bool ALIGN_EPI = false, bool SP2 = false>
; __device__ __forceinline__ void gemm_phase(PG8_LAS unsigned char* lds, const Gemm g, const Sched& S, const Epi& E, const int wv0) {
;     ...
;     PG8_WAIT_V(0);
;     if constexpr (!ALIGN_EPI) { if (wr == 0) PG8_BAR; }
;     PG8_BAR;
; __device__ __forceinline__ void xcd_barrier(const XcdBarrier& b, const int wv0) {
;     const bool TID0 = (opaque(TID()) == 0);
;     asm volatile("s_waitcnt vmcnt(0)" ::: "memory");
;     __syncthreads();
;     if (TID0) {
;         unsigned* bar = b.bar;
;         __builtin_amdgcn_s_waitcnt(0);
;         unsigned nloc = b.st[0], nx = b.st[1];
;         if (nloc == 0u) { xcd_barrier_complete(bar, b.x, nloc, nx); b.st[0] = nloc; b.st[1] = nx; }
;         const unsigned old = xb_add(&bar[XB_XSUB(b.x)], 1u);
.LBB0_1538:
	s_barrier
	s_setprio 0
	v_mov_b32 v0, s77
	ds_read_b64 v[0:1], v0 offset:168
	s_getreg_b32 s4, hwreg(HW_REG_XCC_ID, 0, 4)
	s_waitcnt lgkmcnt(0)
	v_readfirstlane_b32 s2, v0
	v_mov_b32_e32 v0, v204
	v_readfirstlane_b32 s3, v1
	v_mov_b32 v1, s78
	s_waitcnt vmcnt(0)
	s_nop 0
	v_cmp_eq_u32_e32 vcc, 0, v0
	s_barrier
	s_and_saveexec_b64 s[0:1], vcc
	s_xor_b64 s[0:1], exec, s[0:1]
	s_cbranch_execz .LBB0_1591
	s_waitcnt vmcnt(0) expcnt(0) lgkmcnt(0)
	ds_read_b32 v2, v1
	ds_read_b32 v0, v1 offset:4
	s_and_b32 s40, s4, 15
	s_waitcnt lgkmcnt(1)
	v_cmp_eq_u32_e32 vcc, 0, v2
	s_and_saveexec_b64 s[4:5], vcc
	s_cbranch_execz .LBB0_1554
	s_load_dword s6, s[94:95], 0x14
	s_mov_b32 s41, 1
	v_mov_b32_e32 v17, 0
	s_waitcnt lgkmcnt(0)
	s_lshr_b32 s8, s6, 16
	s_and_b32 s6, s6, 0xffff
	s_cmp_lg_u32 s6, 0
	s_cselect_b64 s[6:7], -1, 0
	s_cmp_lg_u64 s[6:7], 0
	s_addc_u32 s6, s42, 0
	s_cmp_lg_u32 s8, 0
	s_mul_i32 s52, s6, s76
	s_cselect_b64 s[6:7], -1, 0
	s_cmp_lg_u64 s[6:7], 0
	s_addc_u32 s6, s43, 0
	s_mul_i32 s52, s52, s6
	s_add_u32 s6, s2, 0x2e400200
	s_addc_u32 s7, s3, 0
	s_add_u32 s8, s2, 0x2e400400
	s_addc_u32 s9, s3, 0
	s_add_u32 s10, s2, 0x2e400500
	s_addc_u32 s11, s3, 0
	s_add_u32 s12, s2, 0x2e400600
	s_addc_u32 s13, s3, 0
	s_add_u32 s14, s2, 0x2e400700
	s_addc_u32 s15, s3, 0
	s_add_u32 s16, s2, 0x2e400800
	s_addc_u32 s17, s3, 0
	s_add_u32 s18, s2, 0x2e400900
	s_addc_u32 s19, s3, 0
	s_add_u32 s20, s2, 0x2e400a00
	s_addc_u32 s21, s3, 0
	s_add_u32 s22, s2, 0x2e400b00
	s_addc_u32 s23, s3, 0
	s_add_u32 s24, s2, 0x2e400c00
	s_addc_u32 s25, s3, 0
	s_add_u32 s26, s2, 0x2e400d00
	s_addc_u32 s27, s3, 0
	s_add_u32 s28, s2, 0x2e400e00
	s_addc_u32 s29, s3, 0
	s_add_u32 s30, s2, 0x2e400f00
	s_addc_u32 s31, s3, 0
	s_add_u32 s34, s2, 0x2e401000
	s_addc_u32 s35, s3, 0
	s_add_u32 s36, s2, 0x2e401100
	s_addc_u32 s37, s3, 0
	s_add_u32 s38, s2, 0x2e401200
	s_addc_u32 s39, s3, 0
	s_add_u32 s44, s2, 0x2e401300
	s_addc_u32 s45, s3, 0
	s_branch .LBB0_1542

;     __device__ __forceinline__ bool next(int i, Unit& u) const { int pm, pn; if (!to.get((long)i * G + c, pm, pn)) return false; u.pm = pm; u.pn = pn; u.aux = 0; u.a = A + (size_t)pm * ta; u.b = B + (size_t)pn * tb; return true; }
;     __device__ __forceinline__ bool next(int i, Unit& u) const { if (i != 0) return false; u = one; return true; }
;     __device__ __forceinline__ bool get(long L, int& pm, int& pn) const {
;         if (L >= nwg) return false;
;         int wgid = (int)L; { const int q = nwg / NXCD, r = nwg % NXCD, xcd = wgid % NXCD, off = wgid / NXCD; wgid = (xcd < r ? xcd * (q + 1) : r * (q + 1) + (xcd - r) * q) + off; }
;         const int nig = WGM * nN, gid = wgid / nig, fm = gid * WGM, gsz = (nM - fm) < WGM ? (nM - fm) : WGM;
;         pm = fm + ((wgid % nig) % gsz); pn = (wgid % nig) / gsz; return true;
; template <class Epi, class Sched, bool ALIGN_EPI = false, bool SP2 = false>
; __device__ __forceinline__ void gemm_phase(PG8_LAS unsigned char* lds, const Gemm g, const Sched& S, const Epi& E, const int wv0) {
;     ...
;     if (!S.next(0, cur)) return;
.Lprio_skip_2:
	v_mov_b32 v0, s77
	ds_read_b64 v[0:1], v0 offset:168
	s_mov_b32 s36, s76
	s_mov_b32 s37, s33
	v_mov_b32_e32 v8, v204
	s_waitcnt lgkmcnt(0)
	v_readfirstlane_b32 s1, v1
	v_readfirstlane_b32 s0, v0
	v_mov_b32_e32 v0, v204
	s_cmpk_gt_i32 s37, 0x1ff
	v_readfirstlane_b32 s11, v8
	s_cbranch_scc1 .LBB0_1615
	s_ashr_i32 s38, s37, 31
	s_lshr_b32 s2, s38, 29
	s_add_i32 s6, s37, s2
	s_and_b32 s2, s6, -8
	s_sub_i32 s5, s37, s2
	s_cmp_gt_i32 s5, -1
	s_cbranch_scc0 .LBB0_1594
	s_lshl_b32 s4, s5, 6
	s_ashr_i32 s2, s6, 3
	s_cbranch_execz .LBB0_1595
	s_branch .LBB0_1596

; #define PG8_STAGE(bufoff, gbase, voff) do { _Pragma("unroll") for (int _i = 0; _i < 2; ++_i) \
;         __builtin_amdgcn_global_load_lds((const unsigned*)((const char*)(gbase) + (voff)[_i]), (PG8_LAS unsigned*)(lds + (bufoff) + ldsw + _i * 8192), 16, 0, 0); } while (0)
; #define PG8_LDA(dst, b, h) do { _Pragma("unroll") for (int m = 0; m < 4; ++m) _Pragma("unroll") for (int k = 0; k < 2; ++k) dst[m][k] = *(const PG8_LAS bf16x8*)(lds + PG8_SA(b, h) + aoff + m * 2048 + k * 1024); } while (0)
; #define PG8_LDB(dst, b, h) do { _Pragma("unroll") for (int n = 0; n < 2; ++n) _Pragma("unroll") for (int k = 0; k < 2; ++k) dst[n][k] = *(const PG8_LAS bf16x8*)(lds + PG8_SB(b, h) + boff + n * 2048 + k * 1024); } while (0)
; #define PG8_MMA(ai, bj, At, Bt) do { __builtin_amdgcn_s_setprio(1); _Pragma("unroll") for (int m = 0; m < 4; ++m) _Pragma("unroll") for (int n = 0; n < 2; ++n) _Pragma("unroll") for (int k = 0; k < 2; ++k) \
;         acc[ai][bj][m][n] = __builtin_amdgcn_mfma_f32_16x16x32_bf16(Bt[n][k], At[m][k], acc[ai][bj][m][n], 0, 0, 0); __builtin_amdgcn_s_setprio(0); } while (0)
; #define PG8_WAIT_V(n) asm volatile("s_waitcnt vmcnt(" #n ")" ::: "memory")
; #define PG8_WAIT_L(n) asm volatile("s_waitcnt lgkmcnt(" #n ")" ::: "memory")
; #define PG8_BAR __builtin_amdgcn_s_barrier()
; #define PG8_SCHED __builtin_amdgcn_sched_barrier(0)
; template <class Epi, class Sched, bool ALIGN_EPI = false, bool SP2 = false>
; __device__ __forceinline__ void gemm_phase(PG8_LAS unsigned char* lds, const Gemm g, const Sched& S, const Epi& E, const int wv0) {
;     ...
;             PG8_LDB(B0, 0, 0); PG8_LDB(B1, 0, 1); PG8_SCHED; PG8_LDA(At, 0, 0); PG8_STAGE(PG8_SA(1, 1), a1 + hstepA, voffA);
;             PG8_WAIT_V(8); PG8_WAIT_L(0); PG8_BAR; PG8_MMA(0, 0, At, B0); PG8_MMA(0, 1, At, B1); PG8_BAR; PG8_SCHED;
;             PG8_LDA(At, 0, 1); PG8_STAGE(PG8_SB(0, 0), b2, voffB); PG8_STAGE(PG8_SB(0, 1), b2 + hstepB, voffB); PG8_STAGE(PG8_SA(0, 0), a2, voffA);
;             PG8_WAIT_V(8); PG8_WAIT_L(0); PG8_BAR; PG8_MMA(1, 0, At, B0); PG8_MMA(1, 1, At, B1); PG8_BAR; PG8_SCHED;
.LBB0_1608:
	ds_read_b128 v[144:147], v155
	ds_read_b128 v[148:151], v155 offset:1024
	ds_read_b128 v[158:161], v155 offset:2048
	ds_read_b128 v[162:165], v155 offset:3072
	ds_read_b128 v[166:169], v156
	ds_read_b128 v[170:173], v156 offset:1024
	ds_read_b128 v[174:177], v156 offset:2048
	ds_read_b128 v[178:181], v156 offset:3072
	s_add_u32 s30, s28, 0xfff80080
	s_addc_u32 s31, s29, -1
	s_cmp_eq_u32 s56, 28
	s_cselect_b32 s35, s23, s31
	s_cselect_b32 s34, s22, s30
	s_cselect_b32 s31, s25, s21
	s_cselect_b32 s30, s24, s19
	v_lshl_add_u64 v[202:203], s[28:29], 0, v[138:139]
	s_add_i32 m0, s27, 0xc000
	ds_read_b128 v[182:185], v157
	ds_read_b128 v[186:189], v157 offset:1024
	ds_read_b128 v[190:193], v157 offset:2048
	ds_read_b128 v[194:197], v157 offset:3072
	ds_read_b128 v[198:201], v157 offset:4096
	ds_read_b128 v[206:209], v157 offset:5120
	ds_read_b128 v[210:213], v157 offset:6144
	ds_read_b128 v[214:217], v157 offset:7168
	global_load_lds_dwordx4 v[202:203], off
	v_lshl_add_u64 v[202:203], s[28:29], 0, v[136:137]
	s_add_i32 m0, s27, 0xe000
	s_nop 0
	global_load_lds_dwordx4 v[202:203], off
	s_waitcnt vmcnt(8)
	s_waitcnt lgkmcnt(0)
	s_barrier
	v_mfma_f32_16x16x32_bf16 v[124:127], v[144:147], v[182:185], v[124:127]
	v_mfma_f32_16x16x32_bf16 v[120:123], v[158:161], v[182:185], v[120:123]
	v_mfma_f32_16x16x32_bf16 v[116:119], v[144:147], v[190:193], v[116:119]
	v_mfma_f32_16x16x32_bf16 v[112:115], v[158:161], v[190:193], v[112:115]
	v_mfma_f32_16x16x32_bf16 v[92:95], v[144:147], v[198:201], v[92:95]
	v_mfma_f32_16x16x32_bf16 v[88:91], v[158:161], v[198:201], v[88:91]
	v_mfma_f32_16x16x32_bf16 v[84:87], v[144:147], v[210:213], v[84:87]
	v_mfma_f32_16x16x32_bf16 v[80:83], v[158:161], v[210:213], v[80:83]
	v_mfma_f32_16x16x32_bf16 v[124:127], v[148:151], v[186:189], v[124:127]
	v_mfma_f32_16x16x32_bf16 v[120:123], v[162:165], v[186:189], v[120:123]
	v_mfma_f32_16x16x32_bf16 v[116:119], v[148:151], v[194:197], v[116:119]
	v_mfma_f32_16x16x32_bf16 v[112:115], v[162:165], v[194:197], v[112:115]
	v_mfma_f32_16x16x32_bf16 v[92:95], v[148:151], v[206:209], v[92:95]
	v_mfma_f32_16x16x32_bf16 v[88:91], v[162:165], v[206:209], v[88:91]
	v_mfma_f32_16x16x32_bf16 v[84:87], v[148:151], v[214:217], v[84:87]
	v_mfma_f32_16x16x32_bf16 v[80:83], v[162:165], v[214:217], v[80:83]
	v_mfma_f32_16x16x32_bf16 v[108:111], v[166:169], v[182:185], v[108:111]
	v_mfma_f32_16x16x32_bf16 v[104:107], v[174:177], v[182:185], v[104:107]
	v_mfma_f32_16x16x32_bf16 v[100:103], v[166:169], v[190:193], v[100:103]
	v_mfma_f32_16x16x32_bf16 v[96:99], v[174:177], v[190:193], v[96:99]
	v_mfma_f32_16x16x32_bf16 v[76:79], v[166:169], v[198:201], v[76:79]
	v_mfma_f32_16x16x32_bf16 v[72:75], v[174:177], v[198:201], v[72:75]
	v_mfma_f32_16x16x32_bf16 v[68:71], v[166:169], v[210:213], v[68:71]
	v_mfma_f32_16x16x32_bf16 v[64:67], v[174:177], v[210:213], v[64:67]
	v_mfma_f32_16x16x32_bf16 v[108:111], v[170:173], v[186:189], v[108:111]
	v_mfma_f32_16x16x32_bf16 v[104:107], v[178:181], v[186:189], v[104:107]
	v_mfma_f32_16x16x32_bf16 v[100:103], v[170:173], v[194:197], v[100:103]
	v_mfma_f32_16x16x32_bf16 v[96:99], v[178:181], v[194:197], v[96:99]
	v_mfma_f32_16x16x32_bf16 v[76:79], v[170:173], v[206:209], v[76:79]
	v_mfma_f32_16x16x32_bf16 v[72:75], v[178:181], v[206:209], v[72:75]
	v_mfma_f32_16x16x32_bf16 v[68:71], v[170:173], v[214:217], v[68:71]
	v_mfma_f32_16x16x32_bf16 v[64:67], v[178:181], v[214:217], v[64:67]
	s_barrier
	s_add_i32 s57, s53, s45
	v_lshl_add_u64 v[202:203], s[30:31], 0, v[130:131]
	s_mov_b32 m0, s57
	ds_read_b128 v[182:185], v157 offset:16384
	ds_read_b128 v[186:189], v157 offset:17408
	ds_read_b128 v[190:193], v157 offset:18432
	ds_read_b128 v[194:197], v157 offset:19456
	ds_read_b128 v[198:201], v157 offset:20480
	ds_read_b128 v[206:209], v157 offset:21504
	ds_read_b128 v[210:213], v157 offset:22528
	ds_read_b128 v[214:217], v157 offset:23552
	global_load_lds_dwordx4 v[202:203], off
	s_add_i32 m0, s57, 0x2000
	s_add_u32 s58, s30, 0x80000
	v_lshl_add_u64 v[218:219], s[30:31], 0, v[134:135]
	s_addc_u32 s59, s31, 0
	s_add_i32 s57, s54, s45
	global_load_lds_dwordx4 v[218:219], off
	v_lshl_add_u64 v[220:221], s[58:59], 0, v[130:131]
	s_mov_b32 m0, s57
	v_lshl_add_u64 v[222:223], s[34:35], 0, v[132:133]
	global_load_lds_dwordx4 v[220:221], off
	v_lshl_add_u64 v[220:221], s[58:59], 0, v[134:135]
	s_add_i32 m0, s57, 0x2000
	s_nop 0
	global_load_lds_dwordx4 v[220:221], off
	v_lshl_add_u64 v[220:221], s[34:35], 0, v[128:129]
	s_mov_b32 m0, s27
	s_nop 0
	global_load_lds_dwordx4 v[220:221], off
	s_mov_b32 m0, s46
	s_nop 0
	global_load_lds_dwordx4 v[222:223], off
	s_waitcnt vmcnt(8)
	s_waitcnt lgkmcnt(0)
	s_barrier
; #define PG8_STAGE(bufoff, gbase, voff) do { _Pragma("unroll") for (int _i = 0; _i < 2; ++_i) \
;         __builtin_amdgcn_global_load_lds((const unsigned*)((const char*)(gbase) + (voff)[_i]), (PG8_LAS unsigned*)(lds + (bufoff) + ldsw + _i * 8192), 16, 0, 0); } while (0)
; #define PG8_LDA(dst, b, h) do { _Pragma("unroll") for (int m = 0; m < 4; ++m) _Pragma("unroll") for (int k = 0; k < 2; ++k) dst[m][k] = *(const PG8_LAS bf16x8*)(lds + PG8_SA(b, h) + aoff + m * 2048 + k * 1024); } while (0)
; #define PG8_LDB(dst, b, h) do { _Pragma("unroll") for (int n = 0; n < 2; ++n) _Pragma("unroll") for (int k = 0; k < 2; ++k) dst[n][k] = *(const PG8_LAS bf16x8*)(lds + PG8_SB(b, h) + boff + n * 2048 + k * 1024); } while (0)
; #define PG8_MMA(ai, bj, At, Bt) do { __builtin_amdgcn_s_setprio(1); _Pragma("unroll") for (int m = 0; m < 4; ++m) _Pragma("unroll") for (int n = 0; n < 2; ++n) _Pragma("unroll") for (int k = 0; k < 2; ++k) \
;         acc[ai][bj][m][n] = __builtin_amdgcn_mfma_f32_16x16x32_bf16(Bt[n][k], At[m][k], acc[ai][bj][m][n], 0, 0, 0); __builtin_amdgcn_s_setprio(0); } while (0)
; #define PG8_WAIT_V(n) asm volatile("s_waitcnt vmcnt(" #n ")" ::: "memory")
; #define PG8_WAIT_L(n) asm volatile("s_waitcnt lgkmcnt(" #n ")" ::: "memory")
; #define PG8_BAR __builtin_amdgcn_s_barrier()
; #define PG8_SCHED __builtin_amdgcn_sched_barrier(0)
; template <class Epi, class Sched, bool ALIGN_EPI = false, bool SP2 = false>
; __device__ __forceinline__ void gemm_phase(PG8_LAS unsigned char* lds, const Gemm g, const Sched& S, const Epi& E, const int wv0) {
;     ...
;             PG8_WAIT_V(8); PG8_WAIT_L(0); PG8_BAR; PG8_MMA(1, 0, At, B0); PG8_MMA(1, 1, At, B1); PG8_BAR; PG8_SCHED;
;             PG8_LDB(B0, 1, 0); PG8_LDB(B1, 1, 1); PG8_SCHED; PG8_LDA(At, 1, 0); PG8_STAGE(PG8_SA(0, 1), a2 + hstepA, voffA);
;             PG8_WAIT_V(8); PG8_WAIT_L(0); PG8_BAR; PG8_MMA(0, 0, At, B0); PG8_MMA(0, 1, At, B1); PG8_BAR; PG8_SCHED;
	v_mfma_f32_16x16x32_bf16 v[60:63], v[144:147], v[182:185], v[60:63]
	v_mfma_f32_16x16x32_bf16 v[56:59], v[158:161], v[182:185], v[56:59]
	v_mfma_f32_16x16x32_bf16 v[52:55], v[144:147], v[190:193], v[52:55]
	v_mfma_f32_16x16x32_bf16 v[48:51], v[158:161], v[190:193], v[48:51]
	v_mfma_f32_16x16x32_bf16 v[28:31], v[144:147], v[198:201], v[28:31]
	v_mfma_f32_16x16x32_bf16 v[24:27], v[158:161], v[198:201], v[24:27]
	v_mfma_f32_16x16x32_bf16 v[20:23], v[144:147], v[210:213], v[20:23]
	v_mfma_f32_16x16x32_bf16 v[16:19], v[158:161], v[210:213], v[16:19]
	v_mfma_f32_16x16x32_bf16 v[60:63], v[148:151], v[186:189], v[60:63]
	v_mfma_f32_16x16x32_bf16 v[56:59], v[162:165], v[186:189], v[56:59]
	v_mfma_f32_16x16x32_bf16 v[52:55], v[148:151], v[194:197], v[52:55]
	v_mfma_f32_16x16x32_bf16 v[48:51], v[162:165], v[194:197], v[48:51]
	v_mfma_f32_16x16x32_bf16 v[28:31], v[148:151], v[206:209], v[28:31]
	v_mfma_f32_16x16x32_bf16 v[24:27], v[162:165], v[206:209], v[24:27]
	v_mfma_f32_16x16x32_bf16 v[20:23], v[148:151], v[214:217], v[20:23]
	v_mfma_f32_16x16x32_bf16 v[16:19], v[162:165], v[214:217], v[16:19]
	v_mfma_f32_16x16x32_bf16 v[44:47], v[166:169], v[182:185], v[44:47]
	v_mfma_f32_16x16x32_bf16 v[40:43], v[174:177], v[182:185], v[40:43]
	v_mfma_f32_16x16x32_bf16 v[36:39], v[166:169], v[190:193], v[36:39]
	v_mfma_f32_16x16x32_bf16 v[32:35], v[174:177], v[190:193], v[32:35]
	v_mfma_f32_16x16x32_bf16 v[12:15], v[166:169], v[198:201], v[12:15]
	v_mfma_f32_16x16x32_bf16 v[8:11], v[174:177], v[198:201], v[8:11]
	v_mfma_f32_16x16x32_bf16 v[4:7], v[166:169], v[210:213], v[4:7]
	v_mfma_f32_16x16x32_bf16 v[0:3], v[174:177], v[210:213], v[0:3]
	v_mfma_f32_16x16x32_bf16 v[44:47], v[170:173], v[186:189], v[44:47]
	v_mfma_f32_16x16x32_bf16 v[40:43], v[178:181], v[186:189], v[40:43]
	v_mfma_f32_16x16x32_bf16 v[36:39], v[170:173], v[194:197], v[36:39]
	v_mfma_f32_16x16x32_bf16 v[32:35], v[178:181], v[194:197], v[32:35]
	v_mfma_f32_16x16x32_bf16 v[12:15], v[170:173], v[206:209], v[12:15]
	v_mfma_f32_16x16x32_bf16 v[8:11], v[178:181], v[206:209], v[8:11]
	v_mfma_f32_16x16x32_bf16 v[4:7], v[170:173], v[214:217], v[4:7]
	v_mfma_f32_16x16x32_bf16 v[0:3], v[178:181], v[214:217], v[0:3]
	s_barrier
	s_add_i32 s57, 0, 0x18000
	s_add_i32 s58, 0, 0x1c000
	v_add_u32_e32 v162, s57, v153
	v_add_u32_e32 v178, s58, v153
	ds_read_b128 v[144:147], v162
	ds_read_b128 v[148:151], v162 offset:1024
	ds_read_b128 v[158:161], v162 offset:2048
	ds_read_b128 v[162:165], v162 offset:3072
	ds_read_b128 v[166:169], v178
	ds_read_b128 v[170:173], v178 offset:1024
	ds_read_b128 v[174:177], v178 offset:2048
	ds_read_b128 v[178:181], v178 offset:3072
	s_add_u32 s34, s34, 0x80000
	s_addc_u32 s35, s35, 0
	s_mov_b32 m0, s47
	v_lshl_add_u64 v[224:225], s[34:35], 0, v[128:129]
	ds_read_b128 v[182:185], v157 offset:32768
	ds_read_b128 v[186:189], v157 offset:33792
	ds_read_b128 v[190:193], v157 offset:34816
	ds_read_b128 v[194:197], v157 offset:35840
	ds_read_b128 v[198:201], v157 offset:36864
	ds_read_b128 v[206:209], v157 offset:37888
	ds_read_b128 v[210:213], v157 offset:38912
	ds_read_b128 v[214:217], v157 offset:39936
	global_load_lds_dwordx4 v[224:225], off
	v_lshl_add_u64 v[224:225], s[34:35], 0, v[132:133]
	s_mov_b32 m0, s48
	s_nop 0
	global_load_lds_dwordx4 v[224:225], off
	s_waitcnt vmcnt(8)
	s_waitcnt lgkmcnt(0)
	s_barrier
	v_mfma_f32_16x16x32_bf16 v[124:127], v[144:147], v[182:185], v[124:127]
	v_mfma_f32_16x16x32_bf16 v[120:123], v[158:161], v[182:185], v[120:123]
	v_mfma_f32_16x16x32_bf16 v[116:119], v[144:147], v[190:193], v[116:119]
	v_mfma_f32_16x16x32_bf16 v[112:115], v[158:161], v[190:193], v[112:115]
	v_mfma_f32_16x16x32_bf16 v[92:95], v[144:147], v[198:201], v[92:95]
	v_mfma_f32_16x16x32_bf16 v[88:91], v[158:161], v[198:201], v[88:91]
	v_mfma_f32_16x16x32_bf16 v[84:87], v[144:147], v[210:213], v[84:87]
	v_mfma_f32_16x16x32_bf16 v[80:83], v[158:161], v[210:213], v[80:83]
	v_mfma_f32_16x16x32_bf16 v[124:127], v[148:151], v[186:189], v[124:127]
	v_mfma_f32_16x16x32_bf16 v[120:123], v[162:165], v[186:189], v[120:123]
	v_mfma_f32_16x16x32_bf16 v[116:119], v[148:151], v[194:197], v[116:119]
	v_mfma_f32_16x16x32_bf16 v[112:115], v[162:165], v[194:197], v[112:115]
	v_mfma_f32_16x16x32_bf16 v[92:95], v[148:151], v[206:209], v[92:95]
	v_mfma_f32_16x16x32_bf16 v[88:91], v[162:165], v[206:209], v[88:91]
	v_mfma_f32_16x16x32_bf16 v[84:87], v[148:151], v[214:217], v[84:87]
	v_mfma_f32_16x16x32_bf16 v[80:83], v[162:165], v[214:217], v[80:83]
	v_mfma_f32_16x16x32_bf16 v[108:111], v[166:169], v[182:185], v[108:111]
	v_mfma_f32_16x16x32_bf16 v[104:107], v[174:177], v[182:185], v[104:107]
	v_mfma_f32_16x16x32_bf16 v[100:103], v[166:169], v[190:193], v[100:103]
	v_mfma_f32_16x16x32_bf16 v[96:99], v[174:177], v[190:193], v[96:99]
	v_mfma_f32_16x16x32_bf16 v[76:79], v[166:169], v[198:201], v[76:79]
	v_mfma_f32_16x16x32_bf16 v[72:75], v[174:177], v[198:201], v[72:75]
	v_mfma_f32_16x16x32_bf16 v[68:71], v[166:169], v[210:213], v[68:71]
	v_mfma_f32_16x16x32_bf16 v[64:67], v[174:177], v[210:213], v[64:67]
	v_mfma_f32_16x16x32_bf16 v[108:111], v[170:173], v[186:189], v[108:111]
	v_mfma_f32_16x16x32_bf16 v[104:107], v[178:181], v[186:189], v[104:107]
	v_mfma_f32_16x16x32_bf16 v[100:103], v[170:173], v[194:197], v[100:103]
	v_mfma_f32_16x16x32_bf16 v[96:99], v[178:181], v[194:197], v[96:99]
	v_mfma_f32_16x16x32_bf16 v[76:79], v[170:173], v[206:209], v[76:79]
	v_mfma_f32_16x16x32_bf16 v[72:75], v[178:181], v[206:209], v[72:75]
	v_mfma_f32_16x16x32_bf16 v[68:71], v[170:173], v[214:217], v[68:71]
	v_mfma_f32_16x16x32_bf16 v[64:67], v[178:181], v[214:217], v[64:67]
	s_barrier
; #define PG8_STAGE(bufoff, gbase, voff) do { _Pragma("unroll") for (int _i = 0; _i < 2; ++_i) \
;         __builtin_amdgcn_global_load_lds((const unsigned*)((const char*)(gbase) + (voff)[_i]), (PG8_LAS unsigned*)(lds + (bufoff) + ldsw + _i * 8192), 16, 0, 0); } while (0)
; #define PG8_LDA(dst, b, h) do { _Pragma("unroll") for (int m = 0; m < 4; ++m) _Pragma("unroll") for (int k = 0; k < 2; ++k) dst[m][k] = *(const PG8_LAS bf16x8*)(lds + PG8_SA(b, h) + aoff + m * 2048 + k * 1024); } while (0)
; #define PG8_MMA(ai, bj, At, Bt) do { __builtin_amdgcn_s_setprio(1); _Pragma("unroll") for (int m = 0; m < 4; ++m) _Pragma("unroll") for (int n = 0; n < 2; ++n) _Pragma("unroll") for (int k = 0; k < 2; ++k) \
;         acc[ai][bj][m][n] = __builtin_amdgcn_mfma_f32_16x16x32_bf16(Bt[n][k], At[m][k], acc[ai][bj][m][n], 0, 0, 0); __builtin_amdgcn_s_setprio(0); } while (0)
; #define PG8_WAIT_V(n) asm volatile("s_waitcnt vmcnt(" #n ")" ::: "memory")
; #define PG8_WAIT_L(n) asm volatile("s_waitcnt lgkmcnt(" #n ")" ::: "memory")
; #define PG8_BAR __builtin_amdgcn_s_barrier()
; #define PG8_SCHED __builtin_amdgcn_sched_barrier(0)
; template <class Epi, class Sched, bool ALIGN_EPI = false, bool SP2 = false>
; __device__ __forceinline__ void gemm_phase(PG8_LAS unsigned char* lds, const Gemm g, const Sched& S, const Epi& E, const int wv0) {
;     ...
;             PG8_LDA(At, 1, 1); PG8_STAGE(PG8_SB(1, 0), b3, voffB); PG8_STAGE(PG8_SB(1, 1), b3 + hstepB, voffB); PG8_STAGE(PG8_SA(1, 0), a3, voffA);
;             PG8_WAIT_V(8); PG8_WAIT_L(0); PG8_BAR; PG8_MMA(1, 0, At, B0); PG8_MMA(1, 1, At, B1); PG8_BAR; PG8_SCHED;
	s_add_i32 s34, s57, s45
	v_lshl_add_u64 v[202:203], v[202:203], 0, s[8:9]
	s_mov_b32 m0, s34
	ds_read_b128 v[182:185], v157 offset:49152
	ds_read_b128 v[186:189], v157 offset:50176
	ds_read_b128 v[190:193], v157 offset:51200
	ds_read_b128 v[194:197], v157 offset:52224
	ds_read_b128 v[198:201], v157 offset:53248
	ds_read_b128 v[206:209], v157 offset:54272
	ds_read_b128 v[210:213], v157 offset:55296
	ds_read_b128 v[214:217], v157 offset:56320
	global_load_lds_dwordx4 v[202:203], off
	s_add_i32 m0, s34, 0x2000
	s_add_u32 s30, s30, 0x80080
	v_lshl_add_u64 v[202:203], v[218:219], 0, s[8:9]
	s_addc_u32 s31, s31, 0
	s_add_i32 s34, s58, s45
	global_load_lds_dwordx4 v[202:203], off
	v_lshl_add_u64 v[202:203], s[30:31], 0, v[130:131]
	s_mov_b32 m0, s34
	s_nop 0
	global_load_lds_dwordx4 v[202:203], off
	v_lshl_add_u64 v[202:203], s[30:31], 0, v[134:135]
	s_add_i32 m0, s34, 0x2000
	s_nop 0
	global_load_lds_dwordx4 v[202:203], off
	v_lshl_add_u64 v[202:203], v[220:221], 0, s[8:9]
	s_mov_b32 m0, s50
	s_nop 0
	global_load_lds_dwordx4 v[202:203], off
	v_lshl_add_u64 v[202:203], v[222:223], 0, s[8:9]
	s_mov_b32 m0, s51
	s_nop 0
	global_load_lds_dwordx4 v[202:203], off
	s_waitcnt vmcnt(8)
	s_waitcnt lgkmcnt(0)
	s_barrier
	v_mfma_f32_16x16x32_bf16 v[60:63], v[144:147], v[182:185], v[60:63]
	v_mfma_f32_16x16x32_bf16 v[56:59], v[158:161], v[182:185], v[56:59]
	v_mfma_f32_16x16x32_bf16 v[52:55], v[144:147], v[190:193], v[52:55]
	v_mfma_f32_16x16x32_bf16 v[48:51], v[158:161], v[190:193], v[48:51]
	v_mfma_f32_16x16x32_bf16 v[28:31], v[144:147], v[198:201], v[28:31]
	v_mfma_f32_16x16x32_bf16 v[24:27], v[158:161], v[198:201], v[24:27]
	v_mfma_f32_16x16x32_bf16 v[20:23], v[144:147], v[210:213], v[20:23]
	v_mfma_f32_16x16x32_bf16 v[16:19], v[158:161], v[210:213], v[16:19]
	v_mfma_f32_16x16x32_bf16 v[60:63], v[148:151], v[186:189], v[60:63]
	v_mfma_f32_16x16x32_bf16 v[56:59], v[162:165], v[186:189], v[56:59]
	v_mfma_f32_16x16x32_bf16 v[52:55], v[148:151], v[194:197], v[52:55]
	v_mfma_f32_16x16x32_bf16 v[48:51], v[162:165], v[194:197], v[48:51]
	v_mfma_f32_16x16x32_bf16 v[28:31], v[148:151], v[206:209], v[28:31]
	v_mfma_f32_16x16x32_bf16 v[24:27], v[162:165], v[206:209], v[24:27]
	v_mfma_f32_16x16x32_bf16 v[20:23], v[148:151], v[214:217], v[20:23]
	v_mfma_f32_16x16x32_bf16 v[16:19], v[162:165], v[214:217], v[16:19]
	v_mfma_f32_16x16x32_bf16 v[44:47], v[166:169], v[182:185], v[44:47]
	v_mfma_f32_16x16x32_bf16 v[40:43], v[174:177], v[182:185], v[40:43]
	v_mfma_f32_16x16x32_bf16 v[36:39], v[166:169], v[190:193], v[36:39]
	v_mfma_f32_16x16x32_bf16 v[32:35], v[174:177], v[190:193], v[32:35]
	v_mfma_f32_16x16x32_bf16 v[12:15], v[166:169], v[198:201], v[12:15]
	v_mfma_f32_16x16x32_bf16 v[8:11], v[174:177], v[198:201], v[8:11]
	v_mfma_f32_16x16x32_bf16 v[4:7], v[166:169], v[210:213], v[4:7]
	v_mfma_f32_16x16x32_bf16 v[0:3], v[174:177], v[210:213], v[0:3]
	v_mfma_f32_16x16x32_bf16 v[44:47], v[170:173], v[186:189], v[44:47]
	v_mfma_f32_16x16x32_bf16 v[40:43], v[178:181], v[186:189], v[40:43]
	v_mfma_f32_16x16x32_bf16 v[36:39], v[170:173], v[194:197], v[36:39]
	v_mfma_f32_16x16x32_bf16 v[32:35], v[178:181], v[194:197], v[32:35]
	v_mfma_f32_16x16x32_bf16 v[12:15], v[170:173], v[206:209], v[12:15]
	v_mfma_f32_16x16x32_bf16 v[8:11], v[178:181], v[206:209], v[8:11]
	v_mfma_f32_16x16x32_bf16 v[4:7], v[170:173], v[214:217], v[4:7]
	v_mfma_f32_16x16x32_bf16 v[0:3], v[178:181], v[214:217], v[0:3]
	s_barrier
	s_add_i32 s56, s56, 2
	s_add_u32 s19, s19, 0x100
	s_addc_u32 s21, s21, 0
	s_add_u32 s28, s28, 0x100
	s_addc_u32 s29, s29, 0
	s_cmp_gt_u32 s56, 29
	s_cbranch_scc0 .LBB0_1608
	s_and_b64 vcc, exec, s[10:11]
	s_cbranch_vccz .LBB0_1611
	s_barrier

; #define TID() (wv0 * 64 + (int)__builtin_amdgcn_mbcnt_hi(~0u, __builtin_amdgcn_mbcnt_lo(~0u, 0u)))
; __device__ __forceinline__ int opaque(int x) { asm volatile("" : "+v"(x)); return x; }
; __device__ __forceinline__ unsigned xb_add(unsigned* p, unsigned v) { return __hip_atomic_fetch_add(p, v, __ATOMIC_RELAXED, __HIP_MEMORY_SCOPE_AGENT); }
; __device__ __forceinline__ void xcd_barrier(const XcdBarrier& b, const int wv0) {
;     const bool TID0 = (opaque(TID()) == 0);
;     asm volatile("s_waitcnt vmcnt(0)" ::: "memory");
;     __syncthreads();
;     if (TID0) {
;         unsigned* bar = b.bar;
;         __builtin_amdgcn_s_waitcnt(0);
;         unsigned nloc = b.st[0], nx = b.st[1];
;         if (nloc == 0u) { xcd_barrier_complete(bar, b.x, nloc, nx); b.st[0] = nloc; b.st[1] = nx; }
;         const unsigned old = xb_add(&bar[XB_XSUB(b.x)], 1u);
.LBB0_1615:
	s_setprio 0
	v_mov_b32 v0, s77
	ds_read_b64 v[2:3], v0 offset:168
	v_mov_b32_e32 v0, v204
	s_getreg_b32 s4, hwreg(HW_REG_XCC_ID, 0, 4)
	v_mov_b32 v1, s78
	s_waitcnt vmcnt(0)
	s_waitcnt lgkmcnt(0)
	v_readfirstlane_b32 s3, v3
	v_readfirstlane_b32 s2, v2
	v_cmp_eq_u32_e32 vcc, 0, v0
	s_barrier
	s_and_saveexec_b64 s[0:1], vcc
	s_cbranch_execz .LBB0_1667
	s_waitcnt vmcnt(0) expcnt(0) lgkmcnt(0)
	ds_read_b32 v2, v1
	ds_read_b32 v0, v1 offset:4
	s_and_b32 s40, s4, 15
	s_waitcnt lgkmcnt(1)
	v_cmp_eq_u32_e32 vcc, 0, v2
	s_and_saveexec_b64 s[4:5], vcc
	s_cbranch_execz .LBB0_1631
	s_load_dword s6, s[94:95], 0x14
	s_mov_b32 s41, 1
	v_mov_b32_e32 v17, 0
	s_waitcnt lgkmcnt(0)
	s_lshr_b32 s8, s6, 16
	s_and_b32 s6, s6, 0xffff
	s_cmp_lg_u32 s6, 0
	s_cselect_b64 s[6:7], -1, 0
	s_cmp_lg_u64 s[6:7], 0
	s_addc_u32 s6, s42, 0
	s_cmp_lg_u32 s8, 0
	s_mul_i32 s52, s6, s76
	s_cselect_b64 s[6:7], -1, 0
	s_cmp_lg_u64 s[6:7], 0
	s_addc_u32 s6, s43, 0
	s_mul_i32 s52, s52, s6
	s_add_u32 s6, s2, 0x2e400200
	s_addc_u32 s7, s3, 0
	s_add_u32 s8, s2, 0x2e400400
	s_addc_u32 s9, s3, 0
	s_add_u32 s10, s2, 0x2e400500
	s_addc_u32 s11, s3, 0
	s_add_u32 s12, s2, 0x2e400600
	s_addc_u32 s13, s3, 0
	s_add_u32 s14, s2, 0x2e400700
	s_addc_u32 s15, s3, 0
	s_add_u32 s16, s2, 0x2e400800
	s_addc_u32 s17, s3, 0
	s_add_u32 s18, s2, 0x2e400900
	s_addc_u32 s19, s3, 0
	s_add_u32 s20, s2, 0x2e400a00
	s_addc_u32 s21, s3, 0
	s_add_u32 s22, s2, 0x2e400b00
	s_addc_u32 s23, s3, 0
	s_add_u32 s24, s2, 0x2e400c00
	s_addc_u32 s25, s3, 0
	s_add_u32 s26, s2, 0x2e400d00
	s_addc_u32 s27, s3, 0
	s_add_u32 s28, s2, 0x2e400e00
	s_addc_u32 s29, s3, 0
	s_add_u32 s30, s2, 0x2e400f00
	s_addc_u32 s31, s3, 0
	s_add_u32 s34, s2, 0x2e401000
	s_addc_u32 s35, s3, 0
	s_add_u32 s36, s2, 0x2e401100
	s_addc_u32 s37, s3, 0
	s_add_u32 s38, s2, 0x2e401200
	s_addc_u32 s39, s3, 0
	s_add_u32 s44, s2, 0x2e401300
	s_addc_u32 s45, s3, 0
	s_branch .LBB0_1619

; #define TID() (wv0 * 64 + (int)__builtin_amdgcn_mbcnt_hi(~0u, __builtin_amdgcn_mbcnt_lo(~0u, 0u)))
; __device__ __forceinline__ int opaque(int x) { asm volatile("" : "+v"(x)); return x; }
; #define PG8_WAIT_V(n) asm volatile("s_waitcnt vmcnt(" #n ")" ::: "memory")
; #define PG8_BAR __builtin_amdgcn_s_barrier()
; __device__ __forceinline__ unsigned xb_add(unsigned* p, unsigned v) { return __hip_atomic_fetch_add(p, v, __ATOMIC_RELAXED, __HIP_MEMORY_SCOPE_AGENT); }
; template <class Epi, class Sched, bool ALIGN_EPI = false, bool SP2 = false>
; __device__ __forceinline__ void gemm_phase(PG8_LAS unsigned char* lds, const Gemm g, const Sched& S, const Epi& E, const int wv0) {
;     ...
;     PG8_WAIT_V(0);
;     if constexpr (!ALIGN_EPI) { if (wr == 0) PG8_BAR; }
;     PG8_BAR;
; __device__ __forceinline__ void xcd_barrier(const XcdBarrier& b, const int wv0) {
;     const bool TID0 = (opaque(TID()) == 0);
;     asm volatile("s_waitcnt vmcnt(0)" ::: "memory");
;     __syncthreads();
;     if (TID0) {
;         unsigned* bar = b.bar;
;         __builtin_amdgcn_s_waitcnt(0);
;         unsigned nloc = b.st[0], nx = b.st[1];
;         if (nloc == 0u) { xcd_barrier_complete(bar, b.x, nloc, nx); b.st[0] = nloc; b.st[1] = nx; }
;         const unsigned old = xb_add(&bar[XB_XSUB(b.x)], 1u);
.LBB0_1738:
	s_waitcnt vmcnt(0)
	s_barrier
	s_setprio 0
	v_mov_b32 v0, s77
	ds_read_b64 v[0:1], v0 offset:168
	s_getreg_b32 s4, hwreg(HW_REG_XCC_ID, 0, 4)
	s_waitcnt lgkmcnt(0)
	v_readfirstlane_b32 s2, v0
	v_mov_b32_e32 v0, v204
	v_readfirstlane_b32 s3, v1
	v_mov_b32 v1, s78
	s_waitcnt vmcnt(0)
	s_nop 0
	v_cmp_eq_u32_e32 vcc, 0, v0
	s_barrier
	s_and_saveexec_b64 s[0:1], vcc
	s_xor_b64 s[0:1], exec, s[0:1]
	s_cbranch_execz .LBB0_1791
	s_waitcnt vmcnt(0) expcnt(0) lgkmcnt(0)
	ds_read_b32 v2, v1
	ds_read_b32 v0, v1 offset:4
	s_and_b32 s48, s4, 15
	s_waitcnt lgkmcnt(1)
	v_cmp_eq_u32_e32 vcc, 0, v2
	s_and_saveexec_b64 s[4:5], vcc
	s_cbranch_execz .LBB0_1754
	s_add_u32 s6, s2, 0x2e400200
	s_addc_u32 s7, s3, 0
	s_add_u32 s8, s2, 0x2e400400
	s_addc_u32 s9, s3, 0
	s_add_u32 s10, s2, 0x2e400500
	s_addc_u32 s11, s3, 0
	s_add_u32 s12, s2, 0x2e400600
	s_addc_u32 s13, s3, 0
	s_add_u32 s14, s2, 0x2e400700
	s_addc_u32 s15, s3, 0
	s_add_u32 s16, s2, 0x2e400800
	s_addc_u32 s17, s3, 0
	s_add_u32 s18, s2, 0x2e400900
	s_addc_u32 s19, s3, 0
	s_add_u32 s20, s2, 0x2e400a00
	s_addc_u32 s21, s3, 0
	s_add_u32 s22, s2, 0x2e400b00
	s_addc_u32 s23, s3, 0
	s_add_u32 s24, s2, 0x2e400c00
	s_addc_u32 s25, s3, 0
	s_add_u32 s26, s2, 0x2e400d00
	s_addc_u32 s27, s3, 0
	s_add_u32 s28, s2, 0x2e400e00
	s_addc_u32 s29, s3, 0
	s_add_u32 s30, s2, 0x2e400f00
	s_addc_u32 s31, s3, 0
	s_add_u32 s34, s2, 0x2e401000
	s_addc_u32 s35, s3, 0
	s_add_u32 s36, s2, 0x2e401100
	s_addc_u32 s37, s3, 0
	s_add_u32 s38, s2, 0x2e401200
	s_addc_u32 s39, s3, 0
	s_mul_i32 s49, s43, s76
	s_add_u32 s40, s2, 0x2e401300
	s_mul_i32 s49, s49, s42
	s_addc_u32 s41, s3, 0
	s_mov_b32 s50, 1
	v_mov_b32_e32 v17, 0
	s_branch .LBB0_1742

;     __device__ __forceinline__ float* out() const { return (float*)(__attribute__((address_space(1))) float*)get(20); }
;     __device__ __forceinline__ unsigned char* ws() const { return (unsigned char*)(__attribute__((address_space(1))) unsigned char*)get(21); }
;     __device__ __forceinline__ bool get(long L, int& pm, int& pn) const {
;         if (L >= nwg) return false;
;         int wgid = (int)L; { const int q = nwg / NXCD, r = nwg % NXCD, xcd = wgid % NXCD, off = wgid / NXCD; wgid = (xcd < r ? xcd * (q + 1) : r * (q + 1) + (xcd - r) * q) + off; }
;         const int nig = WGM * nN, gid = wgid / nig, fm = gid * WGM, gsz = (nM - fm) < WGM ? (nM - fm) : WGM;
;         pm = fm + ((wgid % nig) % gsz); pn = (wgid % nig) / gsz; return true;
; template <int l>
; __device__ __forceinline__ void layer_body(const Ptrs& A, LAS unsigned char* lds, unsigned char* lds_raw, const int wv0) {
;     ...
;         if (PH(10)) {
;             pg8::Gemm g{DFF, DFF, DFF}; pg8::SchedGrid S; S.to.init(T / 256, DM / 256); S.G = G; S.c = c; S.A = (const char*)(ws + WS_GATES); S.B = (const char*)(ws + WS_WDN); S.ta = (size_t)256 * DFF * 2; S.tb = (size_t)256 * DFF * 2;
;             if constexpr (l + 1 < DEPTH) { pg8::EpiRes<true, true> E{(const void*)(ws + WS_X), (void*)(ws + WS_X)}; pg8::gemm_phase<pg8::EpiRes<true, true>, pg8::SchedGrid, true, true>(lds, g, S, E, wv0); }
;             else { pg8::EpiRes<true, false> E{(const void*)(ws + WS_X), (void*)A.out()}; pg8::gemm_phase<pg8::EpiRes<true, false>, pg8::SchedGrid, true, true>(lds, g, S, E, wv0); }
.Lprio_skip_0:
	v_mov_b32 v0, s77
	ds_read_b64 v[0:1], v0 offset:168
	s_waitcnt lgkmcnt(0)
	v_readfirstlane_b32 s1, v1
	v_readfirstlane_b32 s0, v0
	v_mov_b32_e32 v0, v204
	s_cmpk_gt_i32 s33, 0x1ff
	v_mov_b32 v0, s77
	ds_read_b64 v[0:1], v0 offset:160
	s_waitcnt lgkmcnt(0)
	v_readfirstlane_b32 s3, v1
	v_readfirstlane_b32 s2, v0
	v_readfirstlane_b32 s10, v204
	s_cbranch_scc1 .LBB0_1815
	s_ashr_i32 s24, s33, 31
	s_lshr_b32 s4, s24, 29
	s_add_i32 s8, s33, s4
	s_and_b32 s4, s8, -8
	s_sub_i32 s7, s33, s4
	s_cmp_gt_i32 s7, -1
	s_cbranch_scc0 .LBB0_1794
	s_lshl_b32 s6, s7, 6
	s_ashr_i32 s4, s8, 3
	s_cbranch_execz .LBB0_1795
	s_branch .LBB0_1796

; #define PG8_STAGE(bufoff, gbase, voff) do { _Pragma("unroll") for (int _i = 0; _i < 2; ++_i) \
;         __builtin_amdgcn_global_load_lds((const unsigned*)((const char*)(gbase) + (voff)[_i]), (PG8_LAS unsigned*)(lds + (bufoff) + ldsw + _i * 8192), 16, 0, 0); } while (0)
; #define PG8_LDA(dst, b, h) do { _Pragma("unroll") for (int m = 0; m < 4; ++m) _Pragma("unroll") for (int k = 0; k < 2; ++k) dst[m][k] = *(const PG8_LAS bf16x8*)(lds + PG8_SA(b, h) + aoff + m * 2048 + k * 1024); } while (0)
; #define PG8_LDB(dst, b, h) do { _Pragma("unroll") for (int n = 0; n < 2; ++n) _Pragma("unroll") for (int k = 0; k < 2; ++k) dst[n][k] = *(const PG8_LAS bf16x8*)(lds + PG8_SB(b, h) + boff + n * 2048 + k * 1024); } while (0)
; #define PG8_MMA(ai, bj, At, Bt) do { __builtin_amdgcn_s_setprio(1); _Pragma("unroll") for (int m = 0; m < 4; ++m) _Pragma("unroll") for (int n = 0; n < 2; ++n) _Pragma("unroll") for (int k = 0; k < 2; ++k) \
;         acc[ai][bj][m][n] = __builtin_amdgcn_mfma_f32_16x16x32_bf16(Bt[n][k], At[m][k], acc[ai][bj][m][n], 0, 0, 0); __builtin_amdgcn_s_setprio(0); } while (0)
; #define PG8_WAIT_V(n) asm volatile("s_waitcnt vmcnt(" #n ")" ::: "memory")
; #define PG8_WAIT_L(n) asm volatile("s_waitcnt lgkmcnt(" #n ")" ::: "memory")
; #define PG8_BAR __builtin_amdgcn_s_barrier()
; #define PG8_SCHED __builtin_amdgcn_sched_barrier(0)
; template <class Epi, class Sched, bool ALIGN_EPI = false, bool SP2 = false>
; __device__ __forceinline__ void gemm_phase(PG8_LAS unsigned char* lds, const Gemm g, const Sched& S, const Epi& E, const int wv0) {
;     ...
;             PG8_LDB(B0, 0, 0); PG8_LDB(B1, 0, 1); PG8_SCHED; PG8_LDA(At, 0, 0); PG8_STAGE(PG8_SA(1, 1), a1 + hstepA, voffA);
;             PG8_WAIT_V(8); PG8_WAIT_L(0); PG8_BAR; PG8_MMA(0, 0, At, B0); PG8_MMA(0, 1, At, B1); PG8_BAR; PG8_SCHED;
;             PG8_LDA(At, 0, 1); PG8_STAGE(PG8_SB(0, 0), b2, voffB); PG8_STAGE(PG8_SB(0, 1), b2 + hstepB, voffB); PG8_STAGE(PG8_SA(0, 0), a2, voffA);
;             PG8_WAIT_V(8); PG8_WAIT_L(0); PG8_BAR; PG8_MMA(1, 0, At, B0); PG8_MMA(1, 1, At, B1); PG8_BAR; PG8_SCHED;
.LBB0_1808:
	ds_read_b128 v[144:147], v153
	ds_read_b128 v[156:159], v153 offset:1024
	ds_read_b128 v[160:163], v153 offset:2048
	ds_read_b128 v[164:167], v153 offset:3072
	ds_read_b128 v[168:171], v154
	ds_read_b128 v[172:175], v154 offset:1024
	ds_read_b128 v[176:179], v154 offset:2048
	ds_read_b128 v[180:183], v154 offset:3072
	s_add_u32 s18, s16, 0x100
	s_addc_u32 s19, s17, 0
	s_cmpk_eq_i32 s48, 0x54
	s_cselect_b32 s23, s13, s19
	s_cselect_b32 s22, s12, s18
	s_cselect_b32 s21, s15, s47
	s_cselect_b32 s20, s14, s46
	v_lshl_add_u64 v[148:149], s[16:17], 0, v[138:139]
	s_add_i32 m0, s30, 0xc000
	ds_read_b128 v[184:187], v155
	ds_read_b128 v[188:191], v155 offset:1024
	ds_read_b128 v[192:195], v155 offset:2048
	ds_read_b128 v[196:199], v155 offset:3072
	ds_read_b128 v[200:203], v155 offset:4096
	ds_read_b128 v[204:207], v155 offset:5120
	ds_read_b128 v[208:211], v155 offset:6144
	ds_read_b128 v[212:215], v155 offset:7168
	global_load_lds_dwordx4 v[148:149], off
	v_lshl_add_u64 v[148:149], s[16:17], 0, v[136:137]
	s_add_i32 m0, s30, 0xe000
	s_nop 0
	global_load_lds_dwordx4 v[148:149], off
	s_waitcnt vmcnt(8)
	s_waitcnt lgkmcnt(0)
	s_barrier
	v_mfma_f32_16x16x32_bf16 v[124:127], v[144:147], v[184:187], v[124:127]
	v_mfma_f32_16x16x32_bf16 v[120:123], v[160:163], v[184:187], v[120:123]
	v_mfma_f32_16x16x32_bf16 v[116:119], v[144:147], v[192:195], v[116:119]
	v_mfma_f32_16x16x32_bf16 v[112:115], v[160:163], v[192:195], v[112:115]
	v_mfma_f32_16x16x32_bf16 v[92:95], v[144:147], v[200:203], v[92:95]
	v_mfma_f32_16x16x32_bf16 v[88:91], v[160:163], v[200:203], v[88:91]
	v_mfma_f32_16x16x32_bf16 v[84:87], v[144:147], v[208:211], v[84:87]
	v_mfma_f32_16x16x32_bf16 v[80:83], v[160:163], v[208:211], v[80:83]
	v_mfma_f32_16x16x32_bf16 v[124:127], v[156:159], v[188:191], v[124:127]
	v_mfma_f32_16x16x32_bf16 v[120:123], v[164:167], v[188:191], v[120:123]
	v_mfma_f32_16x16x32_bf16 v[116:119], v[156:159], v[196:199], v[116:119]
	v_mfma_f32_16x16x32_bf16 v[112:115], v[164:167], v[196:199], v[112:115]
	v_mfma_f32_16x16x32_bf16 v[92:95], v[156:159], v[204:207], v[92:95]
	v_mfma_f32_16x16x32_bf16 v[88:91], v[164:167], v[204:207], v[88:91]
	v_mfma_f32_16x16x32_bf16 v[84:87], v[156:159], v[212:215], v[84:87]
	v_mfma_f32_16x16x32_bf16 v[80:83], v[164:167], v[212:215], v[80:83]
	v_mfma_f32_16x16x32_bf16 v[108:111], v[168:171], v[184:187], v[108:111]
	v_mfma_f32_16x16x32_bf16 v[104:107], v[176:179], v[184:187], v[104:107]
	v_mfma_f32_16x16x32_bf16 v[100:103], v[168:171], v[192:195], v[100:103]
	v_mfma_f32_16x16x32_bf16 v[96:99], v[176:179], v[192:195], v[96:99]
	v_mfma_f32_16x16x32_bf16 v[76:79], v[168:171], v[200:203], v[76:79]
	v_mfma_f32_16x16x32_bf16 v[72:75], v[176:179], v[200:203], v[72:75]
	v_mfma_f32_16x16x32_bf16 v[68:71], v[168:171], v[208:211], v[68:71]
	v_mfma_f32_16x16x32_bf16 v[64:67], v[176:179], v[208:211], v[64:67]
	v_mfma_f32_16x16x32_bf16 v[108:111], v[172:175], v[188:191], v[108:111]
	v_mfma_f32_16x16x32_bf16 v[104:107], v[180:183], v[188:191], v[104:107]
	v_mfma_f32_16x16x32_bf16 v[100:103], v[172:175], v[196:199], v[100:103]
	v_mfma_f32_16x16x32_bf16 v[96:99], v[180:183], v[196:199], v[96:99]
	v_mfma_f32_16x16x32_bf16 v[76:79], v[172:175], v[204:207], v[76:79]
	v_mfma_f32_16x16x32_bf16 v[72:75], v[180:183], v[204:207], v[72:75]
	v_mfma_f32_16x16x32_bf16 v[68:71], v[172:175], v[212:215], v[68:71]
	v_mfma_f32_16x16x32_bf16 v[64:67], v[180:183], v[212:215], v[64:67]
	s_barrier
	s_add_i32 s16, s40, s29
	v_lshl_add_u64 v[148:149], s[20:21], 0, v[130:131]
	s_mov_b32 m0, s16
	ds_read_b128 v[184:187], v155 offset:16384
	ds_read_b128 v[188:191], v155 offset:17408
	ds_read_b128 v[192:195], v155 offset:18432
	ds_read_b128 v[196:199], v155 offset:19456
	ds_read_b128 v[200:203], v155 offset:20480
	ds_read_b128 v[204:207], v155 offset:21504
	ds_read_b128 v[208:211], v155 offset:22528
	ds_read_b128 v[212:215], v155 offset:23552
	global_load_lds_dwordx4 v[148:149], off
	s_add_i32 m0, s16, 0x2000
	s_add_u32 s16, s20, 0x160000
	v_lshl_add_u64 v[216:217], s[20:21], 0, v[134:135]
	s_addc_u32 s17, s21, 0
	s_add_i32 s49, s41, s29
	global_load_lds_dwordx4 v[216:217], off
	v_lshl_add_u64 v[218:219], s[16:17], 0, v[130:131]
	s_mov_b32 m0, s49
	v_lshl_add_u64 v[220:221], s[22:23], 0, v[132:133]
	global_load_lds_dwordx4 v[218:219], off
	v_lshl_add_u64 v[218:219], s[16:17], 0, v[134:135]
	s_add_i32 m0, s49, 0x2000
	s_nop 0
	global_load_lds_dwordx4 v[218:219], off
	v_lshl_add_u64 v[218:219], s[22:23], 0, v[128:129]
	s_mov_b32 m0, s30
	s_nop 0
	global_load_lds_dwordx4 v[218:219], off
	s_mov_b32 m0, s31
	s_nop 0
	global_load_lds_dwordx4 v[220:221], off
	s_waitcnt vmcnt(8)
	s_waitcnt lgkmcnt(0)
	s_barrier
; #define PG8_STAGE(bufoff, gbase, voff) do { _Pragma("unroll") for (int _i = 0; _i < 2; ++_i) \
;         __builtin_amdgcn_global_load_lds((const unsigned*)((const char*)(gbase) + (voff)[_i]), (PG8_LAS unsigned*)(lds + (bufoff) + ldsw + _i * 8192), 16, 0, 0); } while (0)
; #define PG8_LDA(dst, b, h) do { _Pragma("unroll") for (int m = 0; m < 4; ++m) _Pragma("unroll") for (int k = 0; k < 2; ++k) dst[m][k] = *(const PG8_LAS bf16x8*)(lds + PG8_SA(b, h) + aoff + m * 2048 + k * 1024); } while (0)
; #define PG8_LDB(dst, b, h) do { _Pragma("unroll") for (int n = 0; n < 2; ++n) _Pragma("unroll") for (int k = 0; k < 2; ++k) dst[n][k] = *(const PG8_LAS bf16x8*)(lds + PG8_SB(b, h) + boff + n * 2048 + k * 1024); } while (0)
; #define PG8_MMA(ai, bj, At, Bt) do { __builtin_amdgcn_s_setprio(1); _Pragma("unroll") for (int m = 0; m < 4; ++m) _Pragma("unroll") for (int n = 0; n < 2; ++n) _Pragma("unroll") for (int k = 0; k < 2; ++k) \
;         acc[ai][bj][m][n] = __builtin_amdgcn_mfma_f32_16x16x32_bf16(Bt[n][k], At[m][k], acc[ai][bj][m][n], 0, 0, 0); __builtin_amdgcn_s_setprio(0); } while (0)
; #define PG8_WAIT_V(n) asm volatile("s_waitcnt vmcnt(" #n ")" ::: "memory")
; #define PG8_WAIT_L(n) asm volatile("s_waitcnt lgkmcnt(" #n ")" ::: "memory")
; #define PG8_BAR __builtin_amdgcn_s_barrier()
; #define PG8_SCHED __builtin_amdgcn_sched_barrier(0)
; template <class Epi, class Sched, bool ALIGN_EPI = false, bool SP2 = false>
; __device__ __forceinline__ void gemm_phase(PG8_LAS unsigned char* lds, const Gemm g, const Sched& S, const Epi& E, const int wv0) {
;     ...
;             PG8_WAIT_V(8); PG8_WAIT_L(0); PG8_BAR; PG8_MMA(1, 0, At, B0); PG8_MMA(1, 1, At, B1); PG8_BAR; PG8_SCHED;
;             PG8_LDB(B0, 1, 0); PG8_LDB(B1, 1, 1); PG8_SCHED; PG8_LDA(At, 1, 0); PG8_STAGE(PG8_SA(0, 1), a2 + hstepA, voffA);
;             PG8_WAIT_V(8); PG8_WAIT_L(0); PG8_BAR; PG8_MMA(0, 0, At, B0); PG8_MMA(0, 1, At, B1); PG8_BAR; PG8_SCHED;
	v_mfma_f32_16x16x32_bf16 v[60:63], v[144:147], v[184:187], v[60:63]
	v_mfma_f32_16x16x32_bf16 v[56:59], v[160:163], v[184:187], v[56:59]
	v_mfma_f32_16x16x32_bf16 v[52:55], v[144:147], v[192:195], v[52:55]
	v_mfma_f32_16x16x32_bf16 v[48:51], v[160:163], v[192:195], v[48:51]
	v_mfma_f32_16x16x32_bf16 v[28:31], v[144:147], v[200:203], v[28:31]
	v_mfma_f32_16x16x32_bf16 v[24:27], v[160:163], v[200:203], v[24:27]
	v_mfma_f32_16x16x32_bf16 v[20:23], v[144:147], v[208:211], v[20:23]
	v_mfma_f32_16x16x32_bf16 v[16:19], v[160:163], v[208:211], v[16:19]
	v_mfma_f32_16x16x32_bf16 v[60:63], v[156:159], v[188:191], v[60:63]
	v_mfma_f32_16x16x32_bf16 v[56:59], v[164:167], v[188:191], v[56:59]
	v_mfma_f32_16x16x32_bf16 v[52:55], v[156:159], v[196:199], v[52:55]
	v_mfma_f32_16x16x32_bf16 v[48:51], v[164:167], v[196:199], v[48:51]
	v_mfma_f32_16x16x32_bf16 v[28:31], v[156:159], v[204:207], v[28:31]
	v_mfma_f32_16x16x32_bf16 v[24:27], v[164:167], v[204:207], v[24:27]
	v_mfma_f32_16x16x32_bf16 v[20:23], v[156:159], v[212:215], v[20:23]
	v_mfma_f32_16x16x32_bf16 v[16:19], v[164:167], v[212:215], v[16:19]
	v_mfma_f32_16x16x32_bf16 v[44:47], v[168:171], v[184:187], v[44:47]
	v_mfma_f32_16x16x32_bf16 v[40:43], v[176:179], v[184:187], v[40:43]
	v_mfma_f32_16x16x32_bf16 v[36:39], v[168:171], v[192:195], v[36:39]
	v_mfma_f32_16x16x32_bf16 v[32:35], v[176:179], v[192:195], v[32:35]
	v_mfma_f32_16x16x32_bf16 v[12:15], v[168:171], v[200:203], v[12:15]
	v_mfma_f32_16x16x32_bf16 v[8:11], v[176:179], v[200:203], v[8:11]
	v_mfma_f32_16x16x32_bf16 v[4:7], v[168:171], v[208:211], v[4:7]
	v_mfma_f32_16x16x32_bf16 v[0:3], v[176:179], v[208:211], v[0:3]
	v_mfma_f32_16x16x32_bf16 v[44:47], v[172:175], v[188:191], v[44:47]
	v_mfma_f32_16x16x32_bf16 v[40:43], v[180:183], v[188:191], v[40:43]
	v_mfma_f32_16x16x32_bf16 v[36:39], v[172:175], v[196:199], v[36:39]
	v_mfma_f32_16x16x32_bf16 v[32:35], v[180:183], v[196:199], v[32:35]
	v_mfma_f32_16x16x32_bf16 v[12:15], v[172:175], v[204:207], v[12:15]
	v_mfma_f32_16x16x32_bf16 v[8:11], v[180:183], v[204:207], v[8:11]
	v_mfma_f32_16x16x32_bf16 v[4:7], v[172:175], v[212:215], v[4:7]
	v_mfma_f32_16x16x32_bf16 v[0:3], v[180:183], v[212:215], v[0:3]
	s_barrier
	s_add_i32 s49, 0, 0x18000
	s_add_i32 s50, 0, 0x1c000
	v_add_u32_e32 v164, s49, v151
	v_add_u32_e32 v180, s50, v151
	ds_read_b128 v[144:147], v164
	ds_read_b128 v[156:159], v164 offset:1024
	ds_read_b128 v[160:163], v164 offset:2048
	ds_read_b128 v[164:167], v164 offset:3072
	ds_read_b128 v[168:171], v180
	ds_read_b128 v[172:175], v180 offset:1024
	ds_read_b128 v[176:179], v180 offset:2048
	ds_read_b128 v[180:183], v180 offset:3072
	s_add_u32 s16, s22, 0x160000
	s_addc_u32 s17, s23, 0
	s_mov_b32 m0, s34
	v_lshl_add_u64 v[222:223], s[16:17], 0, v[128:129]
	ds_read_b128 v[184:187], v155 offset:32768
	ds_read_b128 v[188:191], v155 offset:33792
	ds_read_b128 v[192:195], v155 offset:34816
	ds_read_b128 v[196:199], v155 offset:35840
	ds_read_b128 v[200:203], v155 offset:36864
	ds_read_b128 v[204:207], v155 offset:37888
	ds_read_b128 v[208:211], v155 offset:38912
	ds_read_b128 v[212:215], v155 offset:39936
	global_load_lds_dwordx4 v[222:223], off
	v_lshl_add_u64 v[222:223], s[16:17], 0, v[132:133]
	s_mov_b32 m0, s35
	s_nop 0
	global_load_lds_dwordx4 v[222:223], off
	s_waitcnt vmcnt(8)
	s_waitcnt lgkmcnt(0)
	s_barrier
	v_mfma_f32_16x16x32_bf16 v[124:127], v[144:147], v[184:187], v[124:127]
	v_mfma_f32_16x16x32_bf16 v[120:123], v[160:163], v[184:187], v[120:123]
	v_mfma_f32_16x16x32_bf16 v[116:119], v[144:147], v[192:195], v[116:119]
	v_mfma_f32_16x16x32_bf16 v[112:115], v[160:163], v[192:195], v[112:115]
	v_mfma_f32_16x16x32_bf16 v[92:95], v[144:147], v[200:203], v[92:95]
	v_mfma_f32_16x16x32_bf16 v[88:91], v[160:163], v[200:203], v[88:91]
	v_mfma_f32_16x16x32_bf16 v[84:87], v[144:147], v[208:211], v[84:87]
	v_mfma_f32_16x16x32_bf16 v[80:83], v[160:163], v[208:211], v[80:83]
	v_mfma_f32_16x16x32_bf16 v[124:127], v[156:159], v[188:191], v[124:127]
	v_mfma_f32_16x16x32_bf16 v[120:123], v[164:167], v[188:191], v[120:123]
	v_mfma_f32_16x16x32_bf16 v[116:119], v[156:159], v[196:199], v[116:119]
	v_mfma_f32_16x16x32_bf16 v[112:115], v[164:167], v[196:199], v[112:115]
	v_mfma_f32_16x16x32_bf16 v[92:95], v[156:159], v[204:207], v[92:95]
	v_mfma_f32_16x16x32_bf16 v[88:91], v[164:167], v[204:207], v[88:91]
	v_mfma_f32_16x16x32_bf16 v[84:87], v[156:159], v[212:215], v[84:87]
	v_mfma_f32_16x16x32_bf16 v[80:83], v[164:167], v[212:215], v[80:83]
	v_mfma_f32_16x16x32_bf16 v[108:111], v[168:171], v[184:187], v[108:111]
	v_mfma_f32_16x16x32_bf16 v[104:107], v[176:179], v[184:187], v[104:107]
	v_mfma_f32_16x16x32_bf16 v[100:103], v[168:171], v[192:195], v[100:103]
	v_mfma_f32_16x16x32_bf16 v[96:99], v[176:179], v[192:195], v[96:99]
	v_mfma_f32_16x16x32_bf16 v[76:79], v[168:171], v[200:203], v[76:79]
	v_mfma_f32_16x16x32_bf16 v[72:75], v[176:179], v[200:203], v[72:75]
	v_mfma_f32_16x16x32_bf16 v[68:71], v[168:171], v[208:211], v[68:71]
	v_mfma_f32_16x16x32_bf16 v[64:67], v[176:179], v[208:211], v[64:67]
	v_mfma_f32_16x16x32_bf16 v[108:111], v[172:175], v[188:191], v[108:111]
	v_mfma_f32_16x16x32_bf16 v[104:107], v[180:183], v[188:191], v[104:107]
	v_mfma_f32_16x16x32_bf16 v[100:103], v[172:175], v[196:199], v[100:103]
	v_mfma_f32_16x16x32_bf16 v[96:99], v[180:183], v[196:199], v[96:99]
	v_mfma_f32_16x16x32_bf16 v[76:79], v[172:175], v[204:207], v[76:79]
	v_mfma_f32_16x16x32_bf16 v[72:75], v[180:183], v[204:207], v[72:75]
	v_mfma_f32_16x16x32_bf16 v[68:71], v[172:175], v[212:215], v[68:71]
	v_mfma_f32_16x16x32_bf16 v[64:67], v[180:183], v[212:215], v[64:67]
	s_barrier
; #define PG8_STAGE(bufoff, gbase, voff) do { _Pragma("unroll") for (int _i = 0; _i < 2; ++_i) \
;         __builtin_amdgcn_global_load_lds((const unsigned*)((const char*)(gbase) + (voff)[_i]), (PG8_LAS unsigned*)(lds + (bufoff) + ldsw + _i * 8192), 16, 0, 0); } while (0)
; #define PG8_LDA(dst, b, h) do { _Pragma("unroll") for (int m = 0; m < 4; ++m) _Pragma("unroll") for (int k = 0; k < 2; ++k) dst[m][k] = *(const PG8_LAS bf16x8*)(lds + PG8_SA(b, h) + aoff + m * 2048 + k * 1024); } while (0)
; #define PG8_MMA(ai, bj, At, Bt) do { __builtin_amdgcn_s_setprio(1); _Pragma("unroll") for (int m = 0; m < 4; ++m) _Pragma("unroll") for (int n = 0; n < 2; ++n) _Pragma("unroll") for (int k = 0; k < 2; ++k) \
;         acc[ai][bj][m][n] = __builtin_amdgcn_mfma_f32_16x16x32_bf16(Bt[n][k], At[m][k], acc[ai][bj][m][n], 0, 0, 0); __builtin_amdgcn_s_setprio(0); } while (0)
; #define PG8_WAIT_V(n) asm volatile("s_waitcnt vmcnt(" #n ")" ::: "memory")
; #define PG8_WAIT_L(n) asm volatile("s_waitcnt lgkmcnt(" #n ")" ::: "memory")
; #define PG8_BAR __builtin_amdgcn_s_barrier()
; #define PG8_SCHED __builtin_amdgcn_sched_barrier(0)
; template <class Epi, class Sched, bool ALIGN_EPI = false, bool SP2 = false>
; __device__ __forceinline__ void gemm_phase(PG8_LAS unsigned char* lds, const Gemm g, const Sched& S, const Epi& E, const int wv0) {
;     ...
;             PG8_LDA(At, 1, 1); PG8_STAGE(PG8_SB(1, 0), b3, voffB); PG8_STAGE(PG8_SB(1, 1), b3 + hstepB, voffB); PG8_STAGE(PG8_SA(1, 0), a3, voffA);
;             PG8_WAIT_V(8); PG8_WAIT_L(0); PG8_BAR; PG8_MMA(1, 0, At, B0); PG8_MMA(1, 1, At, B1); PG8_BAR; PG8_SCHED;
	s_add_i32 s16, s49, s29
	v_lshl_add_u64 v[148:149], v[148:149], 0, s[8:9]
	s_mov_b32 m0, s16
	ds_read_b128 v[184:187], v155 offset:49152
	ds_read_b128 v[188:191], v155 offset:50176
	ds_read_b128 v[192:195], v155 offset:51200
	ds_read_b128 v[196:199], v155 offset:52224
	ds_read_b128 v[200:203], v155 offset:53248
	ds_read_b128 v[204:207], v155 offset:54272
	ds_read_b128 v[208:211], v155 offset:55296
	ds_read_b128 v[212:215], v155 offset:56320
	global_load_lds_dwordx4 v[148:149], off
	s_add_i32 m0, s16, 0x2000
	s_add_u32 s16, s20, 0x160080
	v_lshl_add_u64 v[148:149], v[216:217], 0, s[8:9]
	s_addc_u32 s17, s21, 0
	s_add_i32 s20, s50, s29
	global_load_lds_dwordx4 v[148:149], off
	v_lshl_add_u64 v[148:149], s[16:17], 0, v[130:131]
	s_mov_b32 m0, s20
	s_nop 0
	global_load_lds_dwordx4 v[148:149], off
	v_lshl_add_u64 v[148:149], s[16:17], 0, v[134:135]
	s_add_i32 m0, s20, 0x2000
	s_nop 0
	global_load_lds_dwordx4 v[148:149], off
	v_lshl_add_u64 v[148:149], v[218:219], 0, s[8:9]
	s_mov_b32 m0, s37
	s_nop 0
	global_load_lds_dwordx4 v[148:149], off
	v_lshl_add_u64 v[148:149], v[220:221], 0, s[8:9]
	s_mov_b32 m0, s38
	s_nop 0
	global_load_lds_dwordx4 v[148:149], off
	s_waitcnt vmcnt(8)
	s_waitcnt lgkmcnt(0)
	s_barrier
	v_mfma_f32_16x16x32_bf16 v[60:63], v[144:147], v[184:187], v[60:63]
	v_mfma_f32_16x16x32_bf16 v[56:59], v[160:163], v[184:187], v[56:59]
	v_mfma_f32_16x16x32_bf16 v[52:55], v[144:147], v[192:195], v[52:55]
	v_mfma_f32_16x16x32_bf16 v[48:51], v[160:163], v[192:195], v[48:51]
	v_mfma_f32_16x16x32_bf16 v[28:31], v[144:147], v[200:203], v[28:31]
	v_mfma_f32_16x16x32_bf16 v[24:27], v[160:163], v[200:203], v[24:27]
	v_mfma_f32_16x16x32_bf16 v[20:23], v[144:147], v[208:211], v[20:23]
	v_mfma_f32_16x16x32_bf16 v[16:19], v[160:163], v[208:211], v[16:19]
	v_mfma_f32_16x16x32_bf16 v[60:63], v[156:159], v[188:191], v[60:63]
	v_mfma_f32_16x16x32_bf16 v[56:59], v[164:167], v[188:191], v[56:59]
	v_mfma_f32_16x16x32_bf16 v[52:55], v[156:159], v[196:199], v[52:55]
	v_mfma_f32_16x16x32_bf16 v[48:51], v[164:167], v[196:199], v[48:51]
	v_mfma_f32_16x16x32_bf16 v[28:31], v[156:159], v[204:207], v[28:31]
	v_mfma_f32_16x16x32_bf16 v[24:27], v[164:167], v[204:207], v[24:27]
	v_mfma_f32_16x16x32_bf16 v[20:23], v[156:159], v[212:215], v[20:23]
	v_mfma_f32_16x16x32_bf16 v[16:19], v[164:167], v[212:215], v[16:19]
	v_mfma_f32_16x16x32_bf16 v[44:47], v[168:171], v[184:187], v[44:47]
	v_mfma_f32_16x16x32_bf16 v[40:43], v[176:179], v[184:187], v[40:43]
	v_mfma_f32_16x16x32_bf16 v[36:39], v[168:171], v[192:195], v[36:39]
	v_mfma_f32_16x16x32_bf16 v[32:35], v[176:179], v[192:195], v[32:35]
	v_mfma_f32_16x16x32_bf16 v[12:15], v[168:171], v[200:203], v[12:15]
	v_mfma_f32_16x16x32_bf16 v[8:11], v[176:179], v[200:203], v[8:11]
	v_mfma_f32_16x16x32_bf16 v[4:7], v[168:171], v[208:211], v[4:7]
	v_mfma_f32_16x16x32_bf16 v[0:3], v[176:179], v[208:211], v[0:3]
	v_mfma_f32_16x16x32_bf16 v[44:47], v[172:175], v[188:191], v[44:47]
	v_mfma_f32_16x16x32_bf16 v[40:43], v[180:183], v[188:191], v[40:43]
	v_mfma_f32_16x16x32_bf16 v[36:39], v[172:175], v[196:199], v[36:39]
	v_mfma_f32_16x16x32_bf16 v[32:35], v[180:183], v[196:199], v[32:35]
	v_mfma_f32_16x16x32_bf16 v[12:15], v[172:175], v[204:207], v[12:15]
	v_mfma_f32_16x16x32_bf16 v[8:11], v[180:183], v[204:207], v[8:11]
	v_mfma_f32_16x16x32_bf16 v[4:7], v[172:175], v[212:215], v[4:7]
	v_mfma_f32_16x16x32_bf16 v[0:3], v[180:183], v[212:215], v[0:3]
	s_barrier
	s_add_i32 s48, s48, 2
	s_add_u32 s46, s46, 0x100
	s_addc_u32 s47, s47, 0
	s_cmpk_gt_u32 s48, 0x55
	s_mov_b64 s[16:17], s[18:19]
	s_cbranch_scc0 .LBB0_1808
	s_and_b64 vcc, exec, s[10:11]
	s_cbranch_vccz .LBB0_1811
	s_barrier
